# v34 + accumulator-stationary MFMA order: the two k-half MFMAs of each accumulator issued back to back (SrcC forwarding chain), accumulators in snake order; bit-identical
# speedup vs baseline: 1.0166x; 1.0084x over previous
; #define PG8_STAGE(bufoff, gbase, voff) do { _Pragma("unroll") for (int _i = 0; _i < 2; ++_i) \
;         __builtin_amdgcn_global_load_lds((const unsigned*)((const char*)(gbase) + (voff)[_i]), (PG8_LAS unsigned*)(lds + (bufoff) + ldsw + _i * 8192), 16, 0, 0); } while (0)
; #define PG8_LDA(dst, b, h) do { _Pragma("unroll") for (int m = 0; m < 4; ++m) _Pragma("unroll") for (int k = 0; k < 2; ++k) dst[m][k] = *(const PG8_LAS bf16x8*)(lds + PG8_SA(b, h) + aoff + m * 2048 + k * 1024); } while (0)
; #define PG8_LDB(dst, b, h) do { _Pragma("unroll") for (int n = 0; n < 2; ++n) _Pragma("unroll") for (int k = 0; k < 2; ++k) dst[n][k] = *(const PG8_LAS bf16x8*)(lds + PG8_SB(b, h) + boff + n * 2048 + k * 1024); } while (0)
; #define PG8_WAIT_V(n) asm volatile("s_waitcnt vmcnt(" #n ")" ::: "memory")
; #define PG8_BAR __builtin_amdgcn_s_barrier()
; template <bool I8> __device__ __forceinline__ f32x4 mma16(bf16x8 b, bf16x8 a, f32x4 c) {
;     if constexpr (I8) { typedef int i32x4 __attribute__((ext_vector_type(4)));
;         return __builtin_bit_cast(f32x4, __builtin_amdgcn_mfma_i32_16x16x64_i8(__builtin_bit_cast(i32x4, b), __builtin_bit_cast(i32x4, a), __builtin_bit_cast(i32x4, c), 0, 0, 0)); }
;     else return __builtin_amdgcn_mfma_f32_16x16x32_bf16(b, a, c, 0, 0, 0);
; template <class Epi, class Sched, bool ALIGN_EPI = false, bool SP2 = false>
; __device__ __forceinline__ void gemm_phase(PG8_LAS unsigned char* lds, const Gemm g, const Sched& S, const Epi& E) {
;     ...
;             const bool last = (t == nt - 2);
;             const char* a1 = cA + (size_t)(t + 1) * kstep;
;             const char* a2 = last ? nA : cA + (size_t)(t + 2) * kstep; const char* b2 = last ? nB : cB + (size_t)(t + 2) * kstep;
;             const char* a3 = a2 + kstep; const char* b3 = b2 + kstep;
;             if (last && has_next) S.a_ready(nxt);
;             if constexpr (SP2) {
;             PG8_LDB(B0, 0, 0); PG8_LDB(B1, 0, 1); PG8_SCHED; PG8_LDA(At, 0, 0); PG8_STAGE(PG8_SA(1, 1), a1 + hstep, voffA);
;             PG8_WAIT_V(8); PG8_WAIT_L(0); PG8_BAR; PG8_MMA(0, 0, At, B0); PG8_MMA(0, 1, At, B1); PG8_BAR; PG8_SCHED;
;             PG8_LDA(At, 0, 1); PG8_STAGE(PG8_SB(0, 0), b2, voffB); PG8_STAGE(PG8_SB(0, 1), b2 + hstep, voffB); PG8_STAGE(PG8_SA(0, 0), a2, voffA);
;             PG8_WAIT_V(8); PG8_WAIT_L(0); PG8_BAR; PG8_MMA(1, 0, At, B0); PG8_MMA(1, 1, At, B1); PG8_BAR; PG8_SCHED;
.Lpeel80:
	s_add_u32 s8, s0, 0x100
	s_addc_u32 s9, s1, 0
	s_add_i32 vcc_hi, 0, 0x10000
	s_cmp_eq_u32 vcc_lo, 12
	s_cselect_b32 s13, s66, s9
	s_cselect_b32 s12, s67, s8
	s_cselect_b32 s7, s82, s97
	s_cselect_b32 s6, s83, s96
	s_add_i32 s4, 0, 0x14000
	v_add_u32_e32 v38, vcc_hi, v242
	v_add_u32_e32 v158, s4, v242
	ds_read_b128 v[18:21], v38
	ds_read_b128 v[22:25], v38 offset:1024
	ds_read_b128 v[34:37], v38 offset:2048
	ds_read_b128 v[38:41], v38 offset:3072
	ds_read_b128 v[130:133], v158
	ds_read_b128 v[134:137], v158 offset:1024
	ds_read_b128 v[154:157], v158 offset:2048
	ds_read_b128 v[158:161], v158 offset:3072
	s_add_i32 m0, s11, 0xc000
	ds_read_b128 v[162:165], v243
	ds_read_b128 v[166:169], v243 offset:1024
	ds_read_b128 v[170:173], v243 offset:2048
	ds_read_b128 v[174:177], v243 offset:3072
	ds_read_b128 v[178:181], v243 offset:4096
	ds_read_b128 v[182:185], v243 offset:5120
	ds_read_b128 v[186:189], v243 offset:6144
	ds_read_b128 v[190:193], v243 offset:7168
	global_load_lds_dwordx4 v216, s[0:1]
	s_add_i32 m0, s11, 0xe000
	s_nop 0
	global_load_lds_dwordx4 v218, s[0:1]
	s_waitcnt vmcnt(8)
	s_waitcnt lgkmcnt(0)
	s_barrier
	s_setprio 1
	s_waitcnt lgkmcnt(0)
	v_mfma_i32_16x16x64_i8 v[150:153], v[18:21], v[162:165], 0
	v_mfma_i32_16x16x64_i8 v[150:153], v[22:25], v[166:169], v[150:153]
	v_mfma_i32_16x16x64_i8 v[118:121], v[18:21], v[170:173], 0
	v_mfma_i32_16x16x64_i8 v[118:121], v[22:25], v[174:177], v[118:121]
	v_mfma_i32_16x16x64_i8 v[54:57], v[18:21], v[178:181], 0
	v_mfma_i32_16x16x64_i8 v[54:57], v[22:25], v[182:185], v[54:57]
	v_mfma_i32_16x16x64_i8 v[94:97], v[18:21], v[186:189], 0
	v_mfma_i32_16x16x64_i8 v[94:97], v[22:25], v[190:193], v[94:97]
	v_mfma_i32_16x16x64_i8 v[58:61], v[34:37], v[186:189], 0
	v_mfma_i32_16x16x64_i8 v[58:61], v[38:41], v[190:193], v[58:61]
	v_mfma_i32_16x16x64_i8 v[30:33], v[34:37], v[178:181], 0
	v_mfma_i32_16x16x64_i8 v[30:33], v[38:41], v[182:185], v[30:33]
	v_mfma_i32_16x16x64_i8 v[110:113], v[34:37], v[170:173], 0
	v_mfma_i32_16x16x64_i8 v[110:113], v[38:41], v[174:177], v[110:113]
	v_mfma_i32_16x16x64_i8 v[146:149], v[34:37], v[162:165], 0
	v_mfma_i32_16x16x64_i8 v[146:149], v[38:41], v[166:169], v[146:149]
	s_setprio 0
	s_setprio 1
	v_mfma_i32_16x16x64_i8 v[142:145], v[130:133], v[162:165], 0
	v_mfma_i32_16x16x64_i8 v[142:145], v[134:137], v[166:169], v[142:145]
	v_mfma_i32_16x16x64_i8 v[102:105], v[130:133], v[170:173], 0
	v_mfma_i32_16x16x64_i8 v[102:105], v[134:137], v[174:177], v[102:105]
	v_mfma_i32_16x16x64_i8 v[42:45], v[130:133], v[178:181], 0
	v_mfma_i32_16x16x64_i8 v[42:45], v[134:137], v[182:185], v[42:45]
	v_mfma_i32_16x16x64_i8 v[78:81], v[130:133], v[186:189], 0
	v_mfma_i32_16x16x64_i8 v[78:81], v[134:137], v[190:193], v[78:81]
	v_mfma_i32_16x16x64_i8 v[62:65], v[154:157], v[186:189], 0
	v_mfma_i32_16x16x64_i8 v[62:65], v[158:161], v[190:193], v[62:65]
	v_mfma_i32_16x16x64_i8 v[26:29], v[154:157], v[178:181], 0
	v_mfma_i32_16x16x64_i8 v[26:29], v[158:161], v[182:185], v[26:29]
	v_mfma_i32_16x16x64_i8 v[98:101], v[154:157], v[170:173], 0
	v_mfma_i32_16x16x64_i8 v[98:101], v[158:161], v[174:177], v[98:101]
	v_mfma_i32_16x16x64_i8 v[138:141], v[154:157], v[162:165], 0
	v_mfma_i32_16x16x64_i8 v[138:141], v[158:161], v[166:169], v[138:141]
	s_setprio 0
	s_barrier
	s_add_i32 s0, vcc_hi, s69
	v_lshl_add_u64 v[198:199], s[6:7], 0, v[0:1]
	s_mov_b32 m0, s0
	ds_read_b128 v[162:165], v243 offset:16384
	ds_read_b128 v[166:169], v243 offset:17408
	ds_read_b128 v[170:173], v243 offset:18432
	ds_read_b128 v[174:177], v243 offset:19456
	ds_read_b128 v[178:181], v243 offset:20480
	ds_read_b128 v[182:185], v243 offset:21504
	ds_read_b128 v[186:189], v243 offset:22528
	ds_read_b128 v[190:193], v243 offset:23552
	global_load_lds_dwordx4 v[198:199], off
	s_add_i32 m0, s0, 0x2000
	s_add_u32 s0, s6, 0x40000
	v_lshl_add_u64 v[200:201], s[6:7], 0, v[214:215]
	s_addc_u32 s1, s7, 0
	s_add_i32 s4, s4, s69
	global_load_lds_dwordx4 v[200:201], off
	s_mov_b32 m0, s4
	v_lshl_add_u64 v[206:207], s[12:13], 0, v[210:211]
	global_load_lds_dwordx4 v0, s[0:1]
	s_add_i32 m0, s4, 0x2000
	v_lshl_add_u64 v[220:221], s[12:13], 0, v[212:213]
	global_load_lds_dwordx4 v214, s[0:1]
	s_mov_b32 m0, s11
	s_nop 0
	global_load_lds_dwordx4 v[206:207], off
	s_mov_b32 m0, s71
	s_nop 0
	global_load_lds_dwordx4 v[220:221], off
	s_waitcnt vmcnt(8)
	s_waitcnt lgkmcnt(0)
	s_barrier
	s_setprio 1
	s_waitcnt lgkmcnt(0)
	v_mfma_i32_16x16x64_i8 v[106:109], v[18:21], v[162:165], 0
	v_mfma_i32_16x16x64_i8 v[46:49], v[34:37], v[162:165], 0
	v_mfma_i32_16x16x64_i8 v[14:17], v[18:21], v[170:173], 0
	v_mfma_i32_16x16x64_i8 v[6:9], v[34:37], v[170:173], 0
	v_mfma_i32_16x16x64_i8 v[90:93], v[18:21], v[178:181], 0
	v_mfma_i32_16x16x64_i8 v[86:89], v[34:37], v[178:181], 0
	v_mfma_i32_16x16x64_i8 v[18:21], v[18:21], v[186:189], 0
	v_mfma_i32_16x16x64_i8 v[106:109], v[22:25], v[166:169], v[106:109]
	v_mfma_i32_16x16x64_i8 v[46:49], v[38:41], v[166:169], v[46:49]
	v_mfma_i32_16x16x64_i8 v[14:17], v[22:25], v[174:177], v[14:17]
	v_mfma_i32_16x16x64_i8 v[6:9], v[38:41], v[174:177], v[6:9]
	v_mfma_i32_16x16x64_i8 v[90:93], v[22:25], v[182:185], v[90:93]
	v_mfma_i32_16x16x64_i8 v[86:89], v[38:41], v[182:185], v[86:89]
	v_mfma_i32_16x16x64_i8 v[18:21], v[22:25], v[190:193], v[18:21]
	v_mfma_i32_16x16x64_i8 v[22:25], v[34:37], v[186:189], 0
	v_mfma_i32_16x16x64_i8 v[22:25], v[38:41], v[190:193], v[22:25]
	s_setprio 0
	s_setprio 1
	v_mfma_i32_16x16x64_i8 v[38:41], v[154:157], v[162:165], 0
	v_mfma_i32_16x16x64_i8 v[50:53], v[130:133], v[178:181], 0
	v_mfma_i32_16x16x64_i8 v[82:85], v[134:137], v[182:185], v[50:53]
	v_mfma_i32_16x16x64_i8 v[50:53], v[154:157], v[178:181], 0
	v_mfma_i32_16x16x64_i8 v[74:77], v[158:161], v[182:185], v[50:53]
	v_mfma_i32_16x16x64_i8 v[50:53], v[130:133], v[186:189], 0
	v_mfma_i32_16x16x64_i8 v[10:13], v[130:133], v[170:173], 0
	v_mfma_i32_16x16x64_i8 v[2:5], v[154:157], v[170:173], 0
	v_mfma_i32_16x16x64_i8 v[122:125], v[134:137], v[190:193], v[50:53]
	v_mfma_i32_16x16x64_i8 v[50:53], v[154:157], v[186:189], 0
	v_mfma_i32_16x16x64_i8 v[34:37], v[130:133], v[162:165], 0
	v_mfma_i32_16x16x64_i8 v[10:13], v[134:137], v[174:177], v[10:13]
	v_mfma_i32_16x16x64_i8 v[2:5], v[158:161], v[174:177], v[2:5]
	v_mfma_i32_16x16x64_i8 v[70:73], v[158:161], v[190:193], v[50:53]
	v_mfma_i32_16x16x64_i8 v[34:37], v[134:137], v[166:169], v[34:37]
	v_mfma_i32_16x16x64_i8 v[38:41], v[158:161], v[166:169], v[38:41]
	s_setprio 0
	s_barrier
; #define PG8_STAGE(bufoff, gbase, voff) do { _Pragma("unroll") for (int _i = 0; _i < 2; ++_i) \
;         __builtin_amdgcn_global_load_lds((const unsigned*)((const char*)(gbase) + (voff)[_i]), (PG8_LAS unsigned*)(lds + (bufoff) + ldsw + _i * 8192), 16, 0, 0); } while (0)
; #define PG8_LDA(dst, b, h) do { _Pragma("unroll") for (int m = 0; m < 4; ++m) _Pragma("unroll") for (int k = 0; k < 2; ++k) dst[m][k] = *(const PG8_LAS bf16x8*)(lds + PG8_SA(b, h) + aoff + m * 2048 + k * 1024); } while (0)
; #define PG8_LDB(dst, b, h) do { _Pragma("unroll") for (int n = 0; n < 2; ++n) _Pragma("unroll") for (int k = 0; k < 2; ++k) dst[n][k] = *(const PG8_LAS bf16x8*)(lds + PG8_SB(b, h) + boff + n * 2048 + k * 1024); } while (0)
; #define PG8_MMA(ai, bj, At, Bt) do { __builtin_amdgcn_s_setprio(1); _Pragma("unroll") for (int m = 0; m < 4; ++m) _Pragma("unroll") for (int n = 0; n < 2; ++n) _Pragma("unroll") for (int k = 0; k < 2; ++k) \
;         acc[ai][bj][m][n] = mma16<Epi::I8>(Bt[n][k], At[m][k], acc[ai][bj][m][n]); __builtin_amdgcn_s_setprio(0); } while (0)
; #define PG8_WAIT_V(n) asm volatile("s_waitcnt vmcnt(" #n ")" ::: "memory")
; #define PG8_WAIT_L(n) asm volatile("s_waitcnt lgkmcnt(" #n ")" ::: "memory")
; #define PG8_BAR __builtin_amdgcn_s_barrier()
; #define PG8_SCHED __builtin_amdgcn_sched_barrier(0)
; template <class Epi, class Sched, bool ALIGN_EPI = false, bool SP2 = false>
; __device__ __forceinline__ void gemm_phase(PG8_LAS unsigned char* lds, const Gemm g, const Sched& S, const Epi& E) {
;     ...
;         for (int t = 0; t < nt; t += 2) {
;     ...
;             PG8_LDB(B0, 1, 0); PG8_LDB(B1, 1, 1); PG8_SCHED; PG8_LDA(At, 1, 0); PG8_STAGE(PG8_SA(0, 1), a2 + hstep, voffA);
;             PG8_WAIT_V(8); PG8_WAIT_L(0); PG8_BAR; PG8_MMA(0, 0, At, B0); PG8_MMA(0, 1, At, B1); PG8_BAR; PG8_SCHED;
;             PG8_LDA(At, 1, 1); PG8_STAGE(PG8_SB(1, 0), b3, voffB); PG8_STAGE(PG8_SB(1, 1), b3 + hstep, voffB); PG8_STAGE(PG8_SA(1, 0), a3, voffA);
;             PG8_WAIT_V(8); PG8_WAIT_L(0); PG8_BAR; PG8_MMA(1, 0, At, B0); PG8_MMA(1, 1, At, B1); PG8_BAR; PG8_SCHED;
	s_add_i32 s4, 0, 0x18000
	v_add_u32_e32 v126, s4, v242
	s_add_i32 s5, 0, 0x1c000
	ds_read_b128 v[50:53], v126
	ds_read_b128 v[66:69], v126 offset:1024
	ds_read_b128 v[114:117], v126 offset:2048
	ds_read_b128 v[130:133], v126 offset:3072
	v_add_u32_e32 v126, s5, v242
	ds_read_b128 v[134:137], v126
	ds_read_b128 v[154:157], v126 offset:1024
	ds_read_b128 v[158:161], v126 offset:2048
	ds_read_b128 v[162:165], v126 offset:3072
	s_add_u32 s0, s12, 0x40000
	s_addc_u32 s1, s13, 0
	s_mov_b32 m0, s80
	ds_read_b128 v[126:129], v243 offset:32768
	ds_read_b128 v[166:169], v243 offset:33792
	ds_read_b128 v[170:173], v243 offset:34816
	ds_read_b128 v[174:177], v243 offset:35840
	ds_read_b128 v[178:181], v243 offset:36864
	ds_read_b128 v[182:185], v243 offset:37888
	ds_read_b128 v[186:189], v243 offset:38912
	ds_read_b128 v[190:193], v243 offset:39936
	global_load_lds_dwordx4 v210, s[0:1]
	s_mov_b32 m0, s81
	s_nop 0
	global_load_lds_dwordx4 v212, s[0:1]
	s_waitcnt vmcnt(8)
	s_waitcnt lgkmcnt(0)
	s_barrier
	s_setprio 1
	s_waitcnt lgkmcnt(0)
	v_mfma_i32_16x16x64_i8 v[150:153], v[50:53], v[126:129], v[150:153]
	v_mfma_i32_16x16x64_i8 v[150:153], v[66:69], v[166:169], v[150:153]
	v_mfma_i32_16x16x64_i8 v[118:121], v[50:53], v[170:173], v[118:121]
	v_mfma_i32_16x16x64_i8 v[118:121], v[66:69], v[174:177], v[118:121]
	v_mfma_i32_16x16x64_i8 v[54:57], v[50:53], v[178:181], v[54:57]
	v_mfma_i32_16x16x64_i8 v[54:57], v[66:69], v[182:185], v[54:57]
	v_mfma_i32_16x16x64_i8 v[94:97], v[50:53], v[186:189], v[94:97]
	v_mfma_i32_16x16x64_i8 v[94:97], v[66:69], v[190:193], v[94:97]
	v_mfma_i32_16x16x64_i8 v[58:61], v[114:117], v[186:189], v[58:61]
	v_mfma_i32_16x16x64_i8 v[58:61], v[130:133], v[190:193], v[58:61]
	v_mfma_i32_16x16x64_i8 v[30:33], v[114:117], v[178:181], v[30:33]
	v_mfma_i32_16x16x64_i8 v[30:33], v[130:133], v[182:185], v[30:33]
	v_mfma_i32_16x16x64_i8 v[110:113], v[114:117], v[170:173], v[110:113]
	v_mfma_i32_16x16x64_i8 v[110:113], v[130:133], v[174:177], v[110:113]
	v_mfma_i32_16x16x64_i8 v[146:149], v[114:117], v[126:129], v[146:149]
	v_mfma_i32_16x16x64_i8 v[146:149], v[130:133], v[166:169], v[146:149]
	s_setprio 0
	s_setprio 1
	v_mfma_i32_16x16x64_i8 v[142:145], v[134:137], v[126:129], v[142:145]
	v_mfma_i32_16x16x64_i8 v[126:129], v[158:161], v[126:129], v[138:141]
	v_mfma_i32_16x16x64_i8 v[102:105], v[134:137], v[170:173], v[102:105]
	v_mfma_i32_16x16x64_i8 v[98:101], v[158:161], v[170:173], v[98:101]
	v_mfma_i32_16x16x64_i8 v[42:45], v[134:137], v[178:181], v[42:45]
	v_mfma_i32_16x16x64_i8 v[26:29], v[158:161], v[178:181], v[26:29]
	v_mfma_i32_16x16x64_i8 v[78:81], v[134:137], v[186:189], v[78:81]
	v_mfma_i32_16x16x64_i8 v[62:65], v[158:161], v[186:189], v[62:65]
	v_mfma_i32_16x16x64_i8 v[142:145], v[154:157], v[166:169], v[142:145]
	v_mfma_i32_16x16x64_i8 v[138:141], v[162:165], v[166:169], v[126:129]
	v_mfma_i32_16x16x64_i8 v[102:105], v[154:157], v[174:177], v[102:105]
	v_mfma_i32_16x16x64_i8 v[98:101], v[162:165], v[174:177], v[98:101]
	v_mfma_i32_16x16x64_i8 v[42:45], v[154:157], v[182:185], v[42:45]
	v_mfma_i32_16x16x64_i8 v[26:29], v[162:165], v[182:185], v[26:29]
	v_mfma_i32_16x16x64_i8 v[78:81], v[154:157], v[190:193], v[78:81]
	v_mfma_i32_16x16x64_i8 v[62:65], v[162:165], v[190:193], v[62:65]
	s_setprio 0
	s_barrier
	s_add_i32 s0, s4, s69
	v_lshl_add_u64 v[126:127], v[198:199], 0, s[92:93]
	s_mov_b32 m0, s0
	ds_read_b128 v[166:169], v243 offset:49152
	ds_read_b128 v[170:173], v243 offset:50176
	ds_read_b128 v[174:177], v243 offset:51200
	ds_read_b128 v[178:181], v243 offset:52224
	ds_read_b128 v[182:185], v243 offset:53248
	ds_read_b128 v[186:189], v243 offset:54272
	ds_read_b128 v[190:193], v243 offset:55296
	ds_read_b128 v[194:197], v243 offset:56320
	global_load_lds_dwordx4 v[126:127], off
	s_add_i32 m0, s0, 0x2000
	s_add_u32 s0, s6, 0x40080
	v_lshl_add_u64 v[126:127], v[200:201], 0, s[92:93]
	s_addc_u32 s1, s7, 0
	s_add_i32 s4, s5, s69
	global_load_lds_dwordx4 v[126:127], off
	s_mov_b32 m0, s4
	s_nop 0
	global_load_lds_dwordx4 v0, s[0:1]
	s_add_i32 m0, s4, 0x2000
	s_nop 0
	global_load_lds_dwordx4 v214, s[0:1]
	v_lshl_add_u64 v[126:127], v[206:207], 0, s[92:93]
	s_mov_b32 m0, s84
	s_nop 0
	global_load_lds_dwordx4 v[126:127], off
	v_lshl_add_u64 v[126:127], v[220:221], 0, s[92:93]
	s_mov_b32 m0, s85
	s_nop 0
	global_load_lds_dwordx4 v[126:127], off
	s_waitcnt vmcnt(8)
	s_waitcnt lgkmcnt(0)
	s_barrier
	s_setprio 1
	s_waitcnt lgkmcnt(0)
	v_mfma_i32_16x16x64_i8 v[18:21], v[50:53], v[190:193], v[18:21]
	v_mfma_i32_16x16x64_i8 v[106:109], v[50:53], v[166:169], v[106:109]
	v_mfma_i32_16x16x64_i8 v[46:49], v[114:117], v[166:169], v[46:49]
	v_mfma_i32_16x16x64_i8 v[14:17], v[50:53], v[174:177], v[14:17]
	v_mfma_i32_16x16x64_i8 v[6:9], v[114:117], v[174:177], v[6:9]
	v_mfma_i32_16x16x64_i8 v[90:93], v[50:53], v[182:185], v[90:93]
	v_mfma_i32_16x16x64_i8 v[86:89], v[114:117], v[182:185], v[86:89]
	v_mfma_i32_16x16x64_i8 v[126:129], v[66:69], v[194:197], v[18:21]
	v_mfma_i32_16x16x64_i8 v[18:21], v[114:117], v[190:193], v[22:25]
	v_mfma_i32_16x16x64_i8 v[106:109], v[66:69], v[170:173], v[106:109]
	v_mfma_i32_16x16x64_i8 v[46:49], v[130:133], v[170:173], v[46:49]
	v_mfma_i32_16x16x64_i8 v[14:17], v[66:69], v[178:181], v[14:17]
	v_mfma_i32_16x16x64_i8 v[6:9], v[130:133], v[178:181], v[6:9]
	v_mfma_i32_16x16x64_i8 v[90:93], v[66:69], v[186:189], v[90:93]
	v_mfma_i32_16x16x64_i8 v[86:89], v[130:133], v[186:189], v[86:89]
	v_mfma_i32_16x16x64_i8 v[66:69], v[130:133], v[194:197], v[18:21]
	s_setprio 0
	s_setprio 1
	v_mfma_i32_16x16x64_i8 v[18:21], v[134:137], v[166:169], v[34:37]
	v_mfma_i32_16x16x64_i8 v[114:117], v[154:157], v[170:173], v[18:21]
	v_mfma_i32_16x16x64_i8 v[18:21], v[158:161], v[166:169], v[38:41]
	v_mfma_i32_16x16x64_i8 v[50:53], v[162:165], v[170:173], v[18:21]
	v_mfma_i32_16x16x64_i8 v[18:21], v[134:137], v[182:185], v[82:85]
	v_mfma_i32_16x16x64_i8 v[82:85], v[154:157], v[186:189], v[18:21]
	v_mfma_i32_16x16x64_i8 v[18:21], v[158:161], v[182:185], v[74:77]
	v_mfma_i32_16x16x64_i8 v[74:77], v[162:165], v[186:189], v[18:21]
	v_mfma_i32_16x16x64_i8 v[18:21], v[134:137], v[190:193], v[122:125]
	v_mfma_i32_16x16x64_i8 v[10:13], v[134:137], v[174:177], v[10:13]
	v_mfma_i32_16x16x64_i8 v[2:5], v[158:161], v[174:177], v[2:5]
	v_mfma_i32_16x16x64_i8 v[122:125], v[154:157], v[194:197], v[18:21]
	v_mfma_i32_16x16x64_i8 v[18:21], v[158:161], v[190:193], v[70:73]
	v_mfma_i32_16x16x64_i8 v[10:13], v[154:157], v[178:181], v[10:13]
	v_mfma_i32_16x16x64_i8 v[2:5], v[162:165], v[178:181], v[2:5]
	v_mfma_i32_16x16x64_i8 v[70:73], v[162:165], v[194:197], v[18:21]
	s_setprio 0
	s_barrier
	s_add_i32 vcc_lo, vcc_lo, 2
	s_add_u32 s96, s96, 0x100
	s_addc_u32 s97, s97, 0
	s_cmp_gt_u32 vcc_lo, 13
	s_mov_b64 s[0:1], s[8:9]
	s_cbranch_scc0 .LBB0_80
	s_branch .Lpeelx80
; #define PG8_STAGE(bufoff, gbase, voff) do { _Pragma("unroll") for (int _i = 0; _i < 2; ++_i) \
;         __builtin_amdgcn_global_load_lds((const unsigned*)((const char*)(gbase) + (voff)[_i]), (PG8_LAS unsigned*)(lds + (bufoff) + ldsw + _i * 8192), 16, 0, 0); } while (0)
; #define PG8_LDA(dst, b, h) do { _Pragma("unroll") for (int m = 0; m < 4; ++m) _Pragma("unroll") for (int k = 0; k < 2; ++k) dst[m][k] = *(const PG8_LAS bf16x8*)(lds + PG8_SA(b, h) + aoff + m * 2048 + k * 1024); } while (0)
; #define PG8_LDB(dst, b, h) do { _Pragma("unroll") for (int n = 0; n < 2; ++n) _Pragma("unroll") for (int k = 0; k < 2; ++k) dst[n][k] = *(const PG8_LAS bf16x8*)(lds + PG8_SB(b, h) + boff + n * 2048 + k * 1024); } while (0)
; template <class Epi, class Sched, bool ALIGN_EPI = false, bool SP2 = false>
; __device__ __forceinline__ void gemm_phase(PG8_LAS unsigned char* lds, const Gemm g, const Sched& S, const Epi& E) {
;     ...
;         for (int t = 0; t < nt; t += 2) {
;             const bool last = (t == nt - 2);
;             const char* a1 = cA + (size_t)(t + 1) * kstep;
;             const char* a2 = last ? nA : cA + (size_t)(t + 2) * kstep; const char* b2 = last ? nB : cB + (size_t)(t + 2) * kstep;
;             const char* a3 = a2 + kstep; const char* b3 = b2 + kstep;
;             if (last && has_next) S.a_ready(nxt);
;             if constexpr (SP2) {
;             PG8_LDB(B0, 0, 0); PG8_LDB(B1, 0, 1); PG8_SCHED; PG8_LDA(At, 0, 0); PG8_STAGE(PG8_SA(1, 1), a1 + hstep, voffA);
;             PG8_WAIT_V(8); PG8_WAIT_L(0); PG8_BAR; PG8_MMA(0, 0, At, B0); PG8_MMA(0, 1, At, B1); PG8_BAR; PG8_SCHED;
;             PG8_LDA(At, 0, 1); PG8_STAGE(PG8_SB(0, 0), b2, voffB); PG8_STAGE(PG8_SB(0, 1), b2 + hstep, voffB); PG8_STAGE(PG8_SA(0, 0), a2, voffA);
;             PG8_WAIT_V(8); PG8_WAIT_L(0); PG8_BAR; PG8_MMA(1, 0, At, B0); PG8_MMA(1, 1, At, B1); PG8_BAR; PG8_SCHED;
;             PG8_LDB(B0, 1, 0); PG8_LDB(B1, 1, 1); PG8_SCHED; PG8_LDA(At, 1, 0); PG8_STAGE(PG8_SA(0, 1), a2 + hstep, voffA);
;             PG8_WAIT_V(8); PG8_WAIT_L(0); PG8_BAR; PG8_MMA(0, 0, At, B0); PG8_MMA(0, 1, At, B1); PG8_BAR; PG8_SCHED;
;             PG8_LDA(At, 1, 1); PG8_STAGE(PG8_SB(1, 0), b3, voffB); PG8_STAGE(PG8_SB(1, 1), b3 + hstep, voffB); PG8_STAGE(PG8_SA(1, 0), a3, voffA);
;             PG8_WAIT_V(8); PG8_WAIT_L(0); PG8_BAR; PG8_MMA(1, 0, At, B0); PG8_MMA(1, 1, At, B1); PG8_BAR; PG8_SCHED;
.LBB0_80:
	s_add_u32 s8, s0, 0x100
	s_addc_u32 s9, s1, 0
	s_add_i32 vcc_hi, 0, 0x10000
	s_cmp_eq_u32 vcc_lo, 12
	s_cselect_b32 s13, s66, s9
	s_cselect_b32 s12, s67, s8
	s_cselect_b32 s7, s82, s97
	s_cselect_b32 s6, s83, s96
	s_add_i32 s4, 0, 0x14000
	v_add_u32_e32 v38, vcc_hi, v242
	v_add_u32_e32 v158, s4, v242
	ds_read_b128 v[18:21], v38
	ds_read_b128 v[22:25], v38 offset:1024
	ds_read_b128 v[34:37], v38 offset:2048
	ds_read_b128 v[38:41], v38 offset:3072
	ds_read_b128 v[130:133], v158
	ds_read_b128 v[134:137], v158 offset:1024
	ds_read_b128 v[154:157], v158 offset:2048
	ds_read_b128 v[158:161], v158 offset:3072
	s_add_i32 m0, s11, 0xc000
	ds_read_b128 v[162:165], v243
	ds_read_b128 v[166:169], v243 offset:1024
	ds_read_b128 v[170:173], v243 offset:2048
	ds_read_b128 v[174:177], v243 offset:3072
	ds_read_b128 v[178:181], v243 offset:4096
	ds_read_b128 v[182:185], v243 offset:5120
	ds_read_b128 v[186:189], v243 offset:6144
	ds_read_b128 v[190:193], v243 offset:7168
	global_load_lds_dwordx4 v216, s[0:1]
	s_add_i32 m0, s11, 0xe000
	s_nop 0
	global_load_lds_dwordx4 v218, s[0:1]
	s_waitcnt vmcnt(8)
	s_waitcnt lgkmcnt(0)
	s_barrier
	s_setprio 1
	s_waitcnt lgkmcnt(0)
	v_mfma_i32_16x16x64_i8 v[150:153], v[18:21], v[162:165], v[150:153]
	v_mfma_i32_16x16x64_i8 v[150:153], v[22:25], v[166:169], v[150:153]
	v_mfma_i32_16x16x64_i8 v[118:121], v[18:21], v[170:173], v[118:121]
	v_mfma_i32_16x16x64_i8 v[118:121], v[22:25], v[174:177], v[118:121]
	v_mfma_i32_16x16x64_i8 v[54:57], v[18:21], v[178:181], v[54:57]
	v_mfma_i32_16x16x64_i8 v[54:57], v[22:25], v[182:185], v[54:57]
	v_mfma_i32_16x16x64_i8 v[94:97], v[18:21], v[186:189], v[94:97]
	v_mfma_i32_16x16x64_i8 v[94:97], v[22:25], v[190:193], v[94:97]
	v_mfma_i32_16x16x64_i8 v[58:61], v[34:37], v[186:189], v[58:61]
	v_mfma_i32_16x16x64_i8 v[58:61], v[38:41], v[190:193], v[58:61]
	v_mfma_i32_16x16x64_i8 v[30:33], v[34:37], v[178:181], v[30:33]
	v_mfma_i32_16x16x64_i8 v[30:33], v[38:41], v[182:185], v[30:33]
	v_mfma_i32_16x16x64_i8 v[110:113], v[34:37], v[170:173], v[110:113]
	v_mfma_i32_16x16x64_i8 v[110:113], v[38:41], v[174:177], v[110:113]
	v_mfma_i32_16x16x64_i8 v[146:149], v[34:37], v[162:165], v[146:149]
	v_mfma_i32_16x16x64_i8 v[146:149], v[38:41], v[166:169], v[146:149]
	s_setprio 0
	s_setprio 1
	v_mfma_i32_16x16x64_i8 v[142:145], v[130:133], v[162:165], v[142:145]
	v_mfma_i32_16x16x64_i8 v[142:145], v[134:137], v[166:169], v[142:145]
	v_mfma_i32_16x16x64_i8 v[102:105], v[130:133], v[170:173], v[102:105]
	v_mfma_i32_16x16x64_i8 v[102:105], v[134:137], v[174:177], v[102:105]
	v_mfma_i32_16x16x64_i8 v[42:45], v[130:133], v[178:181], v[42:45]
	v_mfma_i32_16x16x64_i8 v[42:45], v[134:137], v[182:185], v[42:45]
	v_mfma_i32_16x16x64_i8 v[78:81], v[130:133], v[186:189], v[78:81]
	v_mfma_i32_16x16x64_i8 v[78:81], v[134:137], v[190:193], v[78:81]
	v_mfma_i32_16x16x64_i8 v[62:65], v[154:157], v[186:189], v[62:65]
	v_mfma_i32_16x16x64_i8 v[62:65], v[158:161], v[190:193], v[62:65]
	v_mfma_i32_16x16x64_i8 v[26:29], v[154:157], v[178:181], v[26:29]
	v_mfma_i32_16x16x64_i8 v[26:29], v[158:161], v[182:185], v[26:29]
	v_mfma_i32_16x16x64_i8 v[98:101], v[154:157], v[170:173], v[98:101]
	v_mfma_i32_16x16x64_i8 v[98:101], v[158:161], v[174:177], v[98:101]
	v_mfma_i32_16x16x64_i8 v[138:141], v[154:157], v[162:165], v[138:141]
	v_mfma_i32_16x16x64_i8 v[138:141], v[158:161], v[166:169], v[138:141]
	s_setprio 0
	s_barrier
	s_add_i32 s0, vcc_hi, s69
	v_lshl_add_u64 v[198:199], s[6:7], 0, v[0:1]
	s_mov_b32 m0, s0
	ds_read_b128 v[162:165], v243 offset:16384
	ds_read_b128 v[166:169], v243 offset:17408
	ds_read_b128 v[170:173], v243 offset:18432
	ds_read_b128 v[174:177], v243 offset:19456
	ds_read_b128 v[178:181], v243 offset:20480
	ds_read_b128 v[182:185], v243 offset:21504
	ds_read_b128 v[186:189], v243 offset:22528
	ds_read_b128 v[190:193], v243 offset:23552
	global_load_lds_dwordx4 v[198:199], off
	s_add_i32 m0, s0, 0x2000
	s_add_u32 s0, s6, 0x40000
	v_lshl_add_u64 v[200:201], s[6:7], 0, v[214:215]
	s_addc_u32 s1, s7, 0
	s_add_i32 s4, s4, s69
	global_load_lds_dwordx4 v[200:201], off
	s_mov_b32 m0, s4
	v_lshl_add_u64 v[206:207], s[12:13], 0, v[210:211]
	global_load_lds_dwordx4 v0, s[0:1]
	s_add_i32 m0, s4, 0x2000
	v_lshl_add_u64 v[220:221], s[12:13], 0, v[212:213]
	global_load_lds_dwordx4 v214, s[0:1]
	s_mov_b32 m0, s11
	s_nop 0
	global_load_lds_dwordx4 v[206:207], off
	s_mov_b32 m0, s71
	s_nop 0
	global_load_lds_dwordx4 v[220:221], off
	s_waitcnt vmcnt(8)
	s_waitcnt lgkmcnt(0)
	s_barrier
	s_setprio 1
	s_waitcnt lgkmcnt(0)
	v_mfma_i32_16x16x64_i8 v[106:109], v[18:21], v[162:165], v[106:109]
	v_mfma_i32_16x16x64_i8 v[46:49], v[34:37], v[162:165], v[46:49]
	v_mfma_i32_16x16x64_i8 v[14:17], v[18:21], v[170:173], v[14:17]
	v_mfma_i32_16x16x64_i8 v[6:9], v[34:37], v[170:173], v[6:9]
	v_mfma_i32_16x16x64_i8 v[90:93], v[18:21], v[178:181], v[90:93]
	v_mfma_i32_16x16x64_i8 v[86:89], v[34:37], v[178:181], v[86:89]
	v_mfma_i32_16x16x64_i8 v[18:21], v[18:21], v[186:189], v[126:129]
	v_mfma_i32_16x16x64_i8 v[106:109], v[22:25], v[166:169], v[106:109]
	v_mfma_i32_16x16x64_i8 v[46:49], v[38:41], v[166:169], v[46:49]
	v_mfma_i32_16x16x64_i8 v[14:17], v[22:25], v[174:177], v[14:17]
	v_mfma_i32_16x16x64_i8 v[6:9], v[38:41], v[174:177], v[6:9]
	v_mfma_i32_16x16x64_i8 v[90:93], v[22:25], v[182:185], v[90:93]
	v_mfma_i32_16x16x64_i8 v[86:89], v[38:41], v[182:185], v[86:89]
	v_mfma_i32_16x16x64_i8 v[18:21], v[22:25], v[190:193], v[18:21]
	v_mfma_i32_16x16x64_i8 v[22:25], v[34:37], v[186:189], v[66:69]
	v_mfma_i32_16x16x64_i8 v[22:25], v[38:41], v[190:193], v[22:25]
	s_setprio 0
	s_setprio 1
	v_mfma_i32_16x16x64_i8 v[38:41], v[154:157], v[162:165], v[50:53]
	v_mfma_i32_16x16x64_i8 v[50:53], v[130:133], v[178:181], v[82:85]
	v_mfma_i32_16x16x64_i8 v[82:85], v[134:137], v[182:185], v[50:53]
	v_mfma_i32_16x16x64_i8 v[50:53], v[154:157], v[178:181], v[74:77]
	v_mfma_i32_16x16x64_i8 v[74:77], v[158:161], v[182:185], v[50:53]
	v_mfma_i32_16x16x64_i8 v[50:53], v[130:133], v[186:189], v[122:125]
	v_mfma_i32_16x16x64_i8 v[10:13], v[130:133], v[170:173], v[10:13]
	v_mfma_i32_16x16x64_i8 v[2:5], v[154:157], v[170:173], v[2:5]
	v_mfma_i32_16x16x64_i8 v[122:125], v[134:137], v[190:193], v[50:53]
	v_mfma_i32_16x16x64_i8 v[50:53], v[154:157], v[186:189], v[70:73]
	v_mfma_i32_16x16x64_i8 v[34:37], v[130:133], v[162:165], v[114:117]
	v_mfma_i32_16x16x64_i8 v[10:13], v[134:137], v[174:177], v[10:13]
	v_mfma_i32_16x16x64_i8 v[2:5], v[158:161], v[174:177], v[2:5]
	v_mfma_i32_16x16x64_i8 v[70:73], v[158:161], v[190:193], v[50:53]
	v_mfma_i32_16x16x64_i8 v[34:37], v[134:137], v[166:169], v[34:37]
	v_mfma_i32_16x16x64_i8 v[38:41], v[158:161], v[166:169], v[38:41]
	s_setprio 0
	s_barrier
; #define PG8_STAGE(bufoff, gbase, voff) do { _Pragma("unroll") for (int _i = 0; _i < 2; ++_i) \
;         __builtin_amdgcn_global_load_lds((const unsigned*)((const char*)(gbase) + (voff)[_i]), (PG8_LAS unsigned*)(lds + (bufoff) + ldsw + _i * 8192), 16, 0, 0); } while (0)
; #define PG8_LDA(dst, b, h) do { _Pragma("unroll") for (int m = 0; m < 4; ++m) _Pragma("unroll") for (int k = 0; k < 2; ++k) dst[m][k] = *(const PG8_LAS bf16x8*)(lds + PG8_SA(b, h) + aoff + m * 2048 + k * 1024); } while (0)
; #define PG8_LDB(dst, b, h) do { _Pragma("unroll") for (int n = 0; n < 2; ++n) _Pragma("unroll") for (int k = 0; k < 2; ++k) dst[n][k] = *(const PG8_LAS bf16x8*)(lds + PG8_SB(b, h) + boff + n * 2048 + k * 1024); } while (0)
; #define PG8_MMA(ai, bj, At, Bt) do { __builtin_amdgcn_s_setprio(1); _Pragma("unroll") for (int m = 0; m < 4; ++m) _Pragma("unroll") for (int n = 0; n < 2; ++n) _Pragma("unroll") for (int k = 0; k < 2; ++k) \
;         acc[ai][bj][m][n] = mma16<Epi::I8>(Bt[n][k], At[m][k], acc[ai][bj][m][n]); __builtin_amdgcn_s_setprio(0); } while (0)
; #define PG8_WAIT_V(n) asm volatile("s_waitcnt vmcnt(" #n ")" ::: "memory")
; template <class Epi, class Sched, bool ALIGN_EPI = false, bool SP2 = false>
; __device__ __forceinline__ void gemm_phase(PG8_LAS unsigned char* lds, const Gemm g, const Sched& S, const Epi& E) {
;     ...
;             PG8_LDB(B0, 0, 0); PG8_LDB(B1, 0, 1); PG8_SCHED; PG8_LDA(At, 0, 0); PG8_STAGE(PG8_SA(1, 1), a1 + hstep, voffA);
;             PG8_WAIT_V(8); PG8_WAIT_L(0); PG8_BAR; PG8_MMA(0, 0, At, B0); PG8_MMA(0, 1, At, B1); PG8_BAR; PG8_SCHED;
;             PG8_LDA(At, 0, 1); PG8_STAGE(PG8_SB(0, 0), b2, voffB); PG8_STAGE(PG8_SB(0, 1), b2 + hstep, voffB); PG8_STAGE(PG8_SA(0, 0), a2, voffA);
;             PG8_WAIT_V(8); PG8_WAIT_L(0); PG8_BAR; PG8_MMA(1, 0, At, B0); PG8_MMA(1, 1, At, B1); PG8_BAR; PG8_SCHED;
;             PG8_LDB(B0, 1, 0); PG8_LDB(B1, 1, 1); PG8_SCHED; PG8_LDA(At, 1, 0); PG8_STAGE(PG8_SA(0, 1), a2 + hstep, voffA);
;             PG8_WAIT_V(8); PG8_WAIT_L(0); PG8_BAR; PG8_MMA(0, 0, At, B0); PG8_MMA(0, 1, At, B1); PG8_BAR; PG8_SCHED;
;             PG8_LDA(At, 1, 1); PG8_STAGE(PG8_SB(1, 0), b3, voffB); PG8_STAGE(PG8_SB(1, 1), b3 + hstep, voffB); PG8_STAGE(PG8_SA(1, 0), a3, voffA);
;             PG8_WAIT_V(8); PG8_WAIT_L(0); PG8_BAR; PG8_MMA(1, 0, At, B0); PG8_MMA(1, 1, At, B1); PG8_BAR; PG8_SCHED;
	s_add_i32 s4, 0, 0x18000
	v_add_u32_e32 v126, s4, v242
	s_add_i32 s5, 0, 0x1c000
	ds_read_b128 v[50:53], v126
	ds_read_b128 v[66:69], v126 offset:1024
	ds_read_b128 v[114:117], v126 offset:2048
	ds_read_b128 v[130:133], v126 offset:3072
	v_add_u32_e32 v126, s5, v242
	ds_read_b128 v[134:137], v126
	ds_read_b128 v[154:157], v126 offset:1024
	ds_read_b128 v[158:161], v126 offset:2048
	ds_read_b128 v[162:165], v126 offset:3072
	s_add_u32 s0, s12, 0x40000
	s_addc_u32 s1, s13, 0
	s_mov_b32 m0, s80
	ds_read_b128 v[126:129], v243 offset:32768
	ds_read_b128 v[166:169], v243 offset:33792
	ds_read_b128 v[170:173], v243 offset:34816
	ds_read_b128 v[174:177], v243 offset:35840
	ds_read_b128 v[178:181], v243 offset:36864
	ds_read_b128 v[182:185], v243 offset:37888
	ds_read_b128 v[186:189], v243 offset:38912
	ds_read_b128 v[190:193], v243 offset:39936
	global_load_lds_dwordx4 v210, s[0:1]
	s_mov_b32 m0, s81
	s_nop 0
	global_load_lds_dwordx4 v212, s[0:1]
	s_waitcnt vmcnt(8)
	s_waitcnt lgkmcnt(0)
	s_barrier
	s_setprio 1
	s_waitcnt lgkmcnt(0)
	v_mfma_i32_16x16x64_i8 v[150:153], v[50:53], v[126:129], v[150:153]
	v_mfma_i32_16x16x64_i8 v[150:153], v[66:69], v[166:169], v[150:153]
	v_mfma_i32_16x16x64_i8 v[118:121], v[50:53], v[170:173], v[118:121]
	v_mfma_i32_16x16x64_i8 v[118:121], v[66:69], v[174:177], v[118:121]
	v_mfma_i32_16x16x64_i8 v[54:57], v[50:53], v[178:181], v[54:57]
	v_mfma_i32_16x16x64_i8 v[54:57], v[66:69], v[182:185], v[54:57]
	v_mfma_i32_16x16x64_i8 v[94:97], v[50:53], v[186:189], v[94:97]
	v_mfma_i32_16x16x64_i8 v[94:97], v[66:69], v[190:193], v[94:97]
	v_mfma_i32_16x16x64_i8 v[58:61], v[114:117], v[186:189], v[58:61]
	v_mfma_i32_16x16x64_i8 v[58:61], v[130:133], v[190:193], v[58:61]
	v_mfma_i32_16x16x64_i8 v[30:33], v[114:117], v[178:181], v[30:33]
	v_mfma_i32_16x16x64_i8 v[30:33], v[130:133], v[182:185], v[30:33]
	v_mfma_i32_16x16x64_i8 v[110:113], v[114:117], v[170:173], v[110:113]
	v_mfma_i32_16x16x64_i8 v[110:113], v[130:133], v[174:177], v[110:113]
	v_mfma_i32_16x16x64_i8 v[146:149], v[114:117], v[126:129], v[146:149]
	v_mfma_i32_16x16x64_i8 v[146:149], v[130:133], v[166:169], v[146:149]
	s_setprio 0
	s_setprio 1
	v_mfma_i32_16x16x64_i8 v[142:145], v[134:137], v[126:129], v[142:145]
	v_mfma_i32_16x16x64_i8 v[126:129], v[158:161], v[126:129], v[138:141]
	v_mfma_i32_16x16x64_i8 v[102:105], v[134:137], v[170:173], v[102:105]
	v_mfma_i32_16x16x64_i8 v[98:101], v[158:161], v[170:173], v[98:101]
	v_mfma_i32_16x16x64_i8 v[42:45], v[134:137], v[178:181], v[42:45]
	v_mfma_i32_16x16x64_i8 v[26:29], v[158:161], v[178:181], v[26:29]
	v_mfma_i32_16x16x64_i8 v[78:81], v[134:137], v[186:189], v[78:81]
	v_mfma_i32_16x16x64_i8 v[62:65], v[158:161], v[186:189], v[62:65]
	v_mfma_i32_16x16x64_i8 v[142:145], v[154:157], v[166:169], v[142:145]
	v_mfma_i32_16x16x64_i8 v[138:141], v[162:165], v[166:169], v[126:129]
	v_mfma_i32_16x16x64_i8 v[102:105], v[154:157], v[174:177], v[102:105]
	v_mfma_i32_16x16x64_i8 v[98:101], v[162:165], v[174:177], v[98:101]
	v_mfma_i32_16x16x64_i8 v[42:45], v[154:157], v[182:185], v[42:45]
	v_mfma_i32_16x16x64_i8 v[26:29], v[162:165], v[182:185], v[26:29]
	v_mfma_i32_16x16x64_i8 v[78:81], v[154:157], v[190:193], v[78:81]
	v_mfma_i32_16x16x64_i8 v[62:65], v[162:165], v[190:193], v[62:65]
	s_setprio 0
	s_barrier
	s_add_i32 s0, s4, s69
	v_lshl_add_u64 v[126:127], v[198:199], 0, s[92:93]
	s_mov_b32 m0, s0
	ds_read_b128 v[166:169], v243 offset:49152
	ds_read_b128 v[170:173], v243 offset:50176
	ds_read_b128 v[174:177], v243 offset:51200
	ds_read_b128 v[178:181], v243 offset:52224
	ds_read_b128 v[182:185], v243 offset:53248
	ds_read_b128 v[186:189], v243 offset:54272
	ds_read_b128 v[190:193], v243 offset:55296
	ds_read_b128 v[194:197], v243 offset:56320
	global_load_lds_dwordx4 v[126:127], off
	s_add_i32 m0, s0, 0x2000
	s_add_u32 s0, s6, 0x40080
	v_lshl_add_u64 v[126:127], v[200:201], 0, s[92:93]
	s_addc_u32 s1, s7, 0
	s_add_i32 s4, s5, s69
	global_load_lds_dwordx4 v[126:127], off
	s_mov_b32 m0, s4
	s_nop 0
	global_load_lds_dwordx4 v0, s[0:1]
	s_add_i32 m0, s4, 0x2000
	s_nop 0
	global_load_lds_dwordx4 v214, s[0:1]
	v_lshl_add_u64 v[126:127], v[206:207], 0, s[92:93]
	s_mov_b32 m0, s84
	s_nop 0
	global_load_lds_dwordx4 v[126:127], off
	v_lshl_add_u64 v[126:127], v[220:221], 0, s[92:93]
	s_mov_b32 m0, s85
	s_nop 0
	global_load_lds_dwordx4 v[126:127], off
	s_waitcnt vmcnt(8)
	s_waitcnt lgkmcnt(0)
	s_barrier
	s_setprio 1
	s_waitcnt lgkmcnt(0)
	v_mfma_i32_16x16x64_i8 v[18:21], v[50:53], v[190:193], v[18:21]
	v_mfma_i32_16x16x64_i8 v[106:109], v[50:53], v[166:169], v[106:109]
	v_mfma_i32_16x16x64_i8 v[46:49], v[114:117], v[166:169], v[46:49]
	v_mfma_i32_16x16x64_i8 v[14:17], v[50:53], v[174:177], v[14:17]
	v_mfma_i32_16x16x64_i8 v[6:9], v[114:117], v[174:177], v[6:9]
	v_mfma_i32_16x16x64_i8 v[90:93], v[50:53], v[182:185], v[90:93]
	v_mfma_i32_16x16x64_i8 v[86:89], v[114:117], v[182:185], v[86:89]
	v_mfma_i32_16x16x64_i8 v[126:129], v[66:69], v[194:197], v[18:21]
	v_mfma_i32_16x16x64_i8 v[18:21], v[114:117], v[190:193], v[22:25]
	v_mfma_i32_16x16x64_i8 v[106:109], v[66:69], v[170:173], v[106:109]
	v_mfma_i32_16x16x64_i8 v[46:49], v[130:133], v[170:173], v[46:49]
	v_mfma_i32_16x16x64_i8 v[14:17], v[66:69], v[178:181], v[14:17]
	v_mfma_i32_16x16x64_i8 v[6:9], v[130:133], v[178:181], v[6:9]
	v_mfma_i32_16x16x64_i8 v[90:93], v[66:69], v[186:189], v[90:93]
	v_mfma_i32_16x16x64_i8 v[86:89], v[130:133], v[186:189], v[86:89]
	v_mfma_i32_16x16x64_i8 v[66:69], v[130:133], v[194:197], v[18:21]
	s_setprio 0
	s_setprio 1
	v_mfma_i32_16x16x64_i8 v[18:21], v[134:137], v[166:169], v[34:37]
	v_mfma_i32_16x16x64_i8 v[114:117], v[154:157], v[170:173], v[18:21]
	v_mfma_i32_16x16x64_i8 v[18:21], v[158:161], v[166:169], v[38:41]
	v_mfma_i32_16x16x64_i8 v[50:53], v[162:165], v[170:173], v[18:21]
	v_mfma_i32_16x16x64_i8 v[18:21], v[134:137], v[182:185], v[82:85]
	v_mfma_i32_16x16x64_i8 v[82:85], v[154:157], v[186:189], v[18:21]
	v_mfma_i32_16x16x64_i8 v[18:21], v[158:161], v[182:185], v[74:77]
	v_mfma_i32_16x16x64_i8 v[74:77], v[162:165], v[186:189], v[18:21]
	v_mfma_i32_16x16x64_i8 v[18:21], v[134:137], v[190:193], v[122:125]
	v_mfma_i32_16x16x64_i8 v[10:13], v[134:137], v[174:177], v[10:13]
	v_mfma_i32_16x16x64_i8 v[2:5], v[158:161], v[174:177], v[2:5]
	v_mfma_i32_16x16x64_i8 v[122:125], v[154:157], v[194:197], v[18:21]
	v_mfma_i32_16x16x64_i8 v[18:21], v[158:161], v[190:193], v[70:73]
	v_mfma_i32_16x16x64_i8 v[10:13], v[154:157], v[178:181], v[10:13]
	v_mfma_i32_16x16x64_i8 v[2:5], v[162:165], v[178:181], v[2:5]
	v_mfma_i32_16x16x64_i8 v[70:73], v[162:165], v[194:197], v[18:21]
	s_setprio 0
	s_barrier
	s_add_i32 vcc_lo, vcc_lo, 2
	s_add_u32 s96, s96, 0x100
	s_addc_u32 s97, s97, 0
	s_cmp_gt_u32 vcc_lo, 13
	s_mov_b64 s[0:1], s[8:9]
	s_cbranch_scc0 .LBB0_80

; #define PG8_STAGE(bufoff, gbase, voff) do { _Pragma("unroll") for (int _i = 0; _i < 2; ++_i) \
;         __builtin_amdgcn_global_load_lds((const unsigned*)((const char*)(gbase) + (voff)[_i]), (PG8_LAS unsigned*)(lds + (bufoff) + ldsw + _i * 8192), 16, 0, 0); } while (0)
; #define PG8_LDA(dst, b, h) do { _Pragma("unroll") for (int m = 0; m < 4; ++m) _Pragma("unroll") for (int k = 0; k < 2; ++k) dst[m][k] = *(const PG8_LAS bf16x8*)(lds + PG8_SA(b, h) + aoff + m * 2048 + k * 1024); } while (0)
; #define PG8_LDB(dst, b, h) do { _Pragma("unroll") for (int n = 0; n < 2; ++n) _Pragma("unroll") for (int k = 0; k < 2; ++k) dst[n][k] = *(const PG8_LAS bf16x8*)(lds + PG8_SB(b, h) + boff + n * 2048 + k * 1024); } while (0)
; #define PG8_MMA(ai, bj, At, Bt) do { __builtin_amdgcn_s_setprio(1); _Pragma("unroll") for (int m = 0; m < 4; ++m) _Pragma("unroll") for (int n = 0; n < 2; ++n) _Pragma("unroll") for (int k = 0; k < 2; ++k) \
;         acc[ai][bj][m][n] = mma16<Epi::I8>(Bt[n][k], At[m][k], acc[ai][bj][m][n]); __builtin_amdgcn_s_setprio(0); } while (0)
; #define PG8_WAIT_V(n) asm volatile("s_waitcnt vmcnt(" #n ")" ::: "memory")
; #define PG8_WAIT_L(n) asm volatile("s_waitcnt lgkmcnt(" #n ")" ::: "memory")
; #define PG8_BAR __builtin_amdgcn_s_barrier()
; #define PG8_SCHED __builtin_amdgcn_sched_barrier(0)
; template <class Epi, class Sched, bool ALIGN_EPI = false, bool SP2 = false>
; __device__ __forceinline__ void gemm_phase(PG8_LAS unsigned char* lds, const Gemm g, const Sched& S, const Epi& E) {
;     ...
;             PG8_LDB(B0, 0, 0); PG8_LDB(B1, 0, 1); PG8_SCHED; PG8_LDA(At, 0, 0); PG8_STAGE(PG8_SA(1, 1), a1 + hstep, voffA);
;             PG8_WAIT_V(8); PG8_WAIT_L(0); PG8_BAR; PG8_MMA(0, 0, At, B0); PG8_MMA(0, 1, At, B1); PG8_BAR; PG8_SCHED;
;             PG8_LDA(At, 0, 1); PG8_STAGE(PG8_SB(0, 0), b2, voffB); PG8_STAGE(PG8_SB(0, 1), b2 + hstep, voffB); PG8_STAGE(PG8_SA(0, 0), a2, voffA);
;             PG8_WAIT_V(8); PG8_WAIT_L(0); PG8_BAR; PG8_MMA(1, 0, At, B0); PG8_MMA(1, 1, At, B1); PG8_BAR; PG8_SCHED;
.Lpeel175:
	s_add_i32 vcc_lo, s8, 2
	s_add_u32 s4, s6, 0x80
	s_addc_u32 s5, s7, 0
	s_add_i32 vcc_hi, 0, 0x10000
	s_cmp_eq_u32 s13, s8
	s_cselect_b32 s9, s1, s5
	s_cselect_b32 s8, s0, s4
	s_cselect_b32 s5, s97, s85
	s_cselect_b32 s4, s96, s67
	s_add_i32 s84, 0, 0x14000
	v_add_u32_e32 v122, vcc_hi, v248
	v_add_u32_e32 v154, s84, v248
	ds_read_b128 v[98:101], v122
	ds_read_b128 v[102:105], v122 offset:1024
	ds_read_b128 v[114:117], v122 offset:2048
	ds_read_b128 v[122:125], v122 offset:3072
	ds_read_b128 v[130:133], v154
	ds_read_b128 v[138:141], v154 offset:1024
	ds_read_b128 v[146:149], v154 offset:2048
	ds_read_b128 v[154:157], v154 offset:3072
	v_lshl_add_u64 v[206:207], s[6:7], 0, v[200:201]
	s_add_i32 m0, s81, 0xc000
	ds_read_b128 v[162:165], v249
	ds_read_b128 v[166:169], v249 offset:1024
	ds_read_b128 v[170:173], v249 offset:2048
	ds_read_b128 v[174:177], v249 offset:3072
	ds_read_b128 v[178:181], v249 offset:4096
	ds_read_b128 v[182:185], v249 offset:5120
	ds_read_b128 v[186:189], v249 offset:6144
	ds_read_b128 v[190:193], v249 offset:7168
	global_load_lds_dwordx4 v[206:207], off
	v_lshl_add_u64 v[206:207], s[6:7], 0, v[210:211]
	s_add_i32 m0, s81, 0xe000
	s_nop 0
	global_load_lds_dwordx4 v[206:207], off
	s_waitcnt vmcnt(8)
	s_waitcnt lgkmcnt(0)
	s_barrier
	s_setprio 1
	s_waitcnt lgkmcnt(0)
	v_mfma_f32_16x16x32_bf16 v[158:161], v[98:101], v[162:165], 0
	v_mfma_f32_16x16x32_bf16 v[158:161], v[102:105], v[166:169], v[158:161]
	v_mfma_f32_16x16x32_bf16 v[126:129], v[98:101], v[170:173], 0
	v_mfma_f32_16x16x32_bf16 v[126:129], v[102:105], v[174:177], v[126:129]
	v_mfma_f32_16x16x32_bf16 v[94:97], v[98:101], v[178:181], 0
	v_mfma_f32_16x16x32_bf16 v[94:97], v[102:105], v[182:185], v[94:97]
	v_mfma_f32_16x16x32_bf16 v[78:81], v[98:101], v[186:189], 0
	v_mfma_f32_16x16x32_bf16 v[78:81], v[102:105], v[190:193], v[78:81]
	v_mfma_f32_16x16x32_bf16 v[74:77], v[114:117], v[186:189], 0
	v_mfma_f32_16x16x32_bf16 v[74:77], v[122:125], v[190:193], v[74:77]
	v_mfma_f32_16x16x32_bf16 v[90:93], v[114:117], v[178:181], 0
	v_mfma_f32_16x16x32_bf16 v[90:93], v[122:125], v[182:185], v[90:93]
	v_mfma_f32_16x16x32_bf16 v[118:121], v[114:117], v[170:173], 0
	v_mfma_f32_16x16x32_bf16 v[118:121], v[122:125], v[174:177], v[118:121]
	v_mfma_f32_16x16x32_bf16 v[150:153], v[114:117], v[162:165], 0
	v_mfma_f32_16x16x32_bf16 v[150:153], v[122:125], v[166:169], v[150:153]
	s_setprio 0
	s_setprio 1
	v_mfma_f32_16x16x32_bf16 v[142:145], v[130:133], v[162:165], 0
	v_mfma_f32_16x16x32_bf16 v[142:145], v[138:141], v[166:169], v[142:145]
	v_mfma_f32_16x16x32_bf16 v[110:113], v[130:133], v[170:173], 0
	v_mfma_f32_16x16x32_bf16 v[110:113], v[138:141], v[174:177], v[110:113]
	v_mfma_f32_16x16x32_bf16 v[86:89], v[130:133], v[178:181], 0
	v_mfma_f32_16x16x32_bf16 v[86:89], v[138:141], v[182:185], v[86:89]
	v_mfma_f32_16x16x32_bf16 v[70:73], v[130:133], v[186:189], 0
	v_mfma_f32_16x16x32_bf16 v[70:73], v[138:141], v[190:193], v[70:73]
	v_mfma_f32_16x16x32_bf16 v[66:69], v[146:149], v[186:189], 0
	v_mfma_f32_16x16x32_bf16 v[66:69], v[154:157], v[190:193], v[66:69]
	v_mfma_f32_16x16x32_bf16 v[82:85], v[146:149], v[178:181], 0
	v_mfma_f32_16x16x32_bf16 v[82:85], v[154:157], v[182:185], v[82:85]
	v_mfma_f32_16x16x32_bf16 v[106:109], v[146:149], v[170:173], 0
	v_mfma_f32_16x16x32_bf16 v[106:109], v[154:157], v[174:177], v[106:109]
	v_mfma_f32_16x16x32_bf16 v[134:137], v[146:149], v[162:165], 0
	v_mfma_f32_16x16x32_bf16 v[134:137], v[154:157], v[166:169], v[134:137]
	s_setprio 0
	s_barrier
	s_add_i32 vcc_hi, vcc_hi, s80
	v_lshl_add_u64 v[206:207], s[4:5], 0, v[0:1]
	s_mov_b32 m0, vcc_hi
	ds_read_b128 v[162:165], v249 offset:16384
	ds_read_b128 v[166:169], v249 offset:17408
	ds_read_b128 v[170:173], v249 offset:18432
	ds_read_b128 v[174:177], v249 offset:19456
	ds_read_b128 v[178:181], v249 offset:20480
	ds_read_b128 v[182:185], v249 offset:21504
	ds_read_b128 v[186:189], v249 offset:22528
	ds_read_b128 v[190:193], v249 offset:23552
	global_load_lds_dwordx4 v[206:207], off
	s_add_i32 m0, vcc_hi, 0x2000
	v_lshl_add_u64 v[212:213], s[4:5], 0, v[198:199]
	s_add_u32 s4, s4, s58
	s_addc_u32 s5, s5, 0
	s_add_i32 s84, s84, s80
	global_load_lds_dwordx4 v[212:213], off
	v_lshl_add_u64 v[214:215], s[4:5], 0, v[0:1]
	s_mov_b32 m0, s84
	v_lshl_add_u64 v[216:217], s[4:5], 0, v[198:199]
	global_load_lds_dwordx4 v[214:215], off
	s_add_i32 m0, s84, 0x2000
	v_lshl_add_u64 v[218:219], s[8:9], 0, v[194:195]
	global_load_lds_dwordx4 v[216:217], off
	s_mov_b32 m0, s81
	v_lshl_add_u64 v[220:221], s[8:9], 0, v[196:197]
	global_load_lds_dwordx4 v[218:219], off
	s_mov_b32 m0, s70
	s_nop 0
	global_load_lds_dwordx4 v[220:221], off
	s_waitcnt vmcnt(8)
	s_waitcnt lgkmcnt(0)
	s_barrier
; #define PG8_STAGE(bufoff, gbase, voff) do { _Pragma("unroll") for (int _i = 0; _i < 2; ++_i) \
;         __builtin_amdgcn_global_load_lds((const unsigned*)((const char*)(gbase) + (voff)[_i]), (PG8_LAS unsigned*)(lds + (bufoff) + ldsw + _i * 8192), 16, 0, 0); } while (0)
; #define PG8_LDA(dst, b, h) do { _Pragma("unroll") for (int m = 0; m < 4; ++m) _Pragma("unroll") for (int k = 0; k < 2; ++k) dst[m][k] = *(const PG8_LAS bf16x8*)(lds + PG8_SA(b, h) + aoff + m * 2048 + k * 1024); } while (0)
; #define PG8_LDB(dst, b, h) do { _Pragma("unroll") for (int n = 0; n < 2; ++n) _Pragma("unroll") for (int k = 0; k < 2; ++k) dst[n][k] = *(const PG8_LAS bf16x8*)(lds + PG8_SB(b, h) + boff + n * 2048 + k * 1024); } while (0)
; #define PG8_MMA(ai, bj, At, Bt) do { __builtin_amdgcn_s_setprio(1); _Pragma("unroll") for (int m = 0; m < 4; ++m) _Pragma("unroll") for (int n = 0; n < 2; ++n) _Pragma("unroll") for (int k = 0; k < 2; ++k) \
;         acc[ai][bj][m][n] = mma16<Epi::I8>(Bt[n][k], At[m][k], acc[ai][bj][m][n]); __builtin_amdgcn_s_setprio(0); } while (0)
; #define PG8_WAIT_V(n) asm volatile("s_waitcnt vmcnt(" #n ")" ::: "memory")
; #define PG8_WAIT_L(n) asm volatile("s_waitcnt lgkmcnt(" #n ")" ::: "memory")
; #define PG8_BAR __builtin_amdgcn_s_barrier()
; #define PG8_SCHED __builtin_amdgcn_sched_barrier(0)
; template <class Epi, class Sched, bool ALIGN_EPI = false, bool SP2 = false>
; __device__ __forceinline__ void gemm_phase(PG8_LAS unsigned char* lds, const Gemm g, const Sched& S, const Epi& E) {
;     ...
;             PG8_LDA(At, 0, 1); PG8_STAGE(PG8_SB(0, 0), b2, voffB); PG8_STAGE(PG8_SB(0, 1), b2 + hstep, voffB); PG8_STAGE(PG8_SA(0, 0), a2, voffA);
;             PG8_WAIT_V(8); PG8_WAIT_L(0); PG8_BAR; PG8_MMA(1, 0, At, B0); PG8_MMA(1, 1, At, B1); PG8_BAR; PG8_SCHED;
;             PG8_LDB(B0, 1, 0); PG8_LDB(B1, 1, 1); PG8_SCHED; PG8_LDA(At, 1, 0); PG8_STAGE(PG8_SA(0, 1), a2 + hstep, voffA);
;             PG8_WAIT_V(8); PG8_WAIT_L(0); PG8_BAR; PG8_MMA(0, 0, At, B0); PG8_MMA(0, 1, At, B1); PG8_BAR; PG8_SCHED;
	s_setprio 1
	s_waitcnt lgkmcnt(0)
	v_mfma_f32_16x16x32_bf16 v[62:65], v[98:101], v[162:165], 0
	v_mfma_f32_16x16x32_bf16 v[62:65], v[102:105], v[166:169], v[62:65]
	v_mfma_f32_16x16x32_bf16 v[46:49], v[98:101], v[170:173], 0
	v_mfma_f32_16x16x32_bf16 v[46:49], v[102:105], v[174:177], v[46:49]
	v_mfma_f32_16x16x32_bf16 v[30:33], v[98:101], v[178:181], 0
	v_mfma_f32_16x16x32_bf16 v[30:33], v[102:105], v[182:185], v[30:33]
	v_mfma_f32_16x16x32_bf16 v[14:17], v[98:101], v[186:189], 0
	v_mfma_f32_16x16x32_bf16 v[14:17], v[102:105], v[190:193], v[14:17]
	v_mfma_f32_16x16x32_bf16 v[10:13], v[114:117], v[186:189], 0
	v_mfma_f32_16x16x32_bf16 v[10:13], v[122:125], v[190:193], v[10:13]
	v_mfma_f32_16x16x32_bf16 v[26:29], v[114:117], v[178:181], 0
	v_mfma_f32_16x16x32_bf16 v[26:29], v[122:125], v[182:185], v[26:29]
	v_mfma_f32_16x16x32_bf16 v[42:45], v[114:117], v[170:173], 0
	v_mfma_f32_16x16x32_bf16 v[42:45], v[122:125], v[174:177], v[42:45]
	v_mfma_f32_16x16x32_bf16 v[58:61], v[114:117], v[162:165], 0
	v_mfma_f32_16x16x32_bf16 v[58:61], v[122:125], v[166:169], v[58:61]
	s_setprio 0
	s_setprio 1
	v_mfma_f32_16x16x32_bf16 v[54:57], v[130:133], v[162:165], 0
	v_mfma_f32_16x16x32_bf16 v[54:57], v[138:141], v[166:169], v[54:57]
	v_mfma_f32_16x16x32_bf16 v[38:41], v[130:133], v[170:173], 0
	v_mfma_f32_16x16x32_bf16 v[38:41], v[138:141], v[174:177], v[38:41]
	v_mfma_f32_16x16x32_bf16 v[22:25], v[130:133], v[178:181], 0
	v_mfma_f32_16x16x32_bf16 v[22:25], v[138:141], v[182:185], v[22:25]
	v_mfma_f32_16x16x32_bf16 v[6:9], v[130:133], v[186:189], 0
	v_mfma_f32_16x16x32_bf16 v[6:9], v[138:141], v[190:193], v[6:9]
	v_mfma_f32_16x16x32_bf16 v[2:5], v[146:149], v[186:189], 0
	v_mfma_f32_16x16x32_bf16 v[2:5], v[154:157], v[190:193], v[2:5]
	v_mfma_f32_16x16x32_bf16 v[18:21], v[146:149], v[178:181], 0
	v_mfma_f32_16x16x32_bf16 v[18:21], v[154:157], v[182:185], v[18:21]
	v_mfma_f32_16x16x32_bf16 v[34:37], v[146:149], v[170:173], 0
	v_mfma_f32_16x16x32_bf16 v[34:37], v[154:157], v[174:177], v[34:37]
	v_mfma_f32_16x16x32_bf16 v[50:53], v[146:149], v[162:165], 0
	v_mfma_f32_16x16x32_bf16 v[50:53], v[154:157], v[166:169], v[50:53]
	s_setprio 0
	s_barrier
	s_add_i32 s84, 0, 0x18000
	s_add_i32 vcc_hi, 0, 0x1c000
	v_add_u32_e32 v122, s84, v248
	v_add_u32_e32 v154, vcc_hi, v248
	ds_read_b128 v[98:101], v122
	ds_read_b128 v[102:105], v122 offset:1024
	ds_read_b128 v[114:117], v122 offset:2048
	ds_read_b128 v[122:125], v122 offset:3072
	ds_read_b128 v[130:133], v154
	ds_read_b128 v[138:141], v154 offset:1024
	ds_read_b128 v[146:149], v154 offset:2048
	ds_read_b128 v[154:157], v154 offset:3072
	s_add_u32 s4, s8, s58
	s_addc_u32 s5, s9, 0
	s_mov_b32 m0, s71
	v_lshl_add_u64 v[222:223], s[4:5], 0, v[194:195]
	ds_read_b128 v[162:165], v249 offset:32768
	ds_read_b128 v[166:169], v249 offset:33792
	ds_read_b128 v[170:173], v249 offset:34816
	ds_read_b128 v[174:177], v249 offset:35840
	ds_read_b128 v[178:181], v249 offset:36864
	ds_read_b128 v[182:185], v249 offset:37888
	ds_read_b128 v[186:189], v249 offset:38912
	ds_read_b128 v[190:193], v249 offset:39936
	global_load_lds_dwordx4 v[222:223], off
	v_lshl_add_u64 v[222:223], s[4:5], 0, v[196:197]
	s_mov_b32 m0, s12
	s_nop 0
	global_load_lds_dwordx4 v[222:223], off
	s_waitcnt vmcnt(8)
	s_waitcnt lgkmcnt(0)
	s_barrier
	s_setprio 1
	s_waitcnt lgkmcnt(0)
	v_mfma_f32_16x16x32_bf16 v[158:161], v[98:101], v[162:165], v[158:161]
	v_mfma_f32_16x16x32_bf16 v[158:161], v[102:105], v[166:169], v[158:161]
	v_mfma_f32_16x16x32_bf16 v[126:129], v[98:101], v[170:173], v[126:129]
	v_mfma_f32_16x16x32_bf16 v[126:129], v[102:105], v[174:177], v[126:129]
	v_mfma_f32_16x16x32_bf16 v[94:97], v[98:101], v[178:181], v[94:97]
	v_mfma_f32_16x16x32_bf16 v[94:97], v[102:105], v[182:185], v[94:97]
	v_mfma_f32_16x16x32_bf16 v[78:81], v[98:101], v[186:189], v[78:81]
	v_mfma_f32_16x16x32_bf16 v[78:81], v[102:105], v[190:193], v[78:81]
	v_mfma_f32_16x16x32_bf16 v[74:77], v[114:117], v[186:189], v[74:77]
	v_mfma_f32_16x16x32_bf16 v[74:77], v[122:125], v[190:193], v[74:77]
	v_mfma_f32_16x16x32_bf16 v[90:93], v[114:117], v[178:181], v[90:93]
	v_mfma_f32_16x16x32_bf16 v[90:93], v[122:125], v[182:185], v[90:93]
	v_mfma_f32_16x16x32_bf16 v[118:121], v[114:117], v[170:173], v[118:121]
	v_mfma_f32_16x16x32_bf16 v[118:121], v[122:125], v[174:177], v[118:121]
	v_mfma_f32_16x16x32_bf16 v[150:153], v[114:117], v[162:165], v[150:153]
	v_mfma_f32_16x16x32_bf16 v[150:153], v[122:125], v[166:169], v[150:153]
	s_setprio 0
	s_setprio 1
	v_mfma_f32_16x16x32_bf16 v[142:145], v[130:133], v[162:165], v[142:145]
	v_mfma_f32_16x16x32_bf16 v[142:145], v[138:141], v[166:169], v[142:145]
	v_mfma_f32_16x16x32_bf16 v[110:113], v[130:133], v[170:173], v[110:113]
	v_mfma_f32_16x16x32_bf16 v[110:113], v[138:141], v[174:177], v[110:113]
	v_mfma_f32_16x16x32_bf16 v[86:89], v[130:133], v[178:181], v[86:89]
	v_mfma_f32_16x16x32_bf16 v[86:89], v[138:141], v[182:185], v[86:89]
	v_mfma_f32_16x16x32_bf16 v[70:73], v[130:133], v[186:189], v[70:73]
	v_mfma_f32_16x16x32_bf16 v[70:73], v[138:141], v[190:193], v[70:73]
	v_mfma_f32_16x16x32_bf16 v[66:69], v[146:149], v[186:189], v[66:69]
	v_mfma_f32_16x16x32_bf16 v[66:69], v[154:157], v[190:193], v[66:69]
	v_mfma_f32_16x16x32_bf16 v[82:85], v[146:149], v[178:181], v[82:85]
	v_mfma_f32_16x16x32_bf16 v[82:85], v[154:157], v[182:185], v[82:85]
	v_mfma_f32_16x16x32_bf16 v[106:109], v[146:149], v[170:173], v[106:109]
	v_mfma_f32_16x16x32_bf16 v[106:109], v[154:157], v[174:177], v[106:109]
	v_mfma_f32_16x16x32_bf16 v[134:137], v[146:149], v[162:165], v[134:137]
	v_mfma_f32_16x16x32_bf16 v[134:137], v[154:157], v[166:169], v[134:137]
	s_setprio 0
	s_barrier
; #define PG8_STAGE(bufoff, gbase, voff) do { _Pragma("unroll") for (int _i = 0; _i < 2; ++_i) \
;         __builtin_amdgcn_global_load_lds((const unsigned*)((const char*)(gbase) + (voff)[_i]), (PG8_LAS unsigned*)(lds + (bufoff) + ldsw + _i * 8192), 16, 0, 0); } while (0)
; #define PG8_LDA(dst, b, h) do { _Pragma("unroll") for (int m = 0; m < 4; ++m) _Pragma("unroll") for (int k = 0; k < 2; ++k) dst[m][k] = *(const PG8_LAS bf16x8*)(lds + PG8_SA(b, h) + aoff + m * 2048 + k * 1024); } while (0)
; #define PG8_LDB(dst, b, h) do { _Pragma("unroll") for (int n = 0; n < 2; ++n) _Pragma("unroll") for (int k = 0; k < 2; ++k) dst[n][k] = *(const PG8_LAS bf16x8*)(lds + PG8_SB(b, h) + boff + n * 2048 + k * 1024); } while (0)
; template <class Epi, class Sched, bool ALIGN_EPI = false, bool SP2 = false>
; __device__ __forceinline__ void gemm_phase(PG8_LAS unsigned char* lds, const Gemm g, const Sched& S, const Epi& E) {
;     ...
;         for (int t = 0; t < nt; t += 2) {
;             const bool last = (t == nt - 2);
;             const char* a1 = cA + (size_t)(t + 1) * kstep;
;             const char* a2 = last ? nA : cA + (size_t)(t + 2) * kstep; const char* b2 = last ? nB : cB + (size_t)(t + 2) * kstep;
;             const char* a3 = a2 + kstep; const char* b3 = b2 + kstep;
;             if (last && has_next) S.a_ready(nxt);
;             if constexpr (SP2) {
;             PG8_LDB(B0, 0, 0); PG8_LDB(B1, 0, 1); PG8_SCHED; PG8_LDA(At, 0, 0); PG8_STAGE(PG8_SA(1, 1), a1 + hstep, voffA);
;             PG8_WAIT_V(8); PG8_WAIT_L(0); PG8_BAR; PG8_MMA(0, 0, At, B0); PG8_MMA(0, 1, At, B1); PG8_BAR; PG8_SCHED;
;             PG8_LDA(At, 0, 1); PG8_STAGE(PG8_SB(0, 0), b2, voffB); PG8_STAGE(PG8_SB(0, 1), b2 + hstep, voffB); PG8_STAGE(PG8_SA(0, 0), a2, voffA);
;             PG8_WAIT_V(8); PG8_WAIT_L(0); PG8_BAR; PG8_MMA(1, 0, At, B0); PG8_MMA(1, 1, At, B1); PG8_BAR; PG8_SCHED;
;             PG8_LDB(B0, 1, 0); PG8_LDB(B1, 1, 1); PG8_SCHED; PG8_LDA(At, 1, 0); PG8_STAGE(PG8_SA(0, 1), a2 + hstep, voffA);
;             PG8_WAIT_V(8); PG8_WAIT_L(0); PG8_BAR; PG8_MMA(0, 0, At, B0); PG8_MMA(0, 1, At, B1); PG8_BAR; PG8_SCHED;
;             PG8_LDA(At, 1, 1); PG8_STAGE(PG8_SB(1, 0), b3, voffB); PG8_STAGE(PG8_SB(1, 1), b3 + hstep, voffB); PG8_STAGE(PG8_SA(1, 0), a3, voffA);
;             PG8_WAIT_V(8); PG8_WAIT_L(0); PG8_BAR; PG8_MMA(1, 0, At, B0); PG8_MMA(1, 1, At, B1); PG8_BAR; PG8_SCHED;
	s_add_i32 s4, s84, s80
	v_lshl_add_u64 v[206:207], v[206:207], 0, s[92:93]
	s_mov_b32 m0, s4
	ds_read_b128 v[162:165], v249 offset:49152
	ds_read_b128 v[166:169], v249 offset:50176
	ds_read_b128 v[170:173], v249 offset:51200
	ds_read_b128 v[174:177], v249 offset:52224
	ds_read_b128 v[178:181], v249 offset:53248
	ds_read_b128 v[182:185], v249 offset:54272
	ds_read_b128 v[186:189], v249 offset:55296
	ds_read_b128 v[190:193], v249 offset:56320
	global_load_lds_dwordx4 v[206:207], off
	v_lshl_add_u64 v[206:207], v[212:213], 0, s[92:93]
	s_add_i32 m0, s4, 0x2000
	s_add_i32 s4, vcc_hi, s80
	global_load_lds_dwordx4 v[206:207], off
	v_lshl_add_u64 v[206:207], v[214:215], 0, s[92:93]
	s_mov_b32 m0, s4
	s_nop 0
	global_load_lds_dwordx4 v[206:207], off
	v_lshl_add_u64 v[206:207], v[216:217], 0, s[92:93]
	s_add_i32 m0, s4, 0x2000
	s_nop 0
	global_load_lds_dwordx4 v[206:207], off
	v_lshl_add_u64 v[206:207], v[218:219], 0, s[92:93]
	s_mov_b32 m0, s10
	s_nop 0
	global_load_lds_dwordx4 v[206:207], off
	v_lshl_add_u64 v[206:207], v[220:221], 0, s[92:93]
	s_mov_b32 m0, s11
	s_nop 0
	global_load_lds_dwordx4 v[206:207], off
	s_waitcnt vmcnt(8)
	s_waitcnt lgkmcnt(0)
	s_barrier
	s_setprio 1
	s_waitcnt lgkmcnt(0)
	v_mfma_f32_16x16x32_bf16 v[62:65], v[98:101], v[162:165], v[62:65]
	v_mfma_f32_16x16x32_bf16 v[62:65], v[102:105], v[166:169], v[62:65]
	v_mfma_f32_16x16x32_bf16 v[46:49], v[98:101], v[170:173], v[46:49]
	v_mfma_f32_16x16x32_bf16 v[46:49], v[102:105], v[174:177], v[46:49]
	v_mfma_f32_16x16x32_bf16 v[30:33], v[98:101], v[178:181], v[30:33]
	v_mfma_f32_16x16x32_bf16 v[30:33], v[102:105], v[182:185], v[30:33]
	v_mfma_f32_16x16x32_bf16 v[14:17], v[98:101], v[186:189], v[14:17]
	v_mfma_f32_16x16x32_bf16 v[14:17], v[102:105], v[190:193], v[14:17]
	v_mfma_f32_16x16x32_bf16 v[10:13], v[114:117], v[186:189], v[10:13]
	v_mfma_f32_16x16x32_bf16 v[10:13], v[122:125], v[190:193], v[10:13]
	v_mfma_f32_16x16x32_bf16 v[26:29], v[114:117], v[178:181], v[26:29]
	v_mfma_f32_16x16x32_bf16 v[26:29], v[122:125], v[182:185], v[26:29]
	v_mfma_f32_16x16x32_bf16 v[42:45], v[114:117], v[170:173], v[42:45]
	v_mfma_f32_16x16x32_bf16 v[42:45], v[122:125], v[174:177], v[42:45]
	v_mfma_f32_16x16x32_bf16 v[58:61], v[114:117], v[162:165], v[58:61]
	v_mfma_f32_16x16x32_bf16 v[58:61], v[122:125], v[166:169], v[58:61]
	s_setprio 0
	s_setprio 1
	v_mfma_f32_16x16x32_bf16 v[54:57], v[130:133], v[162:165], v[54:57]
	v_mfma_f32_16x16x32_bf16 v[54:57], v[138:141], v[166:169], v[54:57]
	v_mfma_f32_16x16x32_bf16 v[38:41], v[130:133], v[170:173], v[38:41]
	v_mfma_f32_16x16x32_bf16 v[38:41], v[138:141], v[174:177], v[38:41]
	v_mfma_f32_16x16x32_bf16 v[22:25], v[130:133], v[178:181], v[22:25]
	v_mfma_f32_16x16x32_bf16 v[22:25], v[138:141], v[182:185], v[22:25]
	v_mfma_f32_16x16x32_bf16 v[6:9], v[130:133], v[186:189], v[6:9]
	v_mfma_f32_16x16x32_bf16 v[6:9], v[138:141], v[190:193], v[6:9]
	v_mfma_f32_16x16x32_bf16 v[2:5], v[146:149], v[186:189], v[2:5]
	v_mfma_f32_16x16x32_bf16 v[2:5], v[154:157], v[190:193], v[2:5]
	v_mfma_f32_16x16x32_bf16 v[18:21], v[146:149], v[178:181], v[18:21]
	v_mfma_f32_16x16x32_bf16 v[18:21], v[154:157], v[182:185], v[18:21]
	v_mfma_f32_16x16x32_bf16 v[34:37], v[146:149], v[170:173], v[34:37]
	v_mfma_f32_16x16x32_bf16 v[34:37], v[154:157], v[174:177], v[34:37]
	v_mfma_f32_16x16x32_bf16 v[50:53], v[146:149], v[162:165], v[50:53]
	v_mfma_f32_16x16x32_bf16 v[50:53], v[154:157], v[166:169], v[50:53]
	s_setprio 0
	s_barrier
	s_add_u32 s6, s6, 0x100
	s_addc_u32 s7, s7, 0
	s_add_u32 s67, s67, 0x100
	s_addc_u32 s85, s85, 0
	s_cmp_ge_u32 vcc_lo, s69
	s_mov_b32 s8, vcc_lo
	s_cbranch_scc0 .LBB0_175
	s_branch .Lpeelx175
.LBB0_175:
	s_add_i32 vcc_lo, s8, 2
	s_add_u32 s4, s6, 0x80
	s_addc_u32 s5, s7, 0
	s_add_i32 vcc_hi, 0, 0x10000
	s_cmp_eq_u32 s13, s8
	s_cselect_b32 s9, s1, s5
	s_cselect_b32 s8, s0, s4
	s_cselect_b32 s5, s97, s85
	s_cselect_b32 s4, s96, s67
	s_add_i32 s84, 0, 0x14000
	v_add_u32_e32 v122, vcc_hi, v248
	v_add_u32_e32 v154, s84, v248
	ds_read_b128 v[98:101], v122
	ds_read_b128 v[102:105], v122 offset:1024
	ds_read_b128 v[114:117], v122 offset:2048
	ds_read_b128 v[122:125], v122 offset:3072
	ds_read_b128 v[130:133], v154
	ds_read_b128 v[138:141], v154 offset:1024
	ds_read_b128 v[146:149], v154 offset:2048
	ds_read_b128 v[154:157], v154 offset:3072
	v_lshl_add_u64 v[206:207], s[6:7], 0, v[200:201]
	s_add_i32 m0, s81, 0xc000
	ds_read_b128 v[162:165], v249
	ds_read_b128 v[166:169], v249 offset:1024
	ds_read_b128 v[170:173], v249 offset:2048
	ds_read_b128 v[174:177], v249 offset:3072
	ds_read_b128 v[178:181], v249 offset:4096
	ds_read_b128 v[182:185], v249 offset:5120
	ds_read_b128 v[186:189], v249 offset:6144
	ds_read_b128 v[190:193], v249 offset:7168
	global_load_lds_dwordx4 v[206:207], off
	v_lshl_add_u64 v[206:207], s[6:7], 0, v[210:211]
	s_add_i32 m0, s81, 0xe000
	s_nop 0
	global_load_lds_dwordx4 v[206:207], off
	s_waitcnt vmcnt(8)
	s_waitcnt lgkmcnt(0)
	s_barrier
; #define PG8_STAGE(bufoff, gbase, voff) do { _Pragma("unroll") for (int _i = 0; _i < 2; ++_i) \
;         __builtin_amdgcn_global_load_lds((const unsigned*)((const char*)(gbase) + (voff)[_i]), (PG8_LAS unsigned*)(lds + (bufoff) + ldsw + _i * 8192), 16, 0, 0); } while (0)
; #define PG8_LDA(dst, b, h) do { _Pragma("unroll") for (int m = 0; m < 4; ++m) _Pragma("unroll") for (int k = 0; k < 2; ++k) dst[m][k] = *(const PG8_LAS bf16x8*)(lds + PG8_SA(b, h) + aoff + m * 2048 + k * 1024); } while (0)
; #define PG8_LDB(dst, b, h) do { _Pragma("unroll") for (int n = 0; n < 2; ++n) _Pragma("unroll") for (int k = 0; k < 2; ++k) dst[n][k] = *(const PG8_LAS bf16x8*)(lds + PG8_SB(b, h) + boff + n * 2048 + k * 1024); } while (0)
; #define PG8_MMA(ai, bj, At, Bt) do { __builtin_amdgcn_s_setprio(1); _Pragma("unroll") for (int m = 0; m < 4; ++m) _Pragma("unroll") for (int n = 0; n < 2; ++n) _Pragma("unroll") for (int k = 0; k < 2; ++k) \
;         acc[ai][bj][m][n] = mma16<Epi::I8>(Bt[n][k], At[m][k], acc[ai][bj][m][n]); __builtin_amdgcn_s_setprio(0); } while (0)
; #define PG8_WAIT_V(n) asm volatile("s_waitcnt vmcnt(" #n ")" ::: "memory")
; #define PG8_WAIT_L(n) asm volatile("s_waitcnt lgkmcnt(" #n ")" ::: "memory")
; #define PG8_BAR __builtin_amdgcn_s_barrier()
; #define PG8_SCHED __builtin_amdgcn_sched_barrier(0)
; template <class Epi, class Sched, bool ALIGN_EPI = false, bool SP2 = false>
; __device__ __forceinline__ void gemm_phase(PG8_LAS unsigned char* lds, const Gemm g, const Sched& S, const Epi& E) {
;     ...
;             PG8_LDB(B0, 0, 0); PG8_LDB(B1, 0, 1); PG8_SCHED; PG8_LDA(At, 0, 0); PG8_STAGE(PG8_SA(1, 1), a1 + hstep, voffA);
;             PG8_WAIT_V(8); PG8_WAIT_L(0); PG8_BAR; PG8_MMA(0, 0, At, B0); PG8_MMA(0, 1, At, B1); PG8_BAR; PG8_SCHED;
;             PG8_LDA(At, 0, 1); PG8_STAGE(PG8_SB(0, 0), b2, voffB); PG8_STAGE(PG8_SB(0, 1), b2 + hstep, voffB); PG8_STAGE(PG8_SA(0, 0), a2, voffA);
;             PG8_WAIT_V(8); PG8_WAIT_L(0); PG8_BAR; PG8_MMA(1, 0, At, B0); PG8_MMA(1, 1, At, B1); PG8_BAR; PG8_SCHED;
;             PG8_LDB(B0, 1, 0); PG8_LDB(B1, 1, 1); PG8_SCHED; PG8_LDA(At, 1, 0); PG8_STAGE(PG8_SA(0, 1), a2 + hstep, voffA);
;             PG8_WAIT_V(8); PG8_WAIT_L(0); PG8_BAR; PG8_MMA(0, 0, At, B0); PG8_MMA(0, 1, At, B1); PG8_BAR; PG8_SCHED;
	s_setprio 1
	s_waitcnt lgkmcnt(0)
	v_mfma_f32_16x16x32_bf16 v[158:161], v[98:101], v[162:165], v[158:161]
	v_mfma_f32_16x16x32_bf16 v[158:161], v[102:105], v[166:169], v[158:161]
	v_mfma_f32_16x16x32_bf16 v[126:129], v[98:101], v[170:173], v[126:129]
	v_mfma_f32_16x16x32_bf16 v[126:129], v[102:105], v[174:177], v[126:129]
	v_mfma_f32_16x16x32_bf16 v[94:97], v[98:101], v[178:181], v[94:97]
	v_mfma_f32_16x16x32_bf16 v[94:97], v[102:105], v[182:185], v[94:97]
	v_mfma_f32_16x16x32_bf16 v[78:81], v[98:101], v[186:189], v[78:81]
	v_mfma_f32_16x16x32_bf16 v[78:81], v[102:105], v[190:193], v[78:81]
	v_mfma_f32_16x16x32_bf16 v[74:77], v[114:117], v[186:189], v[74:77]
	v_mfma_f32_16x16x32_bf16 v[74:77], v[122:125], v[190:193], v[74:77]
	v_mfma_f32_16x16x32_bf16 v[90:93], v[114:117], v[178:181], v[90:93]
	v_mfma_f32_16x16x32_bf16 v[90:93], v[122:125], v[182:185], v[90:93]
	v_mfma_f32_16x16x32_bf16 v[118:121], v[114:117], v[170:173], v[118:121]
	v_mfma_f32_16x16x32_bf16 v[118:121], v[122:125], v[174:177], v[118:121]
	v_mfma_f32_16x16x32_bf16 v[150:153], v[114:117], v[162:165], v[150:153]
	v_mfma_f32_16x16x32_bf16 v[150:153], v[122:125], v[166:169], v[150:153]
	s_setprio 0
	s_setprio 1
	v_mfma_f32_16x16x32_bf16 v[142:145], v[130:133], v[162:165], v[142:145]
	v_mfma_f32_16x16x32_bf16 v[142:145], v[138:141], v[166:169], v[142:145]
	v_mfma_f32_16x16x32_bf16 v[110:113], v[130:133], v[170:173], v[110:113]
	v_mfma_f32_16x16x32_bf16 v[110:113], v[138:141], v[174:177], v[110:113]
	v_mfma_f32_16x16x32_bf16 v[86:89], v[130:133], v[178:181], v[86:89]
	v_mfma_f32_16x16x32_bf16 v[86:89], v[138:141], v[182:185], v[86:89]
	v_mfma_f32_16x16x32_bf16 v[70:73], v[130:133], v[186:189], v[70:73]
	v_mfma_f32_16x16x32_bf16 v[70:73], v[138:141], v[190:193], v[70:73]
	v_mfma_f32_16x16x32_bf16 v[66:69], v[146:149], v[186:189], v[66:69]
	v_mfma_f32_16x16x32_bf16 v[66:69], v[154:157], v[190:193], v[66:69]
	v_mfma_f32_16x16x32_bf16 v[82:85], v[146:149], v[178:181], v[82:85]
	v_mfma_f32_16x16x32_bf16 v[82:85], v[154:157], v[182:185], v[82:85]
	v_mfma_f32_16x16x32_bf16 v[106:109], v[146:149], v[170:173], v[106:109]
	v_mfma_f32_16x16x32_bf16 v[106:109], v[154:157], v[174:177], v[106:109]
	v_mfma_f32_16x16x32_bf16 v[134:137], v[146:149], v[162:165], v[134:137]
	v_mfma_f32_16x16x32_bf16 v[134:137], v[154:157], v[166:169], v[134:137]
	s_setprio 0
	s_barrier
	s_add_i32 vcc_hi, vcc_hi, s80
	v_lshl_add_u64 v[206:207], s[4:5], 0, v[0:1]
	s_mov_b32 m0, vcc_hi
	ds_read_b128 v[162:165], v249 offset:16384
	ds_read_b128 v[166:169], v249 offset:17408
	ds_read_b128 v[170:173], v249 offset:18432
	ds_read_b128 v[174:177], v249 offset:19456
	ds_read_b128 v[178:181], v249 offset:20480
	ds_read_b128 v[182:185], v249 offset:21504
	ds_read_b128 v[186:189], v249 offset:22528
	ds_read_b128 v[190:193], v249 offset:23552
	global_load_lds_dwordx4 v[206:207], off
	s_add_i32 m0, vcc_hi, 0x2000
	v_lshl_add_u64 v[212:213], s[4:5], 0, v[198:199]
	s_add_u32 s4, s4, s58
	s_addc_u32 s5, s5, 0
	s_add_i32 s84, s84, s80
	global_load_lds_dwordx4 v[212:213], off
	v_lshl_add_u64 v[214:215], s[4:5], 0, v[0:1]
	s_mov_b32 m0, s84
	v_lshl_add_u64 v[216:217], s[4:5], 0, v[198:199]
	global_load_lds_dwordx4 v[214:215], off
	s_add_i32 m0, s84, 0x2000
	v_lshl_add_u64 v[218:219], s[8:9], 0, v[194:195]
	global_load_lds_dwordx4 v[216:217], off
	s_mov_b32 m0, s81
	v_lshl_add_u64 v[220:221], s[8:9], 0, v[196:197]
	global_load_lds_dwordx4 v[218:219], off
	s_mov_b32 m0, s70
	s_nop 0
	global_load_lds_dwordx4 v[220:221], off
	s_waitcnt vmcnt(8)
	s_waitcnt lgkmcnt(0)
	s_barrier
	s_setprio 1
	s_waitcnt lgkmcnt(0)
	v_mfma_f32_16x16x32_bf16 v[62:65], v[98:101], v[162:165], v[62:65]
	v_mfma_f32_16x16x32_bf16 v[62:65], v[102:105], v[166:169], v[62:65]
	v_mfma_f32_16x16x32_bf16 v[46:49], v[98:101], v[170:173], v[46:49]
	v_mfma_f32_16x16x32_bf16 v[46:49], v[102:105], v[174:177], v[46:49]
	v_mfma_f32_16x16x32_bf16 v[30:33], v[98:101], v[178:181], v[30:33]
	v_mfma_f32_16x16x32_bf16 v[30:33], v[102:105], v[182:185], v[30:33]
	v_mfma_f32_16x16x32_bf16 v[14:17], v[98:101], v[186:189], v[14:17]
	v_mfma_f32_16x16x32_bf16 v[14:17], v[102:105], v[190:193], v[14:17]
	v_mfma_f32_16x16x32_bf16 v[10:13], v[114:117], v[186:189], v[10:13]
	v_mfma_f32_16x16x32_bf16 v[10:13], v[122:125], v[190:193], v[10:13]
	v_mfma_f32_16x16x32_bf16 v[26:29], v[114:117], v[178:181], v[26:29]
	v_mfma_f32_16x16x32_bf16 v[26:29], v[122:125], v[182:185], v[26:29]
	v_mfma_f32_16x16x32_bf16 v[42:45], v[114:117], v[170:173], v[42:45]
	v_mfma_f32_16x16x32_bf16 v[42:45], v[122:125], v[174:177], v[42:45]
	v_mfma_f32_16x16x32_bf16 v[58:61], v[114:117], v[162:165], v[58:61]
	v_mfma_f32_16x16x32_bf16 v[58:61], v[122:125], v[166:169], v[58:61]
	s_setprio 0
	s_setprio 1
	v_mfma_f32_16x16x32_bf16 v[54:57], v[130:133], v[162:165], v[54:57]
	v_mfma_f32_16x16x32_bf16 v[54:57], v[138:141], v[166:169], v[54:57]
	v_mfma_f32_16x16x32_bf16 v[38:41], v[130:133], v[170:173], v[38:41]
	v_mfma_f32_16x16x32_bf16 v[38:41], v[138:141], v[174:177], v[38:41]
	v_mfma_f32_16x16x32_bf16 v[22:25], v[130:133], v[178:181], v[22:25]
	v_mfma_f32_16x16x32_bf16 v[22:25], v[138:141], v[182:185], v[22:25]
	v_mfma_f32_16x16x32_bf16 v[6:9], v[130:133], v[186:189], v[6:9]
	v_mfma_f32_16x16x32_bf16 v[6:9], v[138:141], v[190:193], v[6:9]
	v_mfma_f32_16x16x32_bf16 v[2:5], v[146:149], v[186:189], v[2:5]
	v_mfma_f32_16x16x32_bf16 v[2:5], v[154:157], v[190:193], v[2:5]
	v_mfma_f32_16x16x32_bf16 v[18:21], v[146:149], v[178:181], v[18:21]
	v_mfma_f32_16x16x32_bf16 v[18:21], v[154:157], v[182:185], v[18:21]
	v_mfma_f32_16x16x32_bf16 v[34:37], v[146:149], v[170:173], v[34:37]
	v_mfma_f32_16x16x32_bf16 v[34:37], v[154:157], v[174:177], v[34:37]
	v_mfma_f32_16x16x32_bf16 v[50:53], v[146:149], v[162:165], v[50:53]
	v_mfma_f32_16x16x32_bf16 v[50:53], v[154:157], v[166:169], v[50:53]
	s_setprio 0
	s_barrier
; #define PG8_STAGE(bufoff, gbase, voff) do { _Pragma("unroll") for (int _i = 0; _i < 2; ++_i) \
;         __builtin_amdgcn_global_load_lds((const unsigned*)((const char*)(gbase) + (voff)[_i]), (PG8_LAS unsigned*)(lds + (bufoff) + ldsw + _i * 8192), 16, 0, 0); } while (0)
; #define PG8_LDA(dst, b, h) do { _Pragma("unroll") for (int m = 0; m < 4; ++m) _Pragma("unroll") for (int k = 0; k < 2; ++k) dst[m][k] = *(const PG8_LAS bf16x8*)(lds + PG8_SA(b, h) + aoff + m * 2048 + k * 1024); } while (0)
; #define PG8_LDB(dst, b, h) do { _Pragma("unroll") for (int n = 0; n < 2; ++n) _Pragma("unroll") for (int k = 0; k < 2; ++k) dst[n][k] = *(const PG8_LAS bf16x8*)(lds + PG8_SB(b, h) + boff + n * 2048 + k * 1024); } while (0)
; #define PG8_MMA(ai, bj, At, Bt) do { __builtin_amdgcn_s_setprio(1); _Pragma("unroll") for (int m = 0; m < 4; ++m) _Pragma("unroll") for (int n = 0; n < 2; ++n) _Pragma("unroll") for (int k = 0; k < 2; ++k) \
;         acc[ai][bj][m][n] = mma16<Epi::I8>(Bt[n][k], At[m][k], acc[ai][bj][m][n]); __builtin_amdgcn_s_setprio(0); } while (0)
; #define PG8_WAIT_V(n) asm volatile("s_waitcnt vmcnt(" #n ")" ::: "memory")
; #define PG8_WAIT_L(n) asm volatile("s_waitcnt lgkmcnt(" #n ")" ::: "memory")
; #define PG8_BAR __builtin_amdgcn_s_barrier()
; #define PG8_SCHED __builtin_amdgcn_sched_barrier(0)
; template <class Epi, class Sched, bool ALIGN_EPI = false, bool SP2 = false>
; __device__ __forceinline__ void gemm_phase(PG8_LAS unsigned char* lds, const Gemm g, const Sched& S, const Epi& E) {
;     ...
;             PG8_LDB(B0, 1, 0); PG8_LDB(B1, 1, 1); PG8_SCHED; PG8_LDA(At, 1, 0); PG8_STAGE(PG8_SA(0, 1), a2 + hstep, voffA);
;             PG8_WAIT_V(8); PG8_WAIT_L(0); PG8_BAR; PG8_MMA(0, 0, At, B0); PG8_MMA(0, 1, At, B1); PG8_BAR; PG8_SCHED;
	s_add_i32 s84, 0, 0x18000
	s_add_i32 vcc_hi, 0, 0x1c000
	v_add_u32_e32 v122, s84, v248
	v_add_u32_e32 v154, vcc_hi, v248
	ds_read_b128 v[98:101], v122
	ds_read_b128 v[102:105], v122 offset:1024
	ds_read_b128 v[114:117], v122 offset:2048
	ds_read_b128 v[122:125], v122 offset:3072
	ds_read_b128 v[130:133], v154
	ds_read_b128 v[138:141], v154 offset:1024
	ds_read_b128 v[146:149], v154 offset:2048
	ds_read_b128 v[154:157], v154 offset:3072
	s_add_u32 s4, s8, s58
	s_addc_u32 s5, s9, 0
	s_mov_b32 m0, s71
	v_lshl_add_u64 v[222:223], s[4:5], 0, v[194:195]
	ds_read_b128 v[162:165], v249 offset:32768
	ds_read_b128 v[166:169], v249 offset:33792
	ds_read_b128 v[170:173], v249 offset:34816
	ds_read_b128 v[174:177], v249 offset:35840
	ds_read_b128 v[178:181], v249 offset:36864
	ds_read_b128 v[182:185], v249 offset:37888
	ds_read_b128 v[186:189], v249 offset:38912
	ds_read_b128 v[190:193], v249 offset:39936
	global_load_lds_dwordx4 v[222:223], off
	v_lshl_add_u64 v[222:223], s[4:5], 0, v[196:197]
	s_mov_b32 m0, s12
	s_nop 0
	global_load_lds_dwordx4 v[222:223], off
	s_waitcnt vmcnt(8)
	s_waitcnt lgkmcnt(0)
	s_barrier
	s_setprio 1
	s_waitcnt lgkmcnt(0)
	v_mfma_f32_16x16x32_bf16 v[158:161], v[98:101], v[162:165], v[158:161]
	v_mfma_f32_16x16x32_bf16 v[158:161], v[102:105], v[166:169], v[158:161]
	v_mfma_f32_16x16x32_bf16 v[126:129], v[98:101], v[170:173], v[126:129]
	v_mfma_f32_16x16x32_bf16 v[126:129], v[102:105], v[174:177], v[126:129]
	v_mfma_f32_16x16x32_bf16 v[94:97], v[98:101], v[178:181], v[94:97]
	v_mfma_f32_16x16x32_bf16 v[94:97], v[102:105], v[182:185], v[94:97]
	v_mfma_f32_16x16x32_bf16 v[78:81], v[98:101], v[186:189], v[78:81]
	v_mfma_f32_16x16x32_bf16 v[78:81], v[102:105], v[190:193], v[78:81]
	v_mfma_f32_16x16x32_bf16 v[74:77], v[114:117], v[186:189], v[74:77]
	v_mfma_f32_16x16x32_bf16 v[74:77], v[122:125], v[190:193], v[74:77]
	v_mfma_f32_16x16x32_bf16 v[90:93], v[114:117], v[178:181], v[90:93]
	v_mfma_f32_16x16x32_bf16 v[90:93], v[122:125], v[182:185], v[90:93]
	v_mfma_f32_16x16x32_bf16 v[118:121], v[114:117], v[170:173], v[118:121]
	v_mfma_f32_16x16x32_bf16 v[118:121], v[122:125], v[174:177], v[118:121]
	v_mfma_f32_16x16x32_bf16 v[150:153], v[114:117], v[162:165], v[150:153]
	v_mfma_f32_16x16x32_bf16 v[150:153], v[122:125], v[166:169], v[150:153]
	s_setprio 0
	s_setprio 1
	v_mfma_f32_16x16x32_bf16 v[142:145], v[130:133], v[162:165], v[142:145]
	v_mfma_f32_16x16x32_bf16 v[142:145], v[138:141], v[166:169], v[142:145]
	v_mfma_f32_16x16x32_bf16 v[110:113], v[130:133], v[170:173], v[110:113]
	v_mfma_f32_16x16x32_bf16 v[110:113], v[138:141], v[174:177], v[110:113]
	v_mfma_f32_16x16x32_bf16 v[86:89], v[130:133], v[178:181], v[86:89]
	v_mfma_f32_16x16x32_bf16 v[86:89], v[138:141], v[182:185], v[86:89]
	v_mfma_f32_16x16x32_bf16 v[70:73], v[130:133], v[186:189], v[70:73]
	v_mfma_f32_16x16x32_bf16 v[70:73], v[138:141], v[190:193], v[70:73]
	v_mfma_f32_16x16x32_bf16 v[66:69], v[146:149], v[186:189], v[66:69]
	v_mfma_f32_16x16x32_bf16 v[66:69], v[154:157], v[190:193], v[66:69]
	v_mfma_f32_16x16x32_bf16 v[82:85], v[146:149], v[178:181], v[82:85]
	v_mfma_f32_16x16x32_bf16 v[82:85], v[154:157], v[182:185], v[82:85]
	v_mfma_f32_16x16x32_bf16 v[106:109], v[146:149], v[170:173], v[106:109]
	v_mfma_f32_16x16x32_bf16 v[106:109], v[154:157], v[174:177], v[106:109]
	v_mfma_f32_16x16x32_bf16 v[134:137], v[146:149], v[162:165], v[134:137]
	v_mfma_f32_16x16x32_bf16 v[134:137], v[154:157], v[166:169], v[134:137]
	s_setprio 0
	s_barrier
; #define PG8_STAGE(bufoff, gbase, voff) do { _Pragma("unroll") for (int _i = 0; _i < 2; ++_i) \
;         __builtin_amdgcn_global_load_lds((const unsigned*)((const char*)(gbase) + (voff)[_i]), (PG8_LAS unsigned*)(lds + (bufoff) + ldsw + _i * 8192), 16, 0, 0); } while (0)
; #define PG8_LDA(dst, b, h) do { _Pragma("unroll") for (int m = 0; m < 4; ++m) _Pragma("unroll") for (int k = 0; k < 2; ++k) dst[m][k] = *(const PG8_LAS bf16x8*)(lds + PG8_SA(b, h) + aoff + m * 2048 + k * 1024); } while (0)
; #define PG8_MMA(ai, bj, At, Bt) do { __builtin_amdgcn_s_setprio(1); _Pragma("unroll") for (int m = 0; m < 4; ++m) _Pragma("unroll") for (int n = 0; n < 2; ++n) _Pragma("unroll") for (int k = 0; k < 2; ++k) \
;         acc[ai][bj][m][n] = mma16<Epi::I8>(Bt[n][k], At[m][k], acc[ai][bj][m][n]); __builtin_amdgcn_s_setprio(0); } while (0)
; #define PG8_WAIT_V(n) asm volatile("s_waitcnt vmcnt(" #n ")" ::: "memory")
; #define PG8_WAIT_L(n) asm volatile("s_waitcnt lgkmcnt(" #n ")" ::: "memory")
; #define PG8_BAR __builtin_amdgcn_s_barrier()
; #define PG8_SCHED __builtin_amdgcn_sched_barrier(0)
; template <class Epi, class Sched, bool ALIGN_EPI = false, bool SP2 = false>
; __device__ __forceinline__ void gemm_phase(PG8_LAS unsigned char* lds, const Gemm g, const Sched& S, const Epi& E) {
;     ...
;             PG8_LDA(At, 1, 1); PG8_STAGE(PG8_SB(1, 0), b3, voffB); PG8_STAGE(PG8_SB(1, 1), b3 + hstep, voffB); PG8_STAGE(PG8_SA(1, 0), a3, voffA);
;             PG8_WAIT_V(8); PG8_WAIT_L(0); PG8_BAR; PG8_MMA(1, 0, At, B0); PG8_MMA(1, 1, At, B1); PG8_BAR; PG8_SCHED;
	s_add_i32 s4, s84, s80
	v_lshl_add_u64 v[206:207], v[206:207], 0, s[92:93]
	s_mov_b32 m0, s4
	ds_read_b128 v[162:165], v249 offset:49152
	ds_read_b128 v[166:169], v249 offset:50176
	ds_read_b128 v[170:173], v249 offset:51200
	ds_read_b128 v[174:177], v249 offset:52224
	ds_read_b128 v[178:181], v249 offset:53248
	ds_read_b128 v[182:185], v249 offset:54272
	ds_read_b128 v[186:189], v249 offset:55296
	ds_read_b128 v[190:193], v249 offset:56320
	global_load_lds_dwordx4 v[206:207], off
	v_lshl_add_u64 v[206:207], v[212:213], 0, s[92:93]
	s_add_i32 m0, s4, 0x2000
	s_add_i32 s4, vcc_hi, s80
	global_load_lds_dwordx4 v[206:207], off
	v_lshl_add_u64 v[206:207], v[214:215], 0, s[92:93]
	s_mov_b32 m0, s4
	s_nop 0
	global_load_lds_dwordx4 v[206:207], off
	v_lshl_add_u64 v[206:207], v[216:217], 0, s[92:93]
	s_add_i32 m0, s4, 0x2000
	s_nop 0
	global_load_lds_dwordx4 v[206:207], off
	v_lshl_add_u64 v[206:207], v[218:219], 0, s[92:93]
	s_mov_b32 m0, s10
	s_nop 0
	global_load_lds_dwordx4 v[206:207], off
	v_lshl_add_u64 v[206:207], v[220:221], 0, s[92:93]
	s_mov_b32 m0, s11
	s_nop 0
	global_load_lds_dwordx4 v[206:207], off
	s_waitcnt vmcnt(8)
	s_waitcnt lgkmcnt(0)
	s_barrier
	s_setprio 1
	s_waitcnt lgkmcnt(0)
	v_mfma_f32_16x16x32_bf16 v[62:65], v[98:101], v[162:165], v[62:65]
	v_mfma_f32_16x16x32_bf16 v[62:65], v[102:105], v[166:169], v[62:65]
	v_mfma_f32_16x16x32_bf16 v[46:49], v[98:101], v[170:173], v[46:49]
	v_mfma_f32_16x16x32_bf16 v[46:49], v[102:105], v[174:177], v[46:49]
	v_mfma_f32_16x16x32_bf16 v[30:33], v[98:101], v[178:181], v[30:33]
	v_mfma_f32_16x16x32_bf16 v[30:33], v[102:105], v[182:185], v[30:33]
	v_mfma_f32_16x16x32_bf16 v[14:17], v[98:101], v[186:189], v[14:17]
	v_mfma_f32_16x16x32_bf16 v[14:17], v[102:105], v[190:193], v[14:17]
	v_mfma_f32_16x16x32_bf16 v[10:13], v[114:117], v[186:189], v[10:13]
	v_mfma_f32_16x16x32_bf16 v[10:13], v[122:125], v[190:193], v[10:13]
	v_mfma_f32_16x16x32_bf16 v[26:29], v[114:117], v[178:181], v[26:29]
	v_mfma_f32_16x16x32_bf16 v[26:29], v[122:125], v[182:185], v[26:29]
	v_mfma_f32_16x16x32_bf16 v[42:45], v[114:117], v[170:173], v[42:45]
	v_mfma_f32_16x16x32_bf16 v[42:45], v[122:125], v[174:177], v[42:45]
	v_mfma_f32_16x16x32_bf16 v[58:61], v[114:117], v[162:165], v[58:61]
	v_mfma_f32_16x16x32_bf16 v[58:61], v[122:125], v[166:169], v[58:61]
	s_setprio 0
	s_setprio 1
	v_mfma_f32_16x16x32_bf16 v[54:57], v[130:133], v[162:165], v[54:57]
	v_mfma_f32_16x16x32_bf16 v[54:57], v[138:141], v[166:169], v[54:57]
	v_mfma_f32_16x16x32_bf16 v[38:41], v[130:133], v[170:173], v[38:41]
	v_mfma_f32_16x16x32_bf16 v[38:41], v[138:141], v[174:177], v[38:41]
	v_mfma_f32_16x16x32_bf16 v[22:25], v[130:133], v[178:181], v[22:25]
	v_mfma_f32_16x16x32_bf16 v[22:25], v[138:141], v[182:185], v[22:25]
	v_mfma_f32_16x16x32_bf16 v[6:9], v[130:133], v[186:189], v[6:9]
	v_mfma_f32_16x16x32_bf16 v[6:9], v[138:141], v[190:193], v[6:9]
	v_mfma_f32_16x16x32_bf16 v[2:5], v[146:149], v[186:189], v[2:5]
	v_mfma_f32_16x16x32_bf16 v[2:5], v[154:157], v[190:193], v[2:5]
	v_mfma_f32_16x16x32_bf16 v[18:21], v[146:149], v[178:181], v[18:21]
	v_mfma_f32_16x16x32_bf16 v[18:21], v[154:157], v[182:185], v[18:21]
	v_mfma_f32_16x16x32_bf16 v[34:37], v[146:149], v[170:173], v[34:37]
	v_mfma_f32_16x16x32_bf16 v[34:37], v[154:157], v[174:177], v[34:37]
	v_mfma_f32_16x16x32_bf16 v[50:53], v[146:149], v[162:165], v[50:53]
	v_mfma_f32_16x16x32_bf16 v[50:53], v[154:157], v[166:169], v[50:53]
	s_setprio 0
	s_barrier
	s_add_u32 s6, s6, 0x100
	s_addc_u32 s7, s7, 0
	s_add_u32 s67, s67, 0x100
	s_addc_u32 s85, s85, 0
	s_cmp_ge_u32 vcc_lo, s69
	s_mov_b32 s8, vcc_lo
	s_cbranch_scc0 .LBB0_175

; #define PG8_STAGE(bufoff, gbase, voff) do { _Pragma("unroll") for (int _i = 0; _i < 2; ++_i) \
;         __builtin_amdgcn_global_load_lds((const unsigned*)((const char*)(gbase) + (voff)[_i]), (PG8_LAS unsigned*)(lds + (bufoff) + ldsw + _i * 8192), 16, 0, 0); } while (0)
; #define PG8_LDA(dst, b, h) do { _Pragma("unroll") for (int m = 0; m < 4; ++m) _Pragma("unroll") for (int k = 0; k < 2; ++k) dst[m][k] = *(const PG8_LAS bf16x8*)(lds + PG8_SA(b, h) + aoff + m * 2048 + k * 1024); } while (0)
; #define PG8_LDB(dst, b, h) do { _Pragma("unroll") for (int n = 0; n < 2; ++n) _Pragma("unroll") for (int k = 0; k < 2; ++k) dst[n][k] = *(const PG8_LAS bf16x8*)(lds + PG8_SB(b, h) + boff + n * 2048 + k * 1024); } while (0)
; #define PG8_MMA(ai, bj, At, Bt) do { __builtin_amdgcn_s_setprio(1); _Pragma("unroll") for (int m = 0; m < 4; ++m) _Pragma("unroll") for (int n = 0; n < 2; ++n) _Pragma("unroll") for (int k = 0; k < 2; ++k) \
;         acc[ai][bj][m][n] = mma16<Epi::I8>(Bt[n][k], At[m][k], acc[ai][bj][m][n]); __builtin_amdgcn_s_setprio(0); } while (0)
; #define PG8_WAIT_V(n) asm volatile("s_waitcnt vmcnt(" #n ")" ::: "memory")
; #define PG8_WAIT_L(n) asm volatile("s_waitcnt lgkmcnt(" #n ")" ::: "memory")
; #define PG8_BAR __builtin_amdgcn_s_barrier()
; #define PG8_SCHED __builtin_amdgcn_sched_barrier(0)
; template <class Epi, class Sched, bool ALIGN_EPI = false, bool SP2 = false>
; __device__ __forceinline__ void gemm_phase(PG8_LAS unsigned char* lds, const Gemm g, const Sched& S, const Epi& E) {
;     ...
;             PG8_LDB(B0, 0, 0); PG8_LDB(B1, 0, 1); PG8_SCHED; PG8_LDA(At, 0, 0); PG8_STAGE(PG8_SA(1, 1), a1 + hstep, voffA);
;             PG8_WAIT_V(8); PG8_WAIT_L(0); PG8_BAR; PG8_MMA(0, 0, At, B0); PG8_MMA(0, 1, At, B1); PG8_BAR; PG8_SCHED;
;             PG8_LDA(At, 0, 1); PG8_STAGE(PG8_SB(0, 0), b2, voffB); PG8_STAGE(PG8_SB(0, 1), b2 + hstep, voffB); PG8_STAGE(PG8_SA(0, 0), a2, voffA);
;             PG8_WAIT_V(8); PG8_WAIT_L(0); PG8_BAR; PG8_MMA(1, 0, At, B0); PG8_MMA(1, 1, At, B1); PG8_BAR; PG8_SCHED;
.Lpeel291:
	s_add_u32 s84, s8, 0x100
	s_addc_u32 s85, s9, 0
	s_add_i32 s66, 0, 0x10000
	s_cmp_eq_u32 s10, 12
	s_cselect_b32 vcc_hi, s5, s85
	s_cselect_b32 vcc_lo, s7, s84
	s_cselect_b32 s97, s11, s68
	s_cselect_b32 s96, s67, s69
	s_add_i32 s70, 0, 0x14000
	v_add_u32_e32 v110, s66, v175
	v_add_u32_e32 v168, s70, v175
	s_waitcnt vmcnt(0)
	ds_read_b128 v[66:69], v110
	ds_read_b128 v[70:73], v110 offset:1024
	ds_read_b128 v[106:109], v110 offset:2048
	ds_read_b128 v[110:113], v110 offset:3072
	ds_read_b128 v[114:117], v168
	ds_read_b128 v[118:121], v168 offset:1024
	ds_read_b128 v[126:129], v168 offset:2048
	ds_read_b128 v[178:181], v168 offset:3072
	v_lshl_add_u64 v[168:169], s[8:9], 0, v[164:165]
	s_add_i32 m0, s1, 0xc000
	ds_read_b128 v[182:185], v177
	ds_read_b128 v[186:189], v177 offset:1024
	ds_read_b128 v[190:193], v177 offset:2048
	ds_read_b128 v[194:197], v177 offset:3072
	ds_read_b128 v[198:201], v177 offset:4096
	ds_read_b128 v[210:213], v177 offset:5120
	ds_read_b128 v[214:217], v177 offset:6144
	ds_read_b128 v[218:221], v177 offset:7168
	global_load_lds_dwordx4 v[168:169], off
	v_lshl_add_u64 v[168:169], s[8:9], 0, v[166:167]
	s_add_i32 m0, s1, 0xe000
	s_nop 0
	global_load_lds_dwordx4 v[168:169], off
	s_waitcnt vmcnt(8)
	s_waitcnt lgkmcnt(0)
	s_barrier
	s_setprio 1
	s_waitcnt lgkmcnt(0)
	v_mfma_i32_16x16x64_i8 v[154:157], v[66:69], v[182:185], 0
	v_mfma_i32_16x16x64_i8 v[154:157], v[70:73], v[186:189], v[154:157]
	v_mfma_i32_16x16x64_i8 v[150:153], v[66:69], v[190:193], 0
	v_mfma_i32_16x16x64_i8 v[150:153], v[70:73], v[194:197], v[150:153]
	v_mfma_i32_16x16x64_i8 v[142:145], v[66:69], v[198:201], 0
	v_mfma_i32_16x16x64_i8 v[142:145], v[70:73], v[210:213], v[142:145]
	v_mfma_i32_16x16x64_i8 v[134:137], v[66:69], v[214:217], 0
	v_mfma_i32_16x16x64_i8 v[134:137], v[70:73], v[218:221], v[134:137]
	v_mfma_i32_16x16x64_i8 v[122:125], v[106:109], v[214:217], 0
	v_mfma_i32_16x16x64_i8 v[122:125], v[110:113], v[218:221], v[122:125]
	v_mfma_i32_16x16x64_i8 v[130:133], v[106:109], v[198:201], 0
	v_mfma_i32_16x16x64_i8 v[130:133], v[110:113], v[210:213], v[130:133]
	v_mfma_i32_16x16x64_i8 v[138:141], v[106:109], v[190:193], 0
	v_mfma_i32_16x16x64_i8 v[138:141], v[110:113], v[194:197], v[138:141]
	v_mfma_i32_16x16x64_i8 v[146:149], v[106:109], v[182:185], 0
	v_mfma_i32_16x16x64_i8 v[146:149], v[110:113], v[186:189], v[146:149]
	s_setprio 0
	s_setprio 1
	v_mfma_i32_16x16x64_i8 v[102:105], v[114:117], v[182:185], 0
	v_mfma_i32_16x16x64_i8 v[102:105], v[118:121], v[186:189], v[102:105]
	v_mfma_i32_16x16x64_i8 v[98:101], v[114:117], v[190:193], 0
	v_mfma_i32_16x16x64_i8 v[98:101], v[118:121], v[194:197], v[98:101]
	v_mfma_i32_16x16x64_i8 v[90:93], v[114:117], v[198:201], 0
	v_mfma_i32_16x16x64_i8 v[90:93], v[118:121], v[210:213], v[90:93]
	v_mfma_i32_16x16x64_i8 v[82:85], v[114:117], v[214:217], 0
	v_mfma_i32_16x16x64_i8 v[82:85], v[118:121], v[218:221], v[82:85]
	v_mfma_i32_16x16x64_i8 v[74:77], v[126:129], v[214:217], 0
	v_mfma_i32_16x16x64_i8 v[74:77], v[178:181], v[218:221], v[74:77]
	v_mfma_i32_16x16x64_i8 v[78:81], v[126:129], v[198:201], 0
	v_mfma_i32_16x16x64_i8 v[78:81], v[178:181], v[210:213], v[78:81]
	v_mfma_i32_16x16x64_i8 v[86:89], v[126:129], v[190:193], 0
	v_mfma_i32_16x16x64_i8 v[86:89], v[178:181], v[194:197], v[86:89]
	v_mfma_i32_16x16x64_i8 v[94:97], v[126:129], v[182:185], 0
	v_mfma_i32_16x16x64_i8 v[94:97], v[178:181], v[186:189], v[94:97]
	s_setprio 0
	s_barrier
	s_add_i32 s8, s66, s81
	v_lshl_add_u64 v[168:169], s[96:97], 0, v[0:1]
	s_mov_b32 m0, s8
	ds_read_b128 v[182:185], v177 offset:16384
	ds_read_b128 v[186:189], v177 offset:17408
	ds_read_b128 v[190:193], v177 offset:18432
	ds_read_b128 v[194:197], v177 offset:19456
	ds_read_b128 v[198:201], v177 offset:20480
	ds_read_b128 v[210:213], v177 offset:21504
	ds_read_b128 v[214:217], v177 offset:22528
	ds_read_b128 v[218:221], v177 offset:23552
	global_load_lds_dwordx4 v[168:169], off
	s_add_i32 m0, s8, 0x2000
	s_add_u32 s8, s96, 0x40000
	v_lshl_add_u64 v[206:207], s[96:97], 0, v[158:159]
	s_addc_u32 s9, s97, 0
	s_add_i32 s66, s70, s81
	global_load_lds_dwordx4 v[206:207], off
	v_lshl_add_u64 v[222:223], s[8:9], 0, v[0:1]
	s_mov_b32 m0, s66
	v_lshl_add_u64 v[224:225], vcc, 0, v[160:161]
	global_load_lds_dwordx4 v[222:223], off
	v_lshl_add_u64 v[222:223], s[8:9], 0, v[158:159]
	s_add_i32 m0, s66, 0x2000
	s_nop 0
	global_load_lds_dwordx4 v[222:223], off
	v_lshl_add_u64 v[222:223], vcc, 0, v[162:163]
	s_mov_b32 m0, s1
	s_nop 0
	global_load_lds_dwordx4 v[222:223], off
	s_mov_b32 m0, s58
	s_nop 0
	global_load_lds_dwordx4 v[224:225], off
	s_waitcnt vmcnt(8)
	s_waitcnt lgkmcnt(0)
	s_barrier
; #define PG8_STAGE(bufoff, gbase, voff) do { _Pragma("unroll") for (int _i = 0; _i < 2; ++_i) \
;         __builtin_amdgcn_global_load_lds((const unsigned*)((const char*)(gbase) + (voff)[_i]), (PG8_LAS unsigned*)(lds + (bufoff) + ldsw + _i * 8192), 16, 0, 0); } while (0)
; #define PG8_LDA(dst, b, h) do { _Pragma("unroll") for (int m = 0; m < 4; ++m) _Pragma("unroll") for (int k = 0; k < 2; ++k) dst[m][k] = *(const PG8_LAS bf16x8*)(lds + PG8_SA(b, h) + aoff + m * 2048 + k * 1024); } while (0)
; #define PG8_LDB(dst, b, h) do { _Pragma("unroll") for (int n = 0; n < 2; ++n) _Pragma("unroll") for (int k = 0; k < 2; ++k) dst[n][k] = *(const PG8_LAS bf16x8*)(lds + PG8_SB(b, h) + boff + n * 2048 + k * 1024); } while (0)
; #define PG8_MMA(ai, bj, At, Bt) do { __builtin_amdgcn_s_setprio(1); _Pragma("unroll") for (int m = 0; m < 4; ++m) _Pragma("unroll") for (int n = 0; n < 2; ++n) _Pragma("unroll") for (int k = 0; k < 2; ++k) \
;         acc[ai][bj][m][n] = mma16<Epi::I8>(Bt[n][k], At[m][k], acc[ai][bj][m][n]); __builtin_amdgcn_s_setprio(0); } while (0)
; #define PG8_WAIT_V(n) asm volatile("s_waitcnt vmcnt(" #n ")" ::: "memory")
; #define PG8_WAIT_L(n) asm volatile("s_waitcnt lgkmcnt(" #n ")" ::: "memory")
; #define PG8_BAR __builtin_amdgcn_s_barrier()
; #define PG8_SCHED __builtin_amdgcn_sched_barrier(0)
; template <class Epi, class Sched, bool ALIGN_EPI = false, bool SP2 = false>
; __device__ __forceinline__ void gemm_phase(PG8_LAS unsigned char* lds, const Gemm g, const Sched& S, const Epi& E) {
;     ...
;             PG8_LDA(At, 0, 1); PG8_STAGE(PG8_SB(0, 0), b2, voffB); PG8_STAGE(PG8_SB(0, 1), b2 + hstep, voffB); PG8_STAGE(PG8_SA(0, 0), a2, voffA);
;             PG8_WAIT_V(8); PG8_WAIT_L(0); PG8_BAR; PG8_MMA(1, 0, At, B0); PG8_MMA(1, 1, At, B1); PG8_BAR; PG8_SCHED;
;             PG8_LDB(B0, 1, 0); PG8_LDB(B1, 1, 1); PG8_SCHED; PG8_LDA(At, 1, 0); PG8_STAGE(PG8_SA(0, 1), a2 + hstep, voffA);
;             PG8_WAIT_V(8); PG8_WAIT_L(0); PG8_BAR; PG8_MMA(0, 0, At, B0); PG8_MMA(0, 1, At, B1); PG8_BAR; PG8_SCHED;
	s_setprio 1
	s_waitcnt lgkmcnt(0)
	v_mfma_i32_16x16x64_i8 v[62:65], v[66:69], v[182:185], 0
	v_mfma_i32_16x16x64_i8 v[62:65], v[70:73], v[186:189], v[62:65]
	v_mfma_i32_16x16x64_i8 v[58:61], v[66:69], v[190:193], 0
	v_mfma_i32_16x16x64_i8 v[58:61], v[70:73], v[194:197], v[58:61]
	v_mfma_i32_16x16x64_i8 v[50:53], v[66:69], v[198:201], 0
	v_mfma_i32_16x16x64_i8 v[50:53], v[70:73], v[210:213], v[50:53]
	v_mfma_i32_16x16x64_i8 v[42:45], v[66:69], v[214:217], 0
	v_mfma_i32_16x16x64_i8 v[42:45], v[70:73], v[218:221], v[42:45]
	v_mfma_i32_16x16x64_i8 v[34:37], v[106:109], v[214:217], 0
	v_mfma_i32_16x16x64_i8 v[34:37], v[110:113], v[218:221], v[34:37]
	v_mfma_i32_16x16x64_i8 v[38:41], v[106:109], v[198:201], 0
	v_mfma_i32_16x16x64_i8 v[38:41], v[110:113], v[210:213], v[38:41]
	v_mfma_i32_16x16x64_i8 v[46:49], v[106:109], v[190:193], 0
	v_mfma_i32_16x16x64_i8 v[46:49], v[110:113], v[194:197], v[46:49]
	v_mfma_i32_16x16x64_i8 v[54:57], v[106:109], v[182:185], 0
	v_mfma_i32_16x16x64_i8 v[54:57], v[110:113], v[186:189], v[54:57]
	s_setprio 0
	s_setprio 1
	v_mfma_i32_16x16x64_i8 v[30:33], v[114:117], v[182:185], 0
	v_mfma_i32_16x16x64_i8 v[30:33], v[118:121], v[186:189], v[30:33]
	v_mfma_i32_16x16x64_i8 v[26:29], v[114:117], v[190:193], 0
	v_mfma_i32_16x16x64_i8 v[26:29], v[118:121], v[194:197], v[26:29]
	v_mfma_i32_16x16x64_i8 v[18:21], v[114:117], v[198:201], 0
	v_mfma_i32_16x16x64_i8 v[18:21], v[118:121], v[210:213], v[18:21]
	v_mfma_i32_16x16x64_i8 v[10:13], v[114:117], v[214:217], 0
	v_mfma_i32_16x16x64_i8 v[10:13], v[118:121], v[218:221], v[10:13]
	v_mfma_i32_16x16x64_i8 v[2:5], v[126:129], v[214:217], 0
	v_mfma_i32_16x16x64_i8 v[2:5], v[178:181], v[218:221], v[2:5]
	v_mfma_i32_16x16x64_i8 v[6:9], v[126:129], v[198:201], 0
	v_mfma_i32_16x16x64_i8 v[6:9], v[178:181], v[210:213], v[6:9]
	v_mfma_i32_16x16x64_i8 v[14:17], v[126:129], v[190:193], 0
	v_mfma_i32_16x16x64_i8 v[14:17], v[178:181], v[194:197], v[14:17]
	v_mfma_i32_16x16x64_i8 v[22:25], v[126:129], v[182:185], 0
	v_mfma_i32_16x16x64_i8 v[22:25], v[178:181], v[186:189], v[22:25]
	s_setprio 0
	s_barrier
	s_add_i32 s66, 0, 0x18000
	s_add_i32 s70, 0, 0x1c000
	v_add_u32_e32 v110, s66, v175
	v_add_u32_e32 v170, s70, v175
	ds_read_b128 v[66:69], v110
	ds_read_b128 v[70:73], v110 offset:1024
	ds_read_b128 v[106:109], v110 offset:2048
	ds_read_b128 v[110:113], v110 offset:3072
	ds_read_b128 v[114:117], v170
	ds_read_b128 v[118:121], v170 offset:1024
	ds_read_b128 v[126:129], v170 offset:2048
	ds_read_b128 v[178:181], v170 offset:3072
	s_add_u32 s8, vcc_lo, 0x40000
	s_addc_u32 s9, vcc_hi, 0
	s_mov_b32 m0, s80
	v_lshl_add_u64 v[226:227], s[8:9], 0, v[162:163]
	ds_read_b128 v[182:185], v177 offset:32768
	ds_read_b128 v[186:189], v177 offset:33792
	ds_read_b128 v[190:193], v177 offset:34816
	ds_read_b128 v[194:197], v177 offset:35840
	ds_read_b128 v[198:201], v177 offset:36864
	ds_read_b128 v[210:213], v177 offset:37888
	ds_read_b128 v[214:217], v177 offset:38912
	ds_read_b128 v[218:221], v177 offset:39936
	global_load_lds_dwordx4 v[226:227], off
	v_lshl_add_u64 v[226:227], s[8:9], 0, v[160:161]
	s_mov_b32 m0, s0
	s_nop 0
	global_load_lds_dwordx4 v[226:227], off
	s_waitcnt vmcnt(8)
	s_waitcnt lgkmcnt(0)
	s_barrier
	s_setprio 1
	s_waitcnt lgkmcnt(0)
	v_mfma_i32_16x16x64_i8 v[154:157], v[66:69], v[182:185], v[154:157]
	v_mfma_i32_16x16x64_i8 v[154:157], v[70:73], v[186:189], v[154:157]
	v_mfma_i32_16x16x64_i8 v[150:153], v[66:69], v[190:193], v[150:153]
	v_mfma_i32_16x16x64_i8 v[150:153], v[70:73], v[194:197], v[150:153]
	v_mfma_i32_16x16x64_i8 v[142:145], v[66:69], v[198:201], v[142:145]
	v_mfma_i32_16x16x64_i8 v[142:145], v[70:73], v[210:213], v[142:145]
	v_mfma_i32_16x16x64_i8 v[134:137], v[66:69], v[214:217], v[134:137]
	v_mfma_i32_16x16x64_i8 v[134:137], v[70:73], v[218:221], v[134:137]
	v_mfma_i32_16x16x64_i8 v[122:125], v[106:109], v[214:217], v[122:125]
	v_mfma_i32_16x16x64_i8 v[122:125], v[110:113], v[218:221], v[122:125]
	v_mfma_i32_16x16x64_i8 v[130:133], v[106:109], v[198:201], v[130:133]
	v_mfma_i32_16x16x64_i8 v[130:133], v[110:113], v[210:213], v[130:133]
	v_mfma_i32_16x16x64_i8 v[138:141], v[106:109], v[190:193], v[138:141]
	v_mfma_i32_16x16x64_i8 v[138:141], v[110:113], v[194:197], v[138:141]
	v_mfma_i32_16x16x64_i8 v[146:149], v[106:109], v[182:185], v[146:149]
	v_mfma_i32_16x16x64_i8 v[146:149], v[110:113], v[186:189], v[146:149]
	s_setprio 0
	s_setprio 1
	v_mfma_i32_16x16x64_i8 v[102:105], v[114:117], v[182:185], v[102:105]
	v_mfma_i32_16x16x64_i8 v[102:105], v[118:121], v[186:189], v[102:105]
	v_mfma_i32_16x16x64_i8 v[98:101], v[114:117], v[190:193], v[98:101]
	v_mfma_i32_16x16x64_i8 v[98:101], v[118:121], v[194:197], v[98:101]
	v_mfma_i32_16x16x64_i8 v[90:93], v[114:117], v[198:201], v[90:93]
	v_mfma_i32_16x16x64_i8 v[90:93], v[118:121], v[210:213], v[90:93]
	v_mfma_i32_16x16x64_i8 v[82:85], v[114:117], v[214:217], v[82:85]
	v_mfma_i32_16x16x64_i8 v[82:85], v[118:121], v[218:221], v[82:85]
	v_mfma_i32_16x16x64_i8 v[74:77], v[126:129], v[214:217], v[74:77]
	v_mfma_i32_16x16x64_i8 v[74:77], v[178:181], v[218:221], v[74:77]
	v_mfma_i32_16x16x64_i8 v[78:81], v[126:129], v[198:201], v[78:81]
	v_mfma_i32_16x16x64_i8 v[78:81], v[178:181], v[210:213], v[78:81]
	v_mfma_i32_16x16x64_i8 v[86:89], v[126:129], v[190:193], v[86:89]
	v_mfma_i32_16x16x64_i8 v[86:89], v[178:181], v[194:197], v[86:89]
	v_mfma_i32_16x16x64_i8 v[94:97], v[126:129], v[182:185], v[94:97]
	v_mfma_i32_16x16x64_i8 v[94:97], v[178:181], v[186:189], v[94:97]
	s_setprio 0
	s_barrier
; #define PG8_STAGE(bufoff, gbase, voff) do { _Pragma("unroll") for (int _i = 0; _i < 2; ++_i) \
;         __builtin_amdgcn_global_load_lds((const unsigned*)((const char*)(gbase) + (voff)[_i]), (PG8_LAS unsigned*)(lds + (bufoff) + ldsw + _i * 8192), 16, 0, 0); } while (0)
; #define PG8_LDA(dst, b, h) do { _Pragma("unroll") for (int m = 0; m < 4; ++m) _Pragma("unroll") for (int k = 0; k < 2; ++k) dst[m][k] = *(const PG8_LAS bf16x8*)(lds + PG8_SA(b, h) + aoff + m * 2048 + k * 1024); } while (0)
; #define PG8_LDB(dst, b, h) do { _Pragma("unroll") for (int n = 0; n < 2; ++n) _Pragma("unroll") for (int k = 0; k < 2; ++k) dst[n][k] = *(const PG8_LAS bf16x8*)(lds + PG8_SB(b, h) + boff + n * 2048 + k * 1024); } while (0)
; template <class Epi, class Sched, bool ALIGN_EPI = false, bool SP2 = false>
; __device__ __forceinline__ void gemm_phase(PG8_LAS unsigned char* lds, const Gemm g, const Sched& S, const Epi& E) {
;     ...
;         for (int t = 0; t < nt; t += 2) {
;             const bool last = (t == nt - 2);
;             const char* a1 = cA + (size_t)(t + 1) * kstep;
;             const char* a2 = last ? nA : cA + (size_t)(t + 2) * kstep; const char* b2 = last ? nB : cB + (size_t)(t + 2) * kstep;
;             const char* a3 = a2 + kstep; const char* b3 = b2 + kstep;
;             if (last && has_next) S.a_ready(nxt);
;             if constexpr (SP2) {
;             PG8_LDB(B0, 0, 0); PG8_LDB(B1, 0, 1); PG8_SCHED; PG8_LDA(At, 0, 0); PG8_STAGE(PG8_SA(1, 1), a1 + hstep, voffA);
;             PG8_WAIT_V(8); PG8_WAIT_L(0); PG8_BAR; PG8_MMA(0, 0, At, B0); PG8_MMA(0, 1, At, B1); PG8_BAR; PG8_SCHED;
;             PG8_LDA(At, 0, 1); PG8_STAGE(PG8_SB(0, 0), b2, voffB); PG8_STAGE(PG8_SB(0, 1), b2 + hstep, voffB); PG8_STAGE(PG8_SA(0, 0), a2, voffA);
;             PG8_WAIT_V(8); PG8_WAIT_L(0); PG8_BAR; PG8_MMA(1, 0, At, B0); PG8_MMA(1, 1, At, B1); PG8_BAR; PG8_SCHED;
;             PG8_LDB(B0, 1, 0); PG8_LDB(B1, 1, 1); PG8_SCHED; PG8_LDA(At, 1, 0); PG8_STAGE(PG8_SA(0, 1), a2 + hstep, voffA);
;             PG8_WAIT_V(8); PG8_WAIT_L(0); PG8_BAR; PG8_MMA(0, 0, At, B0); PG8_MMA(0, 1, At, B1); PG8_BAR; PG8_SCHED;
;             PG8_LDA(At, 1, 1); PG8_STAGE(PG8_SB(1, 0), b3, voffB); PG8_STAGE(PG8_SB(1, 1), b3 + hstep, voffB); PG8_STAGE(PG8_SA(1, 0), a3, voffA);
;             PG8_WAIT_V(8); PG8_WAIT_L(0); PG8_BAR; PG8_MMA(1, 0, At, B0); PG8_MMA(1, 1, At, B1); PG8_BAR; PG8_SCHED;
	s_add_i32 s8, s66, s81
	v_lshl_add_u64 v[168:169], v[168:169], 0, s[92:93]
	s_mov_b32 m0, s8
	ds_read_b128 v[182:185], v177 offset:49152
	ds_read_b128 v[186:189], v177 offset:50176
	ds_read_b128 v[190:193], v177 offset:51200
	ds_read_b128 v[194:197], v177 offset:52224
	ds_read_b128 v[198:201], v177 offset:53248
	ds_read_b128 v[210:213], v177 offset:54272
	ds_read_b128 v[214:217], v177 offset:55296
	ds_read_b128 v[218:221], v177 offset:56320
	global_load_lds_dwordx4 v[168:169], off
	s_add_i32 m0, s8, 0x2000
	s_add_u32 s8, s96, 0x40080
	v_lshl_add_u64 v[168:169], v[206:207], 0, s[92:93]
	s_addc_u32 s9, s97, 0
	s_add_i32 s66, s70, s81
	global_load_lds_dwordx4 v[168:169], off
	v_lshl_add_u64 v[168:169], s[8:9], 0, v[0:1]
	s_mov_b32 m0, s66
	s_nop 0
	global_load_lds_dwordx4 v[168:169], off
	v_lshl_add_u64 v[168:169], s[8:9], 0, v[158:159]
	s_add_i32 m0, s66, 0x2000
	s_nop 0
	global_load_lds_dwordx4 v[168:169], off
	v_lshl_add_u64 v[168:169], v[222:223], 0, s[92:93]
	s_mov_b32 m0, s13
	s_nop 0
	global_load_lds_dwordx4 v[168:169], off
	v_lshl_add_u64 v[168:169], v[224:225], 0, s[92:93]
	s_mov_b32 m0, s12
	s_nop 0
	global_load_lds_dwordx4 v[168:169], off
	s_waitcnt vmcnt(8)
	s_waitcnt lgkmcnt(0)
	s_barrier
	s_setprio 1
	s_waitcnt lgkmcnt(0)
	v_mfma_i32_16x16x64_i8 v[62:65], v[66:69], v[182:185], v[62:65]
	v_mfma_i32_16x16x64_i8 v[62:65], v[70:73], v[186:189], v[62:65]
	v_mfma_i32_16x16x64_i8 v[58:61], v[66:69], v[190:193], v[58:61]
	v_mfma_i32_16x16x64_i8 v[58:61], v[70:73], v[194:197], v[58:61]
	v_mfma_i32_16x16x64_i8 v[50:53], v[66:69], v[198:201], v[50:53]
	v_mfma_i32_16x16x64_i8 v[50:53], v[70:73], v[210:213], v[50:53]
	v_mfma_i32_16x16x64_i8 v[42:45], v[66:69], v[214:217], v[42:45]
	v_mfma_i32_16x16x64_i8 v[42:45], v[70:73], v[218:221], v[42:45]
	v_mfma_i32_16x16x64_i8 v[34:37], v[106:109], v[214:217], v[34:37]
	v_mfma_i32_16x16x64_i8 v[34:37], v[110:113], v[218:221], v[34:37]
	v_mfma_i32_16x16x64_i8 v[38:41], v[106:109], v[198:201], v[38:41]
	v_mfma_i32_16x16x64_i8 v[38:41], v[110:113], v[210:213], v[38:41]
	v_mfma_i32_16x16x64_i8 v[46:49], v[106:109], v[190:193], v[46:49]
	v_mfma_i32_16x16x64_i8 v[46:49], v[110:113], v[194:197], v[46:49]
	v_mfma_i32_16x16x64_i8 v[54:57], v[106:109], v[182:185], v[54:57]
	v_mfma_i32_16x16x64_i8 v[54:57], v[110:113], v[186:189], v[54:57]
	s_setprio 0
	s_setprio 1
	v_mfma_i32_16x16x64_i8 v[30:33], v[114:117], v[182:185], v[30:33]
	v_mfma_i32_16x16x64_i8 v[30:33], v[118:121], v[186:189], v[30:33]
	v_mfma_i32_16x16x64_i8 v[26:29], v[114:117], v[190:193], v[26:29]
	v_mfma_i32_16x16x64_i8 v[26:29], v[118:121], v[194:197], v[26:29]
	v_mfma_i32_16x16x64_i8 v[18:21], v[114:117], v[198:201], v[18:21]
	v_mfma_i32_16x16x64_i8 v[18:21], v[118:121], v[210:213], v[18:21]
	v_mfma_i32_16x16x64_i8 v[10:13], v[114:117], v[214:217], v[10:13]
	v_mfma_i32_16x16x64_i8 v[10:13], v[118:121], v[218:221], v[10:13]
	v_mfma_i32_16x16x64_i8 v[2:5], v[126:129], v[214:217], v[2:5]
	v_mfma_i32_16x16x64_i8 v[2:5], v[178:181], v[218:221], v[2:5]
	v_mfma_i32_16x16x64_i8 v[6:9], v[126:129], v[198:201], v[6:9]
	v_mfma_i32_16x16x64_i8 v[6:9], v[178:181], v[210:213], v[6:9]
	v_mfma_i32_16x16x64_i8 v[14:17], v[126:129], v[190:193], v[14:17]
	v_mfma_i32_16x16x64_i8 v[14:17], v[178:181], v[194:197], v[14:17]
	v_mfma_i32_16x16x64_i8 v[22:25], v[126:129], v[182:185], v[22:25]
	v_mfma_i32_16x16x64_i8 v[22:25], v[178:181], v[186:189], v[22:25]
	s_setprio 0
	s_barrier
	s_add_i32 s10, s10, 2
	s_add_u32 s69, s69, 0x100
	s_addc_u32 s68, s68, 0
	s_cmp_gt_u32 s10, 13
	s_mov_b64 s[8:9], s[84:85]
	s_cbranch_scc0 .LBB0_291
	s_branch .Lpeelx291
.LBB0_291:
	s_add_u32 s84, s8, 0x100
	s_addc_u32 s85, s9, 0
	s_add_i32 s66, 0, 0x10000
	s_cmp_eq_u32 s10, 12
	s_cselect_b32 vcc_hi, s5, s85
	s_cselect_b32 vcc_lo, s7, s84
	s_cselect_b32 s97, s11, s68
	s_cselect_b32 s96, s67, s69
	s_add_i32 s70, 0, 0x14000
	v_add_u32_e32 v110, s66, v175
	v_add_u32_e32 v168, s70, v175
	s_waitcnt vmcnt(0)
	ds_read_b128 v[66:69], v110
	ds_read_b128 v[70:73], v110 offset:1024
	ds_read_b128 v[106:109], v110 offset:2048
	ds_read_b128 v[110:113], v110 offset:3072
	ds_read_b128 v[114:117], v168
	ds_read_b128 v[118:121], v168 offset:1024
	ds_read_b128 v[126:129], v168 offset:2048
	ds_read_b128 v[178:181], v168 offset:3072
	v_lshl_add_u64 v[168:169], s[8:9], 0, v[164:165]
	s_add_i32 m0, s1, 0xc000
	ds_read_b128 v[182:185], v177
	ds_read_b128 v[186:189], v177 offset:1024
	ds_read_b128 v[190:193], v177 offset:2048
	ds_read_b128 v[194:197], v177 offset:3072
	ds_read_b128 v[198:201], v177 offset:4096
	ds_read_b128 v[210:213], v177 offset:5120
	ds_read_b128 v[214:217], v177 offset:6144
	ds_read_b128 v[218:221], v177 offset:7168
	global_load_lds_dwordx4 v[168:169], off
	v_lshl_add_u64 v[168:169], s[8:9], 0, v[166:167]
	s_add_i32 m0, s1, 0xe000
	s_nop 0
	global_load_lds_dwordx4 v[168:169], off
	s_waitcnt vmcnt(8)
	s_waitcnt lgkmcnt(0)
	s_barrier
; #define PG8_STAGE(bufoff, gbase, voff) do { _Pragma("unroll") for (int _i = 0; _i < 2; ++_i) \
;         __builtin_amdgcn_global_load_lds((const unsigned*)((const char*)(gbase) + (voff)[_i]), (PG8_LAS unsigned*)(lds + (bufoff) + ldsw + _i * 8192), 16, 0, 0); } while (0)
; #define PG8_LDA(dst, b, h) do { _Pragma("unroll") for (int m = 0; m < 4; ++m) _Pragma("unroll") for (int k = 0; k < 2; ++k) dst[m][k] = *(const PG8_LAS bf16x8*)(lds + PG8_SA(b, h) + aoff + m * 2048 + k * 1024); } while (0)
; #define PG8_LDB(dst, b, h) do { _Pragma("unroll") for (int n = 0; n < 2; ++n) _Pragma("unroll") for (int k = 0; k < 2; ++k) dst[n][k] = *(const PG8_LAS bf16x8*)(lds + PG8_SB(b, h) + boff + n * 2048 + k * 1024); } while (0)
; #define PG8_MMA(ai, bj, At, Bt) do { __builtin_amdgcn_s_setprio(1); _Pragma("unroll") for (int m = 0; m < 4; ++m) _Pragma("unroll") for (int n = 0; n < 2; ++n) _Pragma("unroll") for (int k = 0; k < 2; ++k) \
;         acc[ai][bj][m][n] = mma16<Epi::I8>(Bt[n][k], At[m][k], acc[ai][bj][m][n]); __builtin_amdgcn_s_setprio(0); } while (0)
; #define PG8_WAIT_V(n) asm volatile("s_waitcnt vmcnt(" #n ")" ::: "memory")
; #define PG8_WAIT_L(n) asm volatile("s_waitcnt lgkmcnt(" #n ")" ::: "memory")
; #define PG8_BAR __builtin_amdgcn_s_barrier()
; #define PG8_SCHED __builtin_amdgcn_sched_barrier(0)
; template <class Epi, class Sched, bool ALIGN_EPI = false, bool SP2 = false>
; __device__ __forceinline__ void gemm_phase(PG8_LAS unsigned char* lds, const Gemm g, const Sched& S, const Epi& E) {
;     ...
;             PG8_LDB(B0, 0, 0); PG8_LDB(B1, 0, 1); PG8_SCHED; PG8_LDA(At, 0, 0); PG8_STAGE(PG8_SA(1, 1), a1 + hstep, voffA);
;             PG8_WAIT_V(8); PG8_WAIT_L(0); PG8_BAR; PG8_MMA(0, 0, At, B0); PG8_MMA(0, 1, At, B1); PG8_BAR; PG8_SCHED;
;             PG8_LDA(At, 0, 1); PG8_STAGE(PG8_SB(0, 0), b2, voffB); PG8_STAGE(PG8_SB(0, 1), b2 + hstep, voffB); PG8_STAGE(PG8_SA(0, 0), a2, voffA);
;             PG8_WAIT_V(8); PG8_WAIT_L(0); PG8_BAR; PG8_MMA(1, 0, At, B0); PG8_MMA(1, 1, At, B1); PG8_BAR; PG8_SCHED;
;             PG8_LDB(B0, 1, 0); PG8_LDB(B1, 1, 1); PG8_SCHED; PG8_LDA(At, 1, 0); PG8_STAGE(PG8_SA(0, 1), a2 + hstep, voffA);
;             PG8_WAIT_V(8); PG8_WAIT_L(0); PG8_BAR; PG8_MMA(0, 0, At, B0); PG8_MMA(0, 1, At, B1); PG8_BAR; PG8_SCHED;
	s_setprio 1
	s_waitcnt lgkmcnt(0)
	v_mfma_i32_16x16x64_i8 v[154:157], v[66:69], v[182:185], v[154:157]
	v_mfma_i32_16x16x64_i8 v[154:157], v[70:73], v[186:189], v[154:157]
	v_mfma_i32_16x16x64_i8 v[150:153], v[66:69], v[190:193], v[150:153]
	v_mfma_i32_16x16x64_i8 v[150:153], v[70:73], v[194:197], v[150:153]
	v_mfma_i32_16x16x64_i8 v[142:145], v[66:69], v[198:201], v[142:145]
	v_mfma_i32_16x16x64_i8 v[142:145], v[70:73], v[210:213], v[142:145]
	v_mfma_i32_16x16x64_i8 v[134:137], v[66:69], v[214:217], v[134:137]
	v_mfma_i32_16x16x64_i8 v[134:137], v[70:73], v[218:221], v[134:137]
	v_mfma_i32_16x16x64_i8 v[122:125], v[106:109], v[214:217], v[122:125]
	v_mfma_i32_16x16x64_i8 v[122:125], v[110:113], v[218:221], v[122:125]
	v_mfma_i32_16x16x64_i8 v[130:133], v[106:109], v[198:201], v[130:133]
	v_mfma_i32_16x16x64_i8 v[130:133], v[110:113], v[210:213], v[130:133]
	v_mfma_i32_16x16x64_i8 v[138:141], v[106:109], v[190:193], v[138:141]
	v_mfma_i32_16x16x64_i8 v[138:141], v[110:113], v[194:197], v[138:141]
	v_mfma_i32_16x16x64_i8 v[146:149], v[106:109], v[182:185], v[146:149]
	v_mfma_i32_16x16x64_i8 v[146:149], v[110:113], v[186:189], v[146:149]
	s_setprio 0
	s_setprio 1
	v_mfma_i32_16x16x64_i8 v[102:105], v[114:117], v[182:185], v[102:105]
	v_mfma_i32_16x16x64_i8 v[102:105], v[118:121], v[186:189], v[102:105]
	v_mfma_i32_16x16x64_i8 v[98:101], v[114:117], v[190:193], v[98:101]
	v_mfma_i32_16x16x64_i8 v[98:101], v[118:121], v[194:197], v[98:101]
	v_mfma_i32_16x16x64_i8 v[90:93], v[114:117], v[198:201], v[90:93]
	v_mfma_i32_16x16x64_i8 v[90:93], v[118:121], v[210:213], v[90:93]
	v_mfma_i32_16x16x64_i8 v[82:85], v[114:117], v[214:217], v[82:85]
	v_mfma_i32_16x16x64_i8 v[82:85], v[118:121], v[218:221], v[82:85]
	v_mfma_i32_16x16x64_i8 v[74:77], v[126:129], v[214:217], v[74:77]
	v_mfma_i32_16x16x64_i8 v[74:77], v[178:181], v[218:221], v[74:77]
	v_mfma_i32_16x16x64_i8 v[78:81], v[126:129], v[198:201], v[78:81]
	v_mfma_i32_16x16x64_i8 v[78:81], v[178:181], v[210:213], v[78:81]
	v_mfma_i32_16x16x64_i8 v[86:89], v[126:129], v[190:193], v[86:89]
	v_mfma_i32_16x16x64_i8 v[86:89], v[178:181], v[194:197], v[86:89]
	v_mfma_i32_16x16x64_i8 v[94:97], v[126:129], v[182:185], v[94:97]
	v_mfma_i32_16x16x64_i8 v[94:97], v[178:181], v[186:189], v[94:97]
	s_setprio 0
	s_barrier
	s_add_i32 s8, s66, s81
	v_lshl_add_u64 v[168:169], s[96:97], 0, v[0:1]
	s_mov_b32 m0, s8
	ds_read_b128 v[182:185], v177 offset:16384
	ds_read_b128 v[186:189], v177 offset:17408
	ds_read_b128 v[190:193], v177 offset:18432
	ds_read_b128 v[194:197], v177 offset:19456
	ds_read_b128 v[198:201], v177 offset:20480
	ds_read_b128 v[210:213], v177 offset:21504
	ds_read_b128 v[214:217], v177 offset:22528
	ds_read_b128 v[218:221], v177 offset:23552
	global_load_lds_dwordx4 v[168:169], off
	s_add_i32 m0, s8, 0x2000
	s_add_u32 s8, s96, 0x40000
	v_lshl_add_u64 v[206:207], s[96:97], 0, v[158:159]
	s_addc_u32 s9, s97, 0
	s_add_i32 s66, s70, s81
	global_load_lds_dwordx4 v[206:207], off
	v_lshl_add_u64 v[222:223], s[8:9], 0, v[0:1]
	s_mov_b32 m0, s66
	v_lshl_add_u64 v[224:225], vcc, 0, v[160:161]
	global_load_lds_dwordx4 v[222:223], off
	v_lshl_add_u64 v[222:223], s[8:9], 0, v[158:159]
	s_add_i32 m0, s66, 0x2000
	s_nop 0
	global_load_lds_dwordx4 v[222:223], off
	v_lshl_add_u64 v[222:223], vcc, 0, v[162:163]
	s_mov_b32 m0, s1
	s_nop 0
	global_load_lds_dwordx4 v[222:223], off
	s_mov_b32 m0, s58
	s_nop 0
	global_load_lds_dwordx4 v[224:225], off
	s_waitcnt vmcnt(8)
	s_waitcnt lgkmcnt(0)
	s_barrier
	s_setprio 1
	s_waitcnt lgkmcnt(0)
	v_mfma_i32_16x16x64_i8 v[62:65], v[66:69], v[182:185], v[62:65]
	v_mfma_i32_16x16x64_i8 v[62:65], v[70:73], v[186:189], v[62:65]
	v_mfma_i32_16x16x64_i8 v[58:61], v[66:69], v[190:193], v[58:61]
	v_mfma_i32_16x16x64_i8 v[58:61], v[70:73], v[194:197], v[58:61]
	v_mfma_i32_16x16x64_i8 v[50:53], v[66:69], v[198:201], v[50:53]
	v_mfma_i32_16x16x64_i8 v[50:53], v[70:73], v[210:213], v[50:53]
	v_mfma_i32_16x16x64_i8 v[42:45], v[66:69], v[214:217], v[42:45]
	v_mfma_i32_16x16x64_i8 v[42:45], v[70:73], v[218:221], v[42:45]
	v_mfma_i32_16x16x64_i8 v[34:37], v[106:109], v[214:217], v[34:37]
	v_mfma_i32_16x16x64_i8 v[34:37], v[110:113], v[218:221], v[34:37]
	v_mfma_i32_16x16x64_i8 v[38:41], v[106:109], v[198:201], v[38:41]
	v_mfma_i32_16x16x64_i8 v[38:41], v[110:113], v[210:213], v[38:41]
	v_mfma_i32_16x16x64_i8 v[46:49], v[106:109], v[190:193], v[46:49]
	v_mfma_i32_16x16x64_i8 v[46:49], v[110:113], v[194:197], v[46:49]
	v_mfma_i32_16x16x64_i8 v[54:57], v[106:109], v[182:185], v[54:57]
	v_mfma_i32_16x16x64_i8 v[54:57], v[110:113], v[186:189], v[54:57]
	s_setprio 0
	s_setprio 1
	v_mfma_i32_16x16x64_i8 v[30:33], v[114:117], v[182:185], v[30:33]
	v_mfma_i32_16x16x64_i8 v[30:33], v[118:121], v[186:189], v[30:33]
	v_mfma_i32_16x16x64_i8 v[26:29], v[114:117], v[190:193], v[26:29]
	v_mfma_i32_16x16x64_i8 v[26:29], v[118:121], v[194:197], v[26:29]
	v_mfma_i32_16x16x64_i8 v[18:21], v[114:117], v[198:201], v[18:21]
	v_mfma_i32_16x16x64_i8 v[18:21], v[118:121], v[210:213], v[18:21]
	v_mfma_i32_16x16x64_i8 v[10:13], v[114:117], v[214:217], v[10:13]
	v_mfma_i32_16x16x64_i8 v[10:13], v[118:121], v[218:221], v[10:13]
	v_mfma_i32_16x16x64_i8 v[2:5], v[126:129], v[214:217], v[2:5]
	v_mfma_i32_16x16x64_i8 v[2:5], v[178:181], v[218:221], v[2:5]
	v_mfma_i32_16x16x64_i8 v[6:9], v[126:129], v[198:201], v[6:9]
	v_mfma_i32_16x16x64_i8 v[6:9], v[178:181], v[210:213], v[6:9]
	v_mfma_i32_16x16x64_i8 v[14:17], v[126:129], v[190:193], v[14:17]
	v_mfma_i32_16x16x64_i8 v[14:17], v[178:181], v[194:197], v[14:17]
	v_mfma_i32_16x16x64_i8 v[22:25], v[126:129], v[182:185], v[22:25]
	v_mfma_i32_16x16x64_i8 v[22:25], v[178:181], v[186:189], v[22:25]
	s_setprio 0
	s_barrier
; #define PG8_STAGE(bufoff, gbase, voff) do { _Pragma("unroll") for (int _i = 0; _i < 2; ++_i) \
;         __builtin_amdgcn_global_load_lds((const unsigned*)((const char*)(gbase) + (voff)[_i]), (PG8_LAS unsigned*)(lds + (bufoff) + ldsw + _i * 8192), 16, 0, 0); } while (0)
; #define PG8_LDA(dst, b, h) do { _Pragma("unroll") for (int m = 0; m < 4; ++m) _Pragma("unroll") for (int k = 0; k < 2; ++k) dst[m][k] = *(const PG8_LAS bf16x8*)(lds + PG8_SA(b, h) + aoff + m * 2048 + k * 1024); } while (0)
; #define PG8_LDB(dst, b, h) do { _Pragma("unroll") for (int n = 0; n < 2; ++n) _Pragma("unroll") for (int k = 0; k < 2; ++k) dst[n][k] = *(const PG8_LAS bf16x8*)(lds + PG8_SB(b, h) + boff + n * 2048 + k * 1024); } while (0)
; #define PG8_MMA(ai, bj, At, Bt) do { __builtin_amdgcn_s_setprio(1); _Pragma("unroll") for (int m = 0; m < 4; ++m) _Pragma("unroll") for (int n = 0; n < 2; ++n) _Pragma("unroll") for (int k = 0; k < 2; ++k) \
;         acc[ai][bj][m][n] = mma16<Epi::I8>(Bt[n][k], At[m][k], acc[ai][bj][m][n]); __builtin_amdgcn_s_setprio(0); } while (0)
; #define PG8_WAIT_V(n) asm volatile("s_waitcnt vmcnt(" #n ")" ::: "memory")
; #define PG8_WAIT_L(n) asm volatile("s_waitcnt lgkmcnt(" #n ")" ::: "memory")
; #define PG8_BAR __builtin_amdgcn_s_barrier()
; #define PG8_SCHED __builtin_amdgcn_sched_barrier(0)
; template <class Epi, class Sched, bool ALIGN_EPI = false, bool SP2 = false>
; __device__ __forceinline__ void gemm_phase(PG8_LAS unsigned char* lds, const Gemm g, const Sched& S, const Epi& E) {
;     ...
;             PG8_LDB(B0, 1, 0); PG8_LDB(B1, 1, 1); PG8_SCHED; PG8_LDA(At, 1, 0); PG8_STAGE(PG8_SA(0, 1), a2 + hstep, voffA);
;             PG8_WAIT_V(8); PG8_WAIT_L(0); PG8_BAR; PG8_MMA(0, 0, At, B0); PG8_MMA(0, 1, At, B1); PG8_BAR; PG8_SCHED;
;             PG8_LDA(At, 1, 1); PG8_STAGE(PG8_SB(1, 0), b3, voffB); PG8_STAGE(PG8_SB(1, 1), b3 + hstep, voffB); PG8_STAGE(PG8_SA(1, 0), a3, voffA);
;             PG8_WAIT_V(8); PG8_WAIT_L(0); PG8_BAR; PG8_MMA(1, 0, At, B0); PG8_MMA(1, 1, At, B1); PG8_BAR; PG8_SCHED;
	s_add_i32 s66, 0, 0x18000
	s_add_i32 s70, 0, 0x1c000
	v_add_u32_e32 v110, s66, v175
	v_add_u32_e32 v170, s70, v175
	ds_read_b128 v[66:69], v110
	ds_read_b128 v[70:73], v110 offset:1024
	ds_read_b128 v[106:109], v110 offset:2048
	ds_read_b128 v[110:113], v110 offset:3072
	ds_read_b128 v[114:117], v170
	ds_read_b128 v[118:121], v170 offset:1024
	ds_read_b128 v[126:129], v170 offset:2048
	ds_read_b128 v[178:181], v170 offset:3072
	s_add_u32 s8, vcc_lo, 0x40000
	s_addc_u32 s9, vcc_hi, 0
	s_mov_b32 m0, s80
	v_lshl_add_u64 v[226:227], s[8:9], 0, v[162:163]
	ds_read_b128 v[182:185], v177 offset:32768
	ds_read_b128 v[186:189], v177 offset:33792
	ds_read_b128 v[190:193], v177 offset:34816
	ds_read_b128 v[194:197], v177 offset:35840
	ds_read_b128 v[198:201], v177 offset:36864
	ds_read_b128 v[210:213], v177 offset:37888
	ds_read_b128 v[214:217], v177 offset:38912
	ds_read_b128 v[218:221], v177 offset:39936
	global_load_lds_dwordx4 v[226:227], off
	v_lshl_add_u64 v[226:227], s[8:9], 0, v[160:161]
	s_mov_b32 m0, s0
	s_nop 0
	global_load_lds_dwordx4 v[226:227], off
	s_waitcnt vmcnt(8)
	s_waitcnt lgkmcnt(0)
	s_barrier
	s_setprio 1
	s_waitcnt lgkmcnt(0)
	v_mfma_i32_16x16x64_i8 v[154:157], v[66:69], v[182:185], v[154:157]
	v_mfma_i32_16x16x64_i8 v[154:157], v[70:73], v[186:189], v[154:157]
	v_mfma_i32_16x16x64_i8 v[150:153], v[66:69], v[190:193], v[150:153]
	v_mfma_i32_16x16x64_i8 v[150:153], v[70:73], v[194:197], v[150:153]
	v_mfma_i32_16x16x64_i8 v[142:145], v[66:69], v[198:201], v[142:145]
	v_mfma_i32_16x16x64_i8 v[142:145], v[70:73], v[210:213], v[142:145]
	v_mfma_i32_16x16x64_i8 v[134:137], v[66:69], v[214:217], v[134:137]
	v_mfma_i32_16x16x64_i8 v[134:137], v[70:73], v[218:221], v[134:137]
	v_mfma_i32_16x16x64_i8 v[122:125], v[106:109], v[214:217], v[122:125]
	v_mfma_i32_16x16x64_i8 v[122:125], v[110:113], v[218:221], v[122:125]
	v_mfma_i32_16x16x64_i8 v[130:133], v[106:109], v[198:201], v[130:133]
	v_mfma_i32_16x16x64_i8 v[130:133], v[110:113], v[210:213], v[130:133]
	v_mfma_i32_16x16x64_i8 v[138:141], v[106:109], v[190:193], v[138:141]
	v_mfma_i32_16x16x64_i8 v[138:141], v[110:113], v[194:197], v[138:141]
	v_mfma_i32_16x16x64_i8 v[146:149], v[106:109], v[182:185], v[146:149]
	v_mfma_i32_16x16x64_i8 v[146:149], v[110:113], v[186:189], v[146:149]
	s_setprio 0
	s_setprio 1
	v_mfma_i32_16x16x64_i8 v[102:105], v[114:117], v[182:185], v[102:105]
	v_mfma_i32_16x16x64_i8 v[102:105], v[118:121], v[186:189], v[102:105]
	v_mfma_i32_16x16x64_i8 v[98:101], v[114:117], v[190:193], v[98:101]
	v_mfma_i32_16x16x64_i8 v[98:101], v[118:121], v[194:197], v[98:101]
	v_mfma_i32_16x16x64_i8 v[90:93], v[114:117], v[198:201], v[90:93]
	v_mfma_i32_16x16x64_i8 v[90:93], v[118:121], v[210:213], v[90:93]
	v_mfma_i32_16x16x64_i8 v[82:85], v[114:117], v[214:217], v[82:85]
	v_mfma_i32_16x16x64_i8 v[82:85], v[118:121], v[218:221], v[82:85]
	v_mfma_i32_16x16x64_i8 v[74:77], v[126:129], v[214:217], v[74:77]
	v_mfma_i32_16x16x64_i8 v[74:77], v[178:181], v[218:221], v[74:77]
	v_mfma_i32_16x16x64_i8 v[78:81], v[126:129], v[198:201], v[78:81]
	v_mfma_i32_16x16x64_i8 v[78:81], v[178:181], v[210:213], v[78:81]
	v_mfma_i32_16x16x64_i8 v[86:89], v[126:129], v[190:193], v[86:89]
	v_mfma_i32_16x16x64_i8 v[86:89], v[178:181], v[194:197], v[86:89]
	v_mfma_i32_16x16x64_i8 v[94:97], v[126:129], v[182:185], v[94:97]
	v_mfma_i32_16x16x64_i8 v[94:97], v[178:181], v[186:189], v[94:97]
	s_setprio 0
	s_barrier
	s_add_i32 s8, s66, s81
	v_lshl_add_u64 v[168:169], v[168:169], 0, s[92:93]
	s_mov_b32 m0, s8
	ds_read_b128 v[182:185], v177 offset:49152
	ds_read_b128 v[186:189], v177 offset:50176
	ds_read_b128 v[190:193], v177 offset:51200
	ds_read_b128 v[194:197], v177 offset:52224
	ds_read_b128 v[198:201], v177 offset:53248
	ds_read_b128 v[210:213], v177 offset:54272
	ds_read_b128 v[214:217], v177 offset:55296
	ds_read_b128 v[218:221], v177 offset:56320
	global_load_lds_dwordx4 v[168:169], off
	s_add_i32 m0, s8, 0x2000
	s_add_u32 s8, s96, 0x40080
	v_lshl_add_u64 v[168:169], v[206:207], 0, s[92:93]
	s_addc_u32 s9, s97, 0
	s_add_i32 s66, s70, s81
	global_load_lds_dwordx4 v[168:169], off
	v_lshl_add_u64 v[168:169], s[8:9], 0, v[0:1]
	s_mov_b32 m0, s66
	s_nop 0
	global_load_lds_dwordx4 v[168:169], off
	v_lshl_add_u64 v[168:169], s[8:9], 0, v[158:159]
	s_add_i32 m0, s66, 0x2000
	s_nop 0
	global_load_lds_dwordx4 v[168:169], off
	v_lshl_add_u64 v[168:169], v[222:223], 0, s[92:93]
	s_mov_b32 m0, s13
	s_nop 0
	global_load_lds_dwordx4 v[168:169], off
	v_lshl_add_u64 v[168:169], v[224:225], 0, s[92:93]
	s_mov_b32 m0, s12
	s_nop 0
	global_load_lds_dwordx4 v[168:169], off
	s_waitcnt vmcnt(8)
	s_waitcnt lgkmcnt(0)
	s_barrier
	s_setprio 1
	s_waitcnt lgkmcnt(0)
	v_mfma_i32_16x16x64_i8 v[62:65], v[66:69], v[182:185], v[62:65]
	v_mfma_i32_16x16x64_i8 v[62:65], v[70:73], v[186:189], v[62:65]
	v_mfma_i32_16x16x64_i8 v[58:61], v[66:69], v[190:193], v[58:61]
	v_mfma_i32_16x16x64_i8 v[58:61], v[70:73], v[194:197], v[58:61]
	v_mfma_i32_16x16x64_i8 v[50:53], v[66:69], v[198:201], v[50:53]
	v_mfma_i32_16x16x64_i8 v[50:53], v[70:73], v[210:213], v[50:53]
	v_mfma_i32_16x16x64_i8 v[42:45], v[66:69], v[214:217], v[42:45]
	v_mfma_i32_16x16x64_i8 v[42:45], v[70:73], v[218:221], v[42:45]
	v_mfma_i32_16x16x64_i8 v[34:37], v[106:109], v[214:217], v[34:37]
	v_mfma_i32_16x16x64_i8 v[34:37], v[110:113], v[218:221], v[34:37]
	v_mfma_i32_16x16x64_i8 v[38:41], v[106:109], v[198:201], v[38:41]
	v_mfma_i32_16x16x64_i8 v[38:41], v[110:113], v[210:213], v[38:41]
	v_mfma_i32_16x16x64_i8 v[46:49], v[106:109], v[190:193], v[46:49]
	v_mfma_i32_16x16x64_i8 v[46:49], v[110:113], v[194:197], v[46:49]
	v_mfma_i32_16x16x64_i8 v[54:57], v[106:109], v[182:185], v[54:57]
	v_mfma_i32_16x16x64_i8 v[54:57], v[110:113], v[186:189], v[54:57]
	s_setprio 0
	s_setprio 1
	v_mfma_i32_16x16x64_i8 v[30:33], v[114:117], v[182:185], v[30:33]
	v_mfma_i32_16x16x64_i8 v[30:33], v[118:121], v[186:189], v[30:33]
	v_mfma_i32_16x16x64_i8 v[26:29], v[114:117], v[190:193], v[26:29]
	v_mfma_i32_16x16x64_i8 v[26:29], v[118:121], v[194:197], v[26:29]
	v_mfma_i32_16x16x64_i8 v[18:21], v[114:117], v[198:201], v[18:21]
	v_mfma_i32_16x16x64_i8 v[18:21], v[118:121], v[210:213], v[18:21]
	v_mfma_i32_16x16x64_i8 v[10:13], v[114:117], v[214:217], v[10:13]
	v_mfma_i32_16x16x64_i8 v[10:13], v[118:121], v[218:221], v[10:13]
	v_mfma_i32_16x16x64_i8 v[2:5], v[126:129], v[214:217], v[2:5]
	v_mfma_i32_16x16x64_i8 v[2:5], v[178:181], v[218:221], v[2:5]
	v_mfma_i32_16x16x64_i8 v[6:9], v[126:129], v[198:201], v[6:9]
	v_mfma_i32_16x16x64_i8 v[6:9], v[178:181], v[210:213], v[6:9]
	v_mfma_i32_16x16x64_i8 v[14:17], v[126:129], v[190:193], v[14:17]
	v_mfma_i32_16x16x64_i8 v[14:17], v[178:181], v[194:197], v[14:17]
	v_mfma_i32_16x16x64_i8 v[22:25], v[126:129], v[182:185], v[22:25]
	v_mfma_i32_16x16x64_i8 v[22:25], v[178:181], v[186:189], v[22:25]
	s_setprio 0
	s_barrier
	s_add_i32 s10, s10, 2
	s_add_u32 s69, s69, 0x100
	s_addc_u32 s68, s68, 0
	s_cmp_gt_u32 s10, 13
	s_mov_b64 s[8:9], s[84:85]
	s_cbranch_scc0 .LBB0_291

; #define PG8_STAGE(bufoff, gbase, voff) do { _Pragma("unroll") for (int _i = 0; _i < 2; ++_i) \
;         __builtin_amdgcn_global_load_lds((const unsigned*)((const char*)(gbase) + (voff)[_i]), (PG8_LAS unsigned*)(lds + (bufoff) + ldsw + _i * 8192), 16, 0, 0); } while (0)
; #define PG8_LDA(dst, b, h) do { _Pragma("unroll") for (int m = 0; m < 4; ++m) _Pragma("unroll") for (int k = 0; k < 2; ++k) dst[m][k] = *(const PG8_LAS bf16x8*)(lds + PG8_SA(b, h) + aoff + m * 2048 + k * 1024); } while (0)
; #define PG8_LDB(dst, b, h) do { _Pragma("unroll") for (int n = 0; n < 2; ++n) _Pragma("unroll") for (int k = 0; k < 2; ++k) dst[n][k] = *(const PG8_LAS bf16x8*)(lds + PG8_SB(b, h) + boff + n * 2048 + k * 1024); } while (0)
; #define PG8_MMA(ai, bj, At, Bt) do { __builtin_amdgcn_s_setprio(1); _Pragma("unroll") for (int m = 0; m < 4; ++m) _Pragma("unroll") for (int n = 0; n < 2; ++n) _Pragma("unroll") for (int k = 0; k < 2; ++k) \
;         acc[ai][bj][m][n] = mma16<Epi::I8>(Bt[n][k], At[m][k], acc[ai][bj][m][n]); __builtin_amdgcn_s_setprio(0); } while (0)
; #define PG8_WAIT_V(n) asm volatile("s_waitcnt vmcnt(" #n ")" ::: "memory")
; #define PG8_WAIT_L(n) asm volatile("s_waitcnt lgkmcnt(" #n ")" ::: "memory")
; #define PG8_BAR __builtin_amdgcn_s_barrier()
; #define PG8_SCHED __builtin_amdgcn_sched_barrier(0)
; template <class Epi, class Sched, bool ALIGN_EPI = false, bool SP2 = false>
; __device__ __forceinline__ void gemm_phase(PG8_LAS unsigned char* lds, const Gemm g, const Sched& S, const Epi& E) {
;     ...
;             PG8_LDB(B0, 0, 0); PG8_LDB(B1, 0, 1); PG8_SCHED; PG8_LDA(At, 0, 0); PG8_STAGE(PG8_SA(1, 1), a1 + hstep, voffA);
;             PG8_WAIT_V(8); PG8_WAIT_L(0); PG8_BAR; PG8_MMA(0, 0, At, B0); PG8_MMA(0, 1, At, B1); PG8_BAR; PG8_SCHED;
;             PG8_LDA(At, 0, 1); PG8_STAGE(PG8_SB(0, 0), b2, voffB); PG8_STAGE(PG8_SB(0, 1), b2 + hstep, voffB); PG8_STAGE(PG8_SA(0, 0), a2, voffA);
;             PG8_WAIT_V(8); PG8_WAIT_L(0); PG8_BAR; PG8_MMA(1, 0, At, B0); PG8_MMA(1, 1, At, B1); PG8_BAR; PG8_SCHED;
.Lpeel327:
	s_add_u32 s68, s8, 0x100
	s_addc_u32 s69, s9, 0
	s_add_i32 s84, 0, 0x10000
	s_cmp_eq_u32 s4, 28
	s_cselect_b32 vcc_hi, s1, s69
	s_cselect_b32 vcc_lo, s5, s68
	v_add_u32_e32 v0, s84, v188
	s_cselect_b32 s71, s7, s96
	s_cselect_b32 s70, s85, s97
	s_add_i32 s10, 0, 0x14000
	ds_read_b128 v[52:55], v0
	ds_read_b128 v[56:59], v0 offset:1024
	ds_read_b128 v[76:79], v0 offset:2048
	ds_read_b128 v[80:83], v0 offset:3072
	v_add_u32_e32 v0, s10, v188
	ds_read_b128 v[116:119], v0
	ds_read_b128 v[120:123], v0 offset:1024
	ds_read_b128 v[168:171], v0 offset:2048
	ds_read_b128 v[172:175], v0 offset:3072
	v_lshl_add_u64 v[2:3], s[8:9], 0, v[164:165]
	s_add_i32 m0, s58, 0xc000
	ds_read_b128 v[176:179], v189
	ds_read_b128 v[180:183], v189 offset:1024
	ds_read_b128 v[190:193], v189 offset:2048
	ds_read_b128 v[194:197], v189 offset:3072
	ds_read_b128 v[198:201], v189 offset:4096
	ds_read_b128 v[210:213], v189 offset:5120
	ds_read_b128 v[214:217], v189 offset:6144
	ds_read_b128 v[218:221], v189 offset:7168
	global_load_lds_dwordx4 v[2:3], off
	v_lshl_add_u64 v[2:3], s[8:9], 0, v[166:167]
	s_add_i32 m0, s58, 0xe000
	s_nop 0
	global_load_lds_dwordx4 v[2:3], off
	s_waitcnt vmcnt(8)
	s_waitcnt lgkmcnt(0)
	s_barrier
	s_setprio 1
	s_waitcnt lgkmcnt(0)
	v_mfma_f32_16x16x32_bf16 v[152:155], v[52:55], v[176:179], 0
	v_mfma_f32_16x16x32_bf16 v[152:155], v[56:59], v[180:183], v[152:155]
	v_mfma_f32_16x16x32_bf16 v[148:151], v[52:55], v[190:193], 0
	v_mfma_f32_16x16x32_bf16 v[148:151], v[56:59], v[194:197], v[148:151]
	v_mfma_f32_16x16x32_bf16 v[136:139], v[52:55], v[198:201], 0
	v_mfma_f32_16x16x32_bf16 v[136:139], v[56:59], v[210:213], v[136:139]
	v_mfma_f32_16x16x32_bf16 v[128:131], v[52:55], v[214:217], 0
	v_mfma_f32_16x16x32_bf16 v[128:131], v[56:59], v[218:221], v[128:131]
	v_mfma_f32_16x16x32_bf16 v[124:127], v[76:79], v[214:217], 0
	v_mfma_f32_16x16x32_bf16 v[124:127], v[80:83], v[218:221], v[124:127]
	v_mfma_f32_16x16x32_bf16 v[132:135], v[76:79], v[198:201], 0
	v_mfma_f32_16x16x32_bf16 v[132:135], v[80:83], v[210:213], v[132:135]
	v_mfma_f32_16x16x32_bf16 v[140:143], v[76:79], v[190:193], 0
	v_mfma_f32_16x16x32_bf16 v[140:143], v[80:83], v[194:197], v[140:143]
	v_mfma_f32_16x16x32_bf16 v[144:147], v[76:79], v[176:179], 0
	v_mfma_f32_16x16x32_bf16 v[144:147], v[80:83], v[180:183], v[144:147]
	s_setprio 0
	s_setprio 1
	v_mfma_f32_16x16x32_bf16 v[112:115], v[116:119], v[176:179], 0
	v_mfma_f32_16x16x32_bf16 v[112:115], v[120:123], v[180:183], v[112:115]
	v_mfma_f32_16x16x32_bf16 v[108:111], v[116:119], v[190:193], 0
	v_mfma_f32_16x16x32_bf16 v[108:111], v[120:123], v[194:197], v[108:111]
	v_mfma_f32_16x16x32_bf16 v[96:99], v[116:119], v[198:201], 0
	v_mfma_f32_16x16x32_bf16 v[96:99], v[120:123], v[210:213], v[96:99]
	v_mfma_f32_16x16x32_bf16 v[88:91], v[116:119], v[214:217], 0
	v_mfma_f32_16x16x32_bf16 v[88:91], v[120:123], v[218:221], v[88:91]
	v_mfma_f32_16x16x32_bf16 v[84:87], v[168:171], v[214:217], 0
	v_mfma_f32_16x16x32_bf16 v[84:87], v[172:175], v[218:221], v[84:87]
	v_mfma_f32_16x16x32_bf16 v[92:95], v[168:171], v[198:201], 0
	v_mfma_f32_16x16x32_bf16 v[92:95], v[172:175], v[210:213], v[92:95]
	v_mfma_f32_16x16x32_bf16 v[100:103], v[168:171], v[190:193], 0
	v_mfma_f32_16x16x32_bf16 v[100:103], v[172:175], v[194:197], v[100:103]
	v_mfma_f32_16x16x32_bf16 v[104:107], v[168:171], v[176:179], 0
	v_mfma_f32_16x16x32_bf16 v[104:107], v[172:175], v[180:183], v[104:107]
	s_setprio 0
	s_barrier
	s_add_i32 s8, s84, s80
	v_lshl_add_u64 v[184:185], s[70:71], 0, v[158:159]
	s_mov_b32 m0, s8
	ds_read_b128 v[176:179], v189 offset:16384
	ds_read_b128 v[180:183], v189 offset:17408
	ds_read_b128 v[190:193], v189 offset:18432
	ds_read_b128 v[194:197], v189 offset:19456
	ds_read_b128 v[198:201], v189 offset:20480
	ds_read_b128 v[210:213], v189 offset:21504
	ds_read_b128 v[214:217], v189 offset:22528
	ds_read_b128 v[218:221], v189 offset:23552
	global_load_lds_dwordx4 v[184:185], off
	s_add_i32 m0, s8, 0x2000
	s_add_u32 s8, s70, 0x80000
	v_lshl_add_u64 v[206:207], s[70:71], 0, v[162:163]
	s_addc_u32 s9, s71, 0
	s_add_i32 s10, s10, s80
	global_load_lds_dwordx4 v[206:207], off
	v_lshl_add_u64 v[2:3], s[8:9], 0, v[158:159]
	s_mov_b32 m0, s10
	v_lshl_add_u64 v[222:223], vcc, 0, v[156:157]
	global_load_lds_dwordx4 v[2:3], off
	v_lshl_add_u64 v[2:3], s[8:9], 0, v[162:163]
	s_add_i32 m0, s10, 0x2000
	v_lshl_add_u64 v[224:225], vcc, 0, v[160:161]
	global_load_lds_dwordx4 v[2:3], off
	s_mov_b32 m0, s58
	s_nop 0
	global_load_lds_dwordx4 v[222:223], off
	s_mov_b32 m0, s12
	s_nop 0
	global_load_lds_dwordx4 v[224:225], off
	s_waitcnt vmcnt(8)
	s_waitcnt lgkmcnt(0)
	s_barrier
; #define PG8_STAGE(bufoff, gbase, voff) do { _Pragma("unroll") for (int _i = 0; _i < 2; ++_i) \
;         __builtin_amdgcn_global_load_lds((const unsigned*)((const char*)(gbase) + (voff)[_i]), (PG8_LAS unsigned*)(lds + (bufoff) + ldsw + _i * 8192), 16, 0, 0); } while (0)
; #define PG8_LDA(dst, b, h) do { _Pragma("unroll") for (int m = 0; m < 4; ++m) _Pragma("unroll") for (int k = 0; k < 2; ++k) dst[m][k] = *(const PG8_LAS bf16x8*)(lds + PG8_SA(b, h) + aoff + m * 2048 + k * 1024); } while (0)
; #define PG8_LDB(dst, b, h) do { _Pragma("unroll") for (int n = 0; n < 2; ++n) _Pragma("unroll") for (int k = 0; k < 2; ++k) dst[n][k] = *(const PG8_LAS bf16x8*)(lds + PG8_SB(b, h) + boff + n * 2048 + k * 1024); } while (0)
; #define PG8_MMA(ai, bj, At, Bt) do { __builtin_amdgcn_s_setprio(1); _Pragma("unroll") for (int m = 0; m < 4; ++m) _Pragma("unroll") for (int n = 0; n < 2; ++n) _Pragma("unroll") for (int k = 0; k < 2; ++k) \
;         acc[ai][bj][m][n] = mma16<Epi::I8>(Bt[n][k], At[m][k], acc[ai][bj][m][n]); __builtin_amdgcn_s_setprio(0); } while (0)
; #define PG8_WAIT_V(n) asm volatile("s_waitcnt vmcnt(" #n ")" ::: "memory")
; #define PG8_WAIT_L(n) asm volatile("s_waitcnt lgkmcnt(" #n ")" ::: "memory")
; #define PG8_BAR __builtin_amdgcn_s_barrier()
; #define PG8_SCHED __builtin_amdgcn_sched_barrier(0)
; template <class Epi, class Sched, bool ALIGN_EPI = false, bool SP2 = false>
; __device__ __forceinline__ void gemm_phase(PG8_LAS unsigned char* lds, const Gemm g, const Sched& S, const Epi& E) {
;     ...
;             PG8_LDA(At, 0, 1); PG8_STAGE(PG8_SB(0, 0), b2, voffB); PG8_STAGE(PG8_SB(0, 1), b2 + hstep, voffB); PG8_STAGE(PG8_SA(0, 0), a2, voffA);
;             PG8_WAIT_V(8); PG8_WAIT_L(0); PG8_BAR; PG8_MMA(1, 0, At, B0); PG8_MMA(1, 1, At, B1); PG8_BAR; PG8_SCHED;
;             PG8_LDB(B0, 1, 0); PG8_LDB(B1, 1, 1); PG8_SCHED; PG8_LDA(At, 1, 0); PG8_STAGE(PG8_SA(0, 1), a2 + hstep, voffA);
;             PG8_WAIT_V(8); PG8_WAIT_L(0); PG8_BAR; PG8_MMA(0, 0, At, B0); PG8_MMA(0, 1, At, B1); PG8_BAR; PG8_SCHED;
	s_setprio 1
	s_waitcnt lgkmcnt(0)
	v_mfma_f32_16x16x32_bf16 v[72:75], v[52:55], v[176:179], 0
	v_mfma_f32_16x16x32_bf16 v[72:75], v[56:59], v[180:183], v[72:75]
	v_mfma_f32_16x16x32_bf16 v[68:71], v[52:55], v[190:193], 0
	v_mfma_f32_16x16x32_bf16 v[68:71], v[56:59], v[194:197], v[68:71]
	v_mfma_f32_16x16x32_bf16 v[48:51], v[52:55], v[198:201], 0
	v_mfma_f32_16x16x32_bf16 v[48:51], v[56:59], v[210:213], v[48:51]
	v_mfma_f32_16x16x32_bf16 v[40:43], v[52:55], v[214:217], 0
	v_mfma_f32_16x16x32_bf16 v[40:43], v[56:59], v[218:221], v[40:43]
	v_mfma_f32_16x16x32_bf16 v[36:39], v[76:79], v[214:217], 0
	v_mfma_f32_16x16x32_bf16 v[36:39], v[80:83], v[218:221], v[36:39]
	v_mfma_f32_16x16x32_bf16 v[44:47], v[76:79], v[198:201], 0
	v_mfma_f32_16x16x32_bf16 v[44:47], v[80:83], v[210:213], v[44:47]
	v_mfma_f32_16x16x32_bf16 v[60:63], v[76:79], v[190:193], 0
	v_mfma_f32_16x16x32_bf16 v[60:63], v[80:83], v[194:197], v[60:63]
	v_mfma_f32_16x16x32_bf16 v[64:67], v[76:79], v[176:179], 0
	v_mfma_f32_16x16x32_bf16 v[64:67], v[80:83], v[180:183], v[64:67]
	s_setprio 0
	s_setprio 1
	v_mfma_f32_16x16x32_bf16 v[32:35], v[116:119], v[176:179], 0
	v_mfma_f32_16x16x32_bf16 v[32:35], v[120:123], v[180:183], v[32:35]
	v_mfma_f32_16x16x32_bf16 v[28:31], v[116:119], v[190:193], 0
	v_mfma_f32_16x16x32_bf16 v[28:31], v[120:123], v[194:197], v[28:31]
	v_mfma_f32_16x16x32_bf16 v[16:19], v[116:119], v[198:201], 0
	v_mfma_f32_16x16x32_bf16 v[16:19], v[120:123], v[210:213], v[16:19]
	v_mfma_f32_16x16x32_bf16 v[8:11], v[116:119], v[214:217], 0
	v_mfma_f32_16x16x32_bf16 v[8:11], v[120:123], v[218:221], v[8:11]
	v_mfma_f32_16x16x32_bf16 v[2:5], v[168:171], v[214:217], 0
	v_mfma_f32_16x16x32_bf16 v[2:5], v[172:175], v[218:221], v[2:5]
	v_mfma_f32_16x16x32_bf16 v[12:15], v[168:171], v[198:201], 0
	v_mfma_f32_16x16x32_bf16 v[12:15], v[172:175], v[210:213], v[12:15]
	v_mfma_f32_16x16x32_bf16 v[20:23], v[168:171], v[190:193], 0
	v_mfma_f32_16x16x32_bf16 v[20:23], v[172:175], v[194:197], v[20:23]
	v_mfma_f32_16x16x32_bf16 v[24:27], v[168:171], v[176:179], 0
	v_mfma_f32_16x16x32_bf16 v[24:27], v[172:175], v[180:183], v[24:27]
	s_setprio 0
	s_barrier
	s_add_i32 s10, 0, 0x18000
	v_add_u32_e32 v0, s10, v188
	s_add_i32 s11, 0, 0x1c000
	ds_read_b128 v[52:55], v0
	ds_read_b128 v[56:59], v0 offset:1024
	ds_read_b128 v[76:79], v0 offset:2048
	ds_read_b128 v[80:83], v0 offset:3072
	v_add_u32_e32 v0, s11, v188
	ds_read_b128 v[116:119], v0
	ds_read_b128 v[120:123], v0 offset:1024
	ds_read_b128 v[168:171], v0 offset:2048
	ds_read_b128 v[172:175], v0 offset:3072
	s_add_u32 s8, vcc_lo, 0x80000
	s_addc_u32 s9, vcc_hi, 0
	s_mov_b32 m0, s13
	v_lshl_add_u64 v[6:7], s[8:9], 0, v[156:157]
	ds_read_b128 v[176:179], v189 offset:32768
	ds_read_b128 v[180:183], v189 offset:33792
	ds_read_b128 v[190:193], v189 offset:34816
	ds_read_b128 v[194:197], v189 offset:35840
	ds_read_b128 v[198:201], v189 offset:36864
	ds_read_b128 v[210:213], v189 offset:37888
	ds_read_b128 v[214:217], v189 offset:38912
	ds_read_b128 v[218:221], v189 offset:39936
	global_load_lds_dwordx4 v[6:7], off
	v_lshl_add_u64 v[6:7], s[8:9], 0, v[160:161]
	s_mov_b32 m0, s66
	s_nop 0
	global_load_lds_dwordx4 v[6:7], off
	s_waitcnt vmcnt(8)
	s_waitcnt lgkmcnt(0)
	s_barrier
	s_setprio 1
	s_waitcnt lgkmcnt(0)
	v_mfma_f32_16x16x32_bf16 v[152:155], v[52:55], v[176:179], v[152:155]
	v_mfma_f32_16x16x32_bf16 v[152:155], v[56:59], v[180:183], v[152:155]
	v_mfma_f32_16x16x32_bf16 v[148:151], v[52:55], v[190:193], v[148:151]
	v_mfma_f32_16x16x32_bf16 v[148:151], v[56:59], v[194:197], v[148:151]
	v_mfma_f32_16x16x32_bf16 v[136:139], v[52:55], v[198:201], v[136:139]
	v_mfma_f32_16x16x32_bf16 v[136:139], v[56:59], v[210:213], v[136:139]
	v_mfma_f32_16x16x32_bf16 v[128:131], v[52:55], v[214:217], v[128:131]
	v_mfma_f32_16x16x32_bf16 v[128:131], v[56:59], v[218:221], v[128:131]
	v_mfma_f32_16x16x32_bf16 v[124:127], v[76:79], v[214:217], v[124:127]
	v_mfma_f32_16x16x32_bf16 v[124:127], v[80:83], v[218:221], v[124:127]
	v_mfma_f32_16x16x32_bf16 v[132:135], v[76:79], v[198:201], v[132:135]
	v_mfma_f32_16x16x32_bf16 v[132:135], v[80:83], v[210:213], v[132:135]
	v_mfma_f32_16x16x32_bf16 v[140:143], v[76:79], v[190:193], v[140:143]
	v_mfma_f32_16x16x32_bf16 v[140:143], v[80:83], v[194:197], v[140:143]
	v_mfma_f32_16x16x32_bf16 v[144:147], v[76:79], v[176:179], v[144:147]
	v_mfma_f32_16x16x32_bf16 v[144:147], v[80:83], v[180:183], v[144:147]
	s_setprio 0
	s_setprio 1
	v_mfma_f32_16x16x32_bf16 v[112:115], v[116:119], v[176:179], v[112:115]
	v_mfma_f32_16x16x32_bf16 v[112:115], v[120:123], v[180:183], v[112:115]
	v_mfma_f32_16x16x32_bf16 v[108:111], v[116:119], v[190:193], v[108:111]
	v_mfma_f32_16x16x32_bf16 v[108:111], v[120:123], v[194:197], v[108:111]
	v_mfma_f32_16x16x32_bf16 v[96:99], v[116:119], v[198:201], v[96:99]
	v_mfma_f32_16x16x32_bf16 v[96:99], v[120:123], v[210:213], v[96:99]
	v_mfma_f32_16x16x32_bf16 v[88:91], v[116:119], v[214:217], v[88:91]
	v_mfma_f32_16x16x32_bf16 v[88:91], v[120:123], v[218:221], v[88:91]
	v_mfma_f32_16x16x32_bf16 v[84:87], v[168:171], v[214:217], v[84:87]
	v_mfma_f32_16x16x32_bf16 v[84:87], v[172:175], v[218:221], v[84:87]
	v_mfma_f32_16x16x32_bf16 v[92:95], v[168:171], v[198:201], v[92:95]
	v_mfma_f32_16x16x32_bf16 v[92:95], v[172:175], v[210:213], v[92:95]
	v_mfma_f32_16x16x32_bf16 v[100:103], v[168:171], v[190:193], v[100:103]
	v_mfma_f32_16x16x32_bf16 v[100:103], v[172:175], v[194:197], v[100:103]
	v_mfma_f32_16x16x32_bf16 v[104:107], v[168:171], v[176:179], v[104:107]
	v_mfma_f32_16x16x32_bf16 v[104:107], v[172:175], v[180:183], v[104:107]
	s_setprio 0
	s_barrier
; #define PG8_STAGE(bufoff, gbase, voff) do { _Pragma("unroll") for (int _i = 0; _i < 2; ++_i) \
;         __builtin_amdgcn_global_load_lds((const unsigned*)((const char*)(gbase) + (voff)[_i]), (PG8_LAS unsigned*)(lds + (bufoff) + ldsw + _i * 8192), 16, 0, 0); } while (0)
; #define PG8_LDA(dst, b, h) do { _Pragma("unroll") for (int m = 0; m < 4; ++m) _Pragma("unroll") for (int k = 0; k < 2; ++k) dst[m][k] = *(const PG8_LAS bf16x8*)(lds + PG8_SA(b, h) + aoff + m * 2048 + k * 1024); } while (0)
; #define PG8_LDB(dst, b, h) do { _Pragma("unroll") for (int n = 0; n < 2; ++n) _Pragma("unroll") for (int k = 0; k < 2; ++k) dst[n][k] = *(const PG8_LAS bf16x8*)(lds + PG8_SB(b, h) + boff + n * 2048 + k * 1024); } while (0)
; template <class Epi, class Sched, bool ALIGN_EPI = false, bool SP2 = false>
; __device__ __forceinline__ void gemm_phase(PG8_LAS unsigned char* lds, const Gemm g, const Sched& S, const Epi& E) {
;     ...
;         for (int t = 0; t < nt; t += 2) {
;             const bool last = (t == nt - 2);
;             const char* a1 = cA + (size_t)(t + 1) * kstep;
;             const char* a2 = last ? nA : cA + (size_t)(t + 2) * kstep; const char* b2 = last ? nB : cB + (size_t)(t + 2) * kstep;
;             const char* a3 = a2 + kstep; const char* b3 = b2 + kstep;
;             if (last && has_next) S.a_ready(nxt);
;             if constexpr (SP2) {
;             PG8_LDB(B0, 0, 0); PG8_LDB(B1, 0, 1); PG8_SCHED; PG8_LDA(At, 0, 0); PG8_STAGE(PG8_SA(1, 1), a1 + hstep, voffA);
;             PG8_WAIT_V(8); PG8_WAIT_L(0); PG8_BAR; PG8_MMA(0, 0, At, B0); PG8_MMA(0, 1, At, B1); PG8_BAR; PG8_SCHED;
;             PG8_LDA(At, 0, 1); PG8_STAGE(PG8_SB(0, 0), b2, voffB); PG8_STAGE(PG8_SB(0, 1), b2 + hstep, voffB); PG8_STAGE(PG8_SA(0, 0), a2, voffA);
;             PG8_WAIT_V(8); PG8_WAIT_L(0); PG8_BAR; PG8_MMA(1, 0, At, B0); PG8_MMA(1, 1, At, B1); PG8_BAR; PG8_SCHED;
;             PG8_LDB(B0, 1, 0); PG8_LDB(B1, 1, 1); PG8_SCHED; PG8_LDA(At, 1, 0); PG8_STAGE(PG8_SA(0, 1), a2 + hstep, voffA);
;             PG8_WAIT_V(8); PG8_WAIT_L(0); PG8_BAR; PG8_MMA(0, 0, At, B0); PG8_MMA(0, 1, At, B1); PG8_BAR; PG8_SCHED;
;             PG8_LDA(At, 1, 1); PG8_STAGE(PG8_SB(1, 0), b3, voffB); PG8_STAGE(PG8_SB(1, 1), b3 + hstep, voffB); PG8_STAGE(PG8_SA(1, 0), a3, voffA);
;             PG8_WAIT_V(8); PG8_WAIT_L(0); PG8_BAR; PG8_MMA(1, 0, At, B0); PG8_MMA(1, 1, At, B1); PG8_BAR; PG8_SCHED;
	s_add_i32 s8, s10, s80
	v_lshl_add_u64 v[6:7], v[184:185], 0, s[92:93]
	s_mov_b32 m0, s8
	ds_read_b128 v[176:179], v189 offset:49152
	ds_read_b128 v[180:183], v189 offset:50176
	ds_read_b128 v[190:193], v189 offset:51200
	ds_read_b128 v[194:197], v189 offset:52224
	ds_read_b128 v[198:201], v189 offset:53248
	ds_read_b128 v[210:213], v189 offset:54272
	ds_read_b128 v[214:217], v189 offset:55296
	ds_read_b128 v[218:221], v189 offset:56320
	global_load_lds_dwordx4 v[6:7], off
	s_add_i32 m0, s8, 0x2000
	s_add_u32 s8, s70, 0x80080
	v_lshl_add_u64 v[6:7], v[206:207], 0, s[92:93]
	s_addc_u32 s9, s71, 0
	s_add_i32 s10, s11, s80
	global_load_lds_dwordx4 v[6:7], off
	v_lshl_add_u64 v[6:7], s[8:9], 0, v[158:159]
	s_mov_b32 m0, s10
	s_nop 0
	global_load_lds_dwordx4 v[6:7], off
	v_lshl_add_u64 v[6:7], s[8:9], 0, v[162:163]
	s_add_i32 m0, s10, 0x2000
	s_nop 0
	global_load_lds_dwordx4 v[6:7], off
	v_lshl_add_u64 v[6:7], v[222:223], 0, s[92:93]
	s_mov_b32 m0, s67
	s_nop 0
	global_load_lds_dwordx4 v[6:7], off
	v_lshl_add_u64 v[6:7], v[224:225], 0, s[92:93]
	s_mov_b32 m0, s81
	s_nop 0
	global_load_lds_dwordx4 v[6:7], off
	s_waitcnt vmcnt(8)
	s_waitcnt lgkmcnt(0)
	s_barrier
	s_setprio 1
	s_waitcnt lgkmcnt(0)
	v_mfma_f32_16x16x32_bf16 v[72:75], v[52:55], v[176:179], v[72:75]
	v_mfma_f32_16x16x32_bf16 v[72:75], v[56:59], v[180:183], v[72:75]
	v_mfma_f32_16x16x32_bf16 v[68:71], v[52:55], v[190:193], v[68:71]
	v_mfma_f32_16x16x32_bf16 v[68:71], v[56:59], v[194:197], v[68:71]
	v_mfma_f32_16x16x32_bf16 v[48:51], v[52:55], v[198:201], v[48:51]
	v_mfma_f32_16x16x32_bf16 v[48:51], v[56:59], v[210:213], v[48:51]
	v_mfma_f32_16x16x32_bf16 v[40:43], v[52:55], v[214:217], v[40:43]
	v_mfma_f32_16x16x32_bf16 v[40:43], v[56:59], v[218:221], v[40:43]
	v_mfma_f32_16x16x32_bf16 v[36:39], v[76:79], v[214:217], v[36:39]
	v_mfma_f32_16x16x32_bf16 v[36:39], v[80:83], v[218:221], v[36:39]
	v_mfma_f32_16x16x32_bf16 v[44:47], v[76:79], v[198:201], v[44:47]
	v_mfma_f32_16x16x32_bf16 v[44:47], v[80:83], v[210:213], v[44:47]
	v_mfma_f32_16x16x32_bf16 v[60:63], v[76:79], v[190:193], v[60:63]
	v_mfma_f32_16x16x32_bf16 v[60:63], v[80:83], v[194:197], v[60:63]
	v_mfma_f32_16x16x32_bf16 v[64:67], v[76:79], v[176:179], v[64:67]
	v_mfma_f32_16x16x32_bf16 v[64:67], v[80:83], v[180:183], v[64:67]
	s_setprio 0
	s_setprio 1
	v_mfma_f32_16x16x32_bf16 v[32:35], v[116:119], v[176:179], v[32:35]
	v_mfma_f32_16x16x32_bf16 v[24:27], v[168:171], v[176:179], v[24:27]
	v_mfma_f32_16x16x32_bf16 v[28:31], v[116:119], v[190:193], v[28:31]
	v_mfma_f32_16x16x32_bf16 v[20:23], v[168:171], v[190:193], v[20:23]
	v_mfma_f32_16x16x32_bf16 v[16:19], v[116:119], v[198:201], v[16:19]
	v_mfma_f32_16x16x32_bf16 v[12:15], v[168:171], v[198:201], v[12:15]
	v_mfma_f32_16x16x32_bf16 v[6:9], v[116:119], v[214:217], v[8:11]
	v_mfma_f32_16x16x32_bf16 v[2:5], v[168:171], v[214:217], v[2:5]
	v_mfma_f32_16x16x32_bf16 v[32:35], v[120:123], v[180:183], v[32:35]
	v_mfma_f32_16x16x32_bf16 v[24:27], v[172:175], v[180:183], v[24:27]
	v_mfma_f32_16x16x32_bf16 v[28:31], v[120:123], v[194:197], v[28:31]
	v_mfma_f32_16x16x32_bf16 v[20:23], v[172:175], v[194:197], v[20:23]
	v_mfma_f32_16x16x32_bf16 v[16:19], v[120:123], v[210:213], v[16:19]
	v_mfma_f32_16x16x32_bf16 v[12:15], v[172:175], v[210:213], v[12:15]
	v_mfma_f32_16x16x32_bf16 v[8:11], v[120:123], v[218:221], v[6:9]
	v_mfma_f32_16x16x32_bf16 v[4:7], v[172:175], v[218:221], v[2:5]
	s_setprio 0
	s_barrier
	s_add_i32 s4, s4, 2
	s_add_u32 s97, s97, 0x100
	s_addc_u32 s96, s96, 0
	s_cmp_gt_u32 s4, 29
	s_mov_b64 s[8:9], s[68:69]
	s_cbranch_scc0 .LBB0_327
	s_branch .Lpeelx327
.LBB0_327:
	s_add_u32 s68, s8, 0x100
	s_addc_u32 s69, s9, 0
	s_add_i32 s84, 0, 0x10000
	s_cmp_eq_u32 s4, 28
	s_cselect_b32 vcc_hi, s1, s69
	s_cselect_b32 vcc_lo, s5, s68
	v_add_u32_e32 v0, s84, v188
	s_cselect_b32 s71, s7, s96
	s_cselect_b32 s70, s85, s97
	s_add_i32 s10, 0, 0x14000
	ds_read_b128 v[52:55], v0
	ds_read_b128 v[56:59], v0 offset:1024
	ds_read_b128 v[76:79], v0 offset:2048
	ds_read_b128 v[80:83], v0 offset:3072
	v_add_u32_e32 v0, s10, v188
	ds_read_b128 v[116:119], v0
	ds_read_b128 v[120:123], v0 offset:1024
	ds_read_b128 v[168:171], v0 offset:2048
	ds_read_b128 v[172:175], v0 offset:3072
	v_lshl_add_u64 v[2:3], s[8:9], 0, v[164:165]
	s_add_i32 m0, s58, 0xc000
	ds_read_b128 v[176:179], v189
	ds_read_b128 v[180:183], v189 offset:1024
	ds_read_b128 v[190:193], v189 offset:2048
	ds_read_b128 v[194:197], v189 offset:3072
	ds_read_b128 v[198:201], v189 offset:4096
	ds_read_b128 v[210:213], v189 offset:5120
	ds_read_b128 v[214:217], v189 offset:6144
	ds_read_b128 v[218:221], v189 offset:7168
	global_load_lds_dwordx4 v[2:3], off
	v_lshl_add_u64 v[2:3], s[8:9], 0, v[166:167]
	s_add_i32 m0, s58, 0xe000
	s_nop 0
	global_load_lds_dwordx4 v[2:3], off
	s_waitcnt vmcnt(8)
	s_waitcnt lgkmcnt(0)
	s_barrier
; #define PG8_STAGE(bufoff, gbase, voff) do { _Pragma("unroll") for (int _i = 0; _i < 2; ++_i) \
;         __builtin_amdgcn_global_load_lds((const unsigned*)((const char*)(gbase) + (voff)[_i]), (PG8_LAS unsigned*)(lds + (bufoff) + ldsw + _i * 8192), 16, 0, 0); } while (0)
; #define PG8_LDA(dst, b, h) do { _Pragma("unroll") for (int m = 0; m < 4; ++m) _Pragma("unroll") for (int k = 0; k < 2; ++k) dst[m][k] = *(const PG8_LAS bf16x8*)(lds + PG8_SA(b, h) + aoff + m * 2048 + k * 1024); } while (0)
; #define PG8_MMA(ai, bj, At, Bt) do { __builtin_amdgcn_s_setprio(1); _Pragma("unroll") for (int m = 0; m < 4; ++m) _Pragma("unroll") for (int n = 0; n < 2; ++n) _Pragma("unroll") for (int k = 0; k < 2; ++k) \
;         acc[ai][bj][m][n] = mma16<Epi::I8>(Bt[n][k], At[m][k], acc[ai][bj][m][n]); __builtin_amdgcn_s_setprio(0); } while (0)
; #define PG8_WAIT_V(n) asm volatile("s_waitcnt vmcnt(" #n ")" ::: "memory")
; #define PG8_WAIT_L(n) asm volatile("s_waitcnt lgkmcnt(" #n ")" ::: "memory")
; #define PG8_BAR __builtin_amdgcn_s_barrier()
; #define PG8_SCHED __builtin_amdgcn_sched_barrier(0)
; template <class Epi, class Sched, bool ALIGN_EPI = false, bool SP2 = false>
; __device__ __forceinline__ void gemm_phase(PG8_LAS unsigned char* lds, const Gemm g, const Sched& S, const Epi& E) {
;     ...
;             PG8_WAIT_V(8); PG8_WAIT_L(0); PG8_BAR; PG8_MMA(0, 0, At, B0); PG8_MMA(0, 1, At, B1); PG8_BAR; PG8_SCHED;
;             PG8_LDA(At, 0, 1); PG8_STAGE(PG8_SB(0, 0), b2, voffB); PG8_STAGE(PG8_SB(0, 1), b2 + hstep, voffB); PG8_STAGE(PG8_SA(0, 0), a2, voffA);
;             PG8_WAIT_V(8); PG8_WAIT_L(0); PG8_BAR; PG8_MMA(1, 0, At, B0); PG8_MMA(1, 1, At, B1); PG8_BAR; PG8_SCHED;
	s_setprio 1
	s_waitcnt lgkmcnt(0)
	v_mfma_f32_16x16x32_bf16 v[152:155], v[52:55], v[176:179], v[152:155]
	v_mfma_f32_16x16x32_bf16 v[152:155], v[56:59], v[180:183], v[152:155]
	v_mfma_f32_16x16x32_bf16 v[148:151], v[52:55], v[190:193], v[148:151]
	v_mfma_f32_16x16x32_bf16 v[148:151], v[56:59], v[194:197], v[148:151]
	v_mfma_f32_16x16x32_bf16 v[136:139], v[52:55], v[198:201], v[136:139]
	v_mfma_f32_16x16x32_bf16 v[136:139], v[56:59], v[210:213], v[136:139]
	v_mfma_f32_16x16x32_bf16 v[128:131], v[52:55], v[214:217], v[128:131]
	v_mfma_f32_16x16x32_bf16 v[128:131], v[56:59], v[218:221], v[128:131]
	v_mfma_f32_16x16x32_bf16 v[124:127], v[76:79], v[214:217], v[124:127]
	v_mfma_f32_16x16x32_bf16 v[124:127], v[80:83], v[218:221], v[124:127]
	v_mfma_f32_16x16x32_bf16 v[132:135], v[76:79], v[198:201], v[132:135]
	v_mfma_f32_16x16x32_bf16 v[132:135], v[80:83], v[210:213], v[132:135]
	v_mfma_f32_16x16x32_bf16 v[140:143], v[76:79], v[190:193], v[140:143]
	v_mfma_f32_16x16x32_bf16 v[140:143], v[80:83], v[194:197], v[140:143]
	v_mfma_f32_16x16x32_bf16 v[144:147], v[76:79], v[176:179], v[144:147]
	v_mfma_f32_16x16x32_bf16 v[144:147], v[80:83], v[180:183], v[144:147]
	s_setprio 0
	s_setprio 1
	v_mfma_f32_16x16x32_bf16 v[112:115], v[116:119], v[176:179], v[112:115]
	v_mfma_f32_16x16x32_bf16 v[112:115], v[120:123], v[180:183], v[112:115]
	v_mfma_f32_16x16x32_bf16 v[108:111], v[116:119], v[190:193], v[108:111]
	v_mfma_f32_16x16x32_bf16 v[108:111], v[120:123], v[194:197], v[108:111]
	v_mfma_f32_16x16x32_bf16 v[96:99], v[116:119], v[198:201], v[96:99]
	v_mfma_f32_16x16x32_bf16 v[96:99], v[120:123], v[210:213], v[96:99]
	v_mfma_f32_16x16x32_bf16 v[88:91], v[116:119], v[214:217], v[88:91]
	v_mfma_f32_16x16x32_bf16 v[88:91], v[120:123], v[218:221], v[88:91]
	v_mfma_f32_16x16x32_bf16 v[84:87], v[168:171], v[214:217], v[84:87]
	v_mfma_f32_16x16x32_bf16 v[84:87], v[172:175], v[218:221], v[84:87]
	v_mfma_f32_16x16x32_bf16 v[92:95], v[168:171], v[198:201], v[92:95]
	v_mfma_f32_16x16x32_bf16 v[92:95], v[172:175], v[210:213], v[92:95]
	v_mfma_f32_16x16x32_bf16 v[100:103], v[168:171], v[190:193], v[100:103]
	v_mfma_f32_16x16x32_bf16 v[100:103], v[172:175], v[194:197], v[100:103]
	v_mfma_f32_16x16x32_bf16 v[104:107], v[168:171], v[176:179], v[104:107]
	v_mfma_f32_16x16x32_bf16 v[104:107], v[172:175], v[180:183], v[104:107]
	s_setprio 0
	s_barrier
	s_add_i32 s8, s84, s80
	v_lshl_add_u64 v[184:185], s[70:71], 0, v[158:159]
	s_mov_b32 m0, s8
	ds_read_b128 v[176:179], v189 offset:16384
	ds_read_b128 v[180:183], v189 offset:17408
	ds_read_b128 v[190:193], v189 offset:18432
	ds_read_b128 v[194:197], v189 offset:19456
	ds_read_b128 v[198:201], v189 offset:20480
	ds_read_b128 v[210:213], v189 offset:21504
	ds_read_b128 v[214:217], v189 offset:22528
	ds_read_b128 v[218:221], v189 offset:23552
	global_load_lds_dwordx4 v[184:185], off
	s_add_i32 m0, s8, 0x2000
	s_add_u32 s8, s70, 0x80000
	v_lshl_add_u64 v[206:207], s[70:71], 0, v[162:163]
	s_addc_u32 s9, s71, 0
	s_add_i32 s10, s10, s80
	global_load_lds_dwordx4 v[206:207], off
	v_lshl_add_u64 v[2:3], s[8:9], 0, v[158:159]
	s_mov_b32 m0, s10
	v_lshl_add_u64 v[222:223], vcc, 0, v[156:157]
	global_load_lds_dwordx4 v[2:3], off
	v_lshl_add_u64 v[2:3], s[8:9], 0, v[162:163]
	s_add_i32 m0, s10, 0x2000
	v_lshl_add_u64 v[224:225], vcc, 0, v[160:161]
	global_load_lds_dwordx4 v[2:3], off
	s_mov_b32 m0, s58
	s_nop 0
	global_load_lds_dwordx4 v[222:223], off
	s_mov_b32 m0, s12
	s_nop 0
	global_load_lds_dwordx4 v[224:225], off
	s_waitcnt vmcnt(8)
	s_waitcnt lgkmcnt(0)
	s_barrier
	s_setprio 1
	s_waitcnt lgkmcnt(0)
	v_mfma_f32_16x16x32_bf16 v[72:75], v[52:55], v[176:179], v[72:75]
	v_mfma_f32_16x16x32_bf16 v[72:75], v[56:59], v[180:183], v[72:75]
	v_mfma_f32_16x16x32_bf16 v[68:71], v[52:55], v[190:193], v[68:71]
	v_mfma_f32_16x16x32_bf16 v[68:71], v[56:59], v[194:197], v[68:71]
	v_mfma_f32_16x16x32_bf16 v[48:51], v[52:55], v[198:201], v[48:51]
	v_mfma_f32_16x16x32_bf16 v[48:51], v[56:59], v[210:213], v[48:51]
	v_mfma_f32_16x16x32_bf16 v[40:43], v[52:55], v[214:217], v[40:43]
	v_mfma_f32_16x16x32_bf16 v[40:43], v[56:59], v[218:221], v[40:43]
	v_mfma_f32_16x16x32_bf16 v[36:39], v[76:79], v[214:217], v[36:39]
	v_mfma_f32_16x16x32_bf16 v[36:39], v[80:83], v[218:221], v[36:39]
	v_mfma_f32_16x16x32_bf16 v[44:47], v[76:79], v[198:201], v[44:47]
	v_mfma_f32_16x16x32_bf16 v[44:47], v[80:83], v[210:213], v[44:47]
	v_mfma_f32_16x16x32_bf16 v[60:63], v[76:79], v[190:193], v[60:63]
	v_mfma_f32_16x16x32_bf16 v[60:63], v[80:83], v[194:197], v[60:63]
	v_mfma_f32_16x16x32_bf16 v[64:67], v[76:79], v[176:179], v[64:67]
	v_mfma_f32_16x16x32_bf16 v[64:67], v[80:83], v[180:183], v[64:67]
	s_setprio 0
	s_setprio 1
	v_mfma_f32_16x16x32_bf16 v[32:35], v[116:119], v[176:179], v[32:35]
	v_mfma_f32_16x16x32_bf16 v[24:27], v[168:171], v[176:179], v[24:27]
	v_mfma_f32_16x16x32_bf16 v[28:31], v[116:119], v[190:193], v[28:31]
	v_mfma_f32_16x16x32_bf16 v[20:23], v[168:171], v[190:193], v[20:23]
	v_mfma_f32_16x16x32_bf16 v[16:19], v[116:119], v[198:201], v[16:19]
	v_mfma_f32_16x16x32_bf16 v[12:15], v[168:171], v[198:201], v[12:15]
	v_mfma_f32_16x16x32_bf16 v[8:11], v[116:119], v[214:217], v[8:11]
	v_mfma_f32_16x16x32_bf16 v[2:5], v[168:171], v[214:217], v[4:7]
	v_mfma_f32_16x16x32_bf16 v[32:35], v[120:123], v[180:183], v[32:35]
	v_mfma_f32_16x16x32_bf16 v[24:27], v[172:175], v[180:183], v[24:27]
	v_mfma_f32_16x16x32_bf16 v[28:31], v[120:123], v[194:197], v[28:31]
	v_mfma_f32_16x16x32_bf16 v[20:23], v[172:175], v[194:197], v[20:23]
	v_mfma_f32_16x16x32_bf16 v[16:19], v[120:123], v[210:213], v[16:19]
	v_mfma_f32_16x16x32_bf16 v[12:15], v[172:175], v[210:213], v[12:15]
	v_mfma_f32_16x16x32_bf16 v[8:11], v[120:123], v[218:221], v[8:11]
	v_mfma_f32_16x16x32_bf16 v[2:5], v[172:175], v[218:221], v[2:5]
	s_setprio 0
	s_barrier
; #define PG8_STAGE(bufoff, gbase, voff) do { _Pragma("unroll") for (int _i = 0; _i < 2; ++_i) \
;         __builtin_amdgcn_global_load_lds((const unsigned*)((const char*)(gbase) + (voff)[_i]), (PG8_LAS unsigned*)(lds + (bufoff) + ldsw + _i * 8192), 16, 0, 0); } while (0)
; #define PG8_LDA(dst, b, h) do { _Pragma("unroll") for (int m = 0; m < 4; ++m) _Pragma("unroll") for (int k = 0; k < 2; ++k) dst[m][k] = *(const PG8_LAS bf16x8*)(lds + PG8_SA(b, h) + aoff + m * 2048 + k * 1024); } while (0)
; #define PG8_LDB(dst, b, h) do { _Pragma("unroll") for (int n = 0; n < 2; ++n) _Pragma("unroll") for (int k = 0; k < 2; ++k) dst[n][k] = *(const PG8_LAS bf16x8*)(lds + PG8_SB(b, h) + boff + n * 2048 + k * 1024); } while (0)
; #define PG8_MMA(ai, bj, At, Bt) do { __builtin_amdgcn_s_setprio(1); _Pragma("unroll") for (int m = 0; m < 4; ++m) _Pragma("unroll") for (int n = 0; n < 2; ++n) _Pragma("unroll") for (int k = 0; k < 2; ++k) \
;         acc[ai][bj][m][n] = mma16<Epi::I8>(Bt[n][k], At[m][k], acc[ai][bj][m][n]); __builtin_amdgcn_s_setprio(0); } while (0)
; #define PG8_WAIT_V(n) asm volatile("s_waitcnt vmcnt(" #n ")" ::: "memory")
; #define PG8_WAIT_L(n) asm volatile("s_waitcnt lgkmcnt(" #n ")" ::: "memory")
; #define PG8_BAR __builtin_amdgcn_s_barrier()
; #define PG8_SCHED __builtin_amdgcn_sched_barrier(0)
; template <class Epi, class Sched, bool ALIGN_EPI = false, bool SP2 = false>
; __device__ __forceinline__ void gemm_phase(PG8_LAS unsigned char* lds, const Gemm g, const Sched& S, const Epi& E) {
;     ...
;         for (int t = 0; t < nt; t += 2) {
;     ...
;             PG8_LDB(B0, 1, 0); PG8_LDB(B1, 1, 1); PG8_SCHED; PG8_LDA(At, 1, 0); PG8_STAGE(PG8_SA(0, 1), a2 + hstep, voffA);
;             PG8_WAIT_V(8); PG8_WAIT_L(0); PG8_BAR; PG8_MMA(0, 0, At, B0); PG8_MMA(0, 1, At, B1); PG8_BAR; PG8_SCHED;
;             PG8_LDA(At, 1, 1); PG8_STAGE(PG8_SB(1, 0), b3, voffB); PG8_STAGE(PG8_SB(1, 1), b3 + hstep, voffB); PG8_STAGE(PG8_SA(1, 0), a3, voffA);
;             PG8_WAIT_V(8); PG8_WAIT_L(0); PG8_BAR; PG8_MMA(1, 0, At, B0); PG8_MMA(1, 1, At, B1); PG8_BAR; PG8_SCHED;
	s_add_i32 s10, 0, 0x18000
	v_add_u32_e32 v0, s10, v188
	s_add_i32 s11, 0, 0x1c000
	ds_read_b128 v[52:55], v0
	ds_read_b128 v[56:59], v0 offset:1024
	ds_read_b128 v[76:79], v0 offset:2048
	ds_read_b128 v[80:83], v0 offset:3072
	v_add_u32_e32 v0, s11, v188
	ds_read_b128 v[116:119], v0
	ds_read_b128 v[120:123], v0 offset:1024
	ds_read_b128 v[168:171], v0 offset:2048
	ds_read_b128 v[172:175], v0 offset:3072
	s_add_u32 s8, vcc_lo, 0x80000
	s_addc_u32 s9, vcc_hi, 0
	s_mov_b32 m0, s13
	v_lshl_add_u64 v[6:7], s[8:9], 0, v[156:157]
	ds_read_b128 v[176:179], v189 offset:32768
	ds_read_b128 v[180:183], v189 offset:33792
	ds_read_b128 v[190:193], v189 offset:34816
	ds_read_b128 v[194:197], v189 offset:35840
	ds_read_b128 v[198:201], v189 offset:36864
	ds_read_b128 v[210:213], v189 offset:37888
	ds_read_b128 v[214:217], v189 offset:38912
	ds_read_b128 v[218:221], v189 offset:39936
	global_load_lds_dwordx4 v[6:7], off
	v_lshl_add_u64 v[6:7], s[8:9], 0, v[160:161]
	s_mov_b32 m0, s66
	s_nop 0
	global_load_lds_dwordx4 v[6:7], off
	s_waitcnt vmcnt(8)
	s_waitcnt lgkmcnt(0)
	s_barrier
	s_setprio 1
	s_waitcnt lgkmcnt(0)
	v_mfma_f32_16x16x32_bf16 v[152:155], v[52:55], v[176:179], v[152:155]
	v_mfma_f32_16x16x32_bf16 v[152:155], v[56:59], v[180:183], v[152:155]
	v_mfma_f32_16x16x32_bf16 v[148:151], v[52:55], v[190:193], v[148:151]
	v_mfma_f32_16x16x32_bf16 v[148:151], v[56:59], v[194:197], v[148:151]
	v_mfma_f32_16x16x32_bf16 v[136:139], v[52:55], v[198:201], v[136:139]
	v_mfma_f32_16x16x32_bf16 v[136:139], v[56:59], v[210:213], v[136:139]
	v_mfma_f32_16x16x32_bf16 v[128:131], v[52:55], v[214:217], v[128:131]
	v_mfma_f32_16x16x32_bf16 v[128:131], v[56:59], v[218:221], v[128:131]
	v_mfma_f32_16x16x32_bf16 v[124:127], v[76:79], v[214:217], v[124:127]
	v_mfma_f32_16x16x32_bf16 v[124:127], v[80:83], v[218:221], v[124:127]
	v_mfma_f32_16x16x32_bf16 v[132:135], v[76:79], v[198:201], v[132:135]
	v_mfma_f32_16x16x32_bf16 v[132:135], v[80:83], v[210:213], v[132:135]
	v_mfma_f32_16x16x32_bf16 v[140:143], v[76:79], v[190:193], v[140:143]
	v_mfma_f32_16x16x32_bf16 v[140:143], v[80:83], v[194:197], v[140:143]
	v_mfma_f32_16x16x32_bf16 v[144:147], v[76:79], v[176:179], v[144:147]
	v_mfma_f32_16x16x32_bf16 v[144:147], v[80:83], v[180:183], v[144:147]
	s_setprio 0
	s_setprio 1
	v_mfma_f32_16x16x32_bf16 v[112:115], v[116:119], v[176:179], v[112:115]
	v_mfma_f32_16x16x32_bf16 v[112:115], v[120:123], v[180:183], v[112:115]
	v_mfma_f32_16x16x32_bf16 v[108:111], v[116:119], v[190:193], v[108:111]
	v_mfma_f32_16x16x32_bf16 v[108:111], v[120:123], v[194:197], v[108:111]
	v_mfma_f32_16x16x32_bf16 v[96:99], v[116:119], v[198:201], v[96:99]
	v_mfma_f32_16x16x32_bf16 v[96:99], v[120:123], v[210:213], v[96:99]
	v_mfma_f32_16x16x32_bf16 v[88:91], v[116:119], v[214:217], v[88:91]
	v_mfma_f32_16x16x32_bf16 v[88:91], v[120:123], v[218:221], v[88:91]
	v_mfma_f32_16x16x32_bf16 v[84:87], v[168:171], v[214:217], v[84:87]
	v_mfma_f32_16x16x32_bf16 v[84:87], v[172:175], v[218:221], v[84:87]
	v_mfma_f32_16x16x32_bf16 v[92:95], v[168:171], v[198:201], v[92:95]
	v_mfma_f32_16x16x32_bf16 v[92:95], v[172:175], v[210:213], v[92:95]
	v_mfma_f32_16x16x32_bf16 v[100:103], v[168:171], v[190:193], v[100:103]
	v_mfma_f32_16x16x32_bf16 v[100:103], v[172:175], v[194:197], v[100:103]
	v_mfma_f32_16x16x32_bf16 v[104:107], v[168:171], v[176:179], v[104:107]
	v_mfma_f32_16x16x32_bf16 v[104:107], v[172:175], v[180:183], v[104:107]
	s_setprio 0
	s_barrier
	s_add_i32 s8, s10, s80
	v_lshl_add_u64 v[6:7], v[184:185], 0, s[92:93]
	s_mov_b32 m0, s8
	ds_read_b128 v[176:179], v189 offset:49152
	ds_read_b128 v[180:183], v189 offset:50176
	ds_read_b128 v[190:193], v189 offset:51200
	ds_read_b128 v[194:197], v189 offset:52224
	ds_read_b128 v[198:201], v189 offset:53248
	ds_read_b128 v[210:213], v189 offset:54272
	ds_read_b128 v[214:217], v189 offset:55296
	ds_read_b128 v[218:221], v189 offset:56320
	global_load_lds_dwordx4 v[6:7], off
	s_add_i32 m0, s8, 0x2000
	s_add_u32 s8, s70, 0x80080
	v_lshl_add_u64 v[6:7], v[206:207], 0, s[92:93]
	s_addc_u32 s9, s71, 0
	s_add_i32 s10, s11, s80
	global_load_lds_dwordx4 v[6:7], off
	v_lshl_add_u64 v[6:7], s[8:9], 0, v[158:159]
	s_mov_b32 m0, s10
	s_nop 0
	global_load_lds_dwordx4 v[6:7], off
	v_lshl_add_u64 v[6:7], s[8:9], 0, v[162:163]
	s_add_i32 m0, s10, 0x2000
	s_nop 0
	global_load_lds_dwordx4 v[6:7], off
	v_lshl_add_u64 v[6:7], v[222:223], 0, s[92:93]
	s_mov_b32 m0, s67
	s_nop 0
	global_load_lds_dwordx4 v[6:7], off
	v_lshl_add_u64 v[6:7], v[224:225], 0, s[92:93]
	s_mov_b32 m0, s81
	s_nop 0
	global_load_lds_dwordx4 v[6:7], off
	s_waitcnt vmcnt(8)
	s_waitcnt lgkmcnt(0)
	s_barrier
	s_setprio 1
	s_waitcnt lgkmcnt(0)
	v_mfma_f32_16x16x32_bf16 v[72:75], v[52:55], v[176:179], v[72:75]
	v_mfma_f32_16x16x32_bf16 v[72:75], v[56:59], v[180:183], v[72:75]
	v_mfma_f32_16x16x32_bf16 v[68:71], v[52:55], v[190:193], v[68:71]
	v_mfma_f32_16x16x32_bf16 v[68:71], v[56:59], v[194:197], v[68:71]
	v_mfma_f32_16x16x32_bf16 v[48:51], v[52:55], v[198:201], v[48:51]
	v_mfma_f32_16x16x32_bf16 v[48:51], v[56:59], v[210:213], v[48:51]
	v_mfma_f32_16x16x32_bf16 v[40:43], v[52:55], v[214:217], v[40:43]
	v_mfma_f32_16x16x32_bf16 v[40:43], v[56:59], v[218:221], v[40:43]
	v_mfma_f32_16x16x32_bf16 v[36:39], v[76:79], v[214:217], v[36:39]
	v_mfma_f32_16x16x32_bf16 v[36:39], v[80:83], v[218:221], v[36:39]
	v_mfma_f32_16x16x32_bf16 v[44:47], v[76:79], v[198:201], v[44:47]
	v_mfma_f32_16x16x32_bf16 v[44:47], v[80:83], v[210:213], v[44:47]
	v_mfma_f32_16x16x32_bf16 v[60:63], v[76:79], v[190:193], v[60:63]
	v_mfma_f32_16x16x32_bf16 v[60:63], v[80:83], v[194:197], v[60:63]
	v_mfma_f32_16x16x32_bf16 v[64:67], v[76:79], v[176:179], v[64:67]
	v_mfma_f32_16x16x32_bf16 v[64:67], v[80:83], v[180:183], v[64:67]
	s_setprio 0
	s_setprio 1
	v_mfma_f32_16x16x32_bf16 v[32:35], v[116:119], v[176:179], v[32:35]
	v_mfma_f32_16x16x32_bf16 v[24:27], v[168:171], v[176:179], v[24:27]
	v_mfma_f32_16x16x32_bf16 v[28:31], v[116:119], v[190:193], v[28:31]
	v_mfma_f32_16x16x32_bf16 v[20:23], v[168:171], v[190:193], v[20:23]
	v_mfma_f32_16x16x32_bf16 v[16:19], v[116:119], v[198:201], v[16:19]
	v_mfma_f32_16x16x32_bf16 v[12:15], v[168:171], v[198:201], v[12:15]
	v_mfma_f32_16x16x32_bf16 v[6:9], v[116:119], v[214:217], v[8:11]
	v_mfma_f32_16x16x32_bf16 v[2:5], v[168:171], v[214:217], v[2:5]
	v_mfma_f32_16x16x32_bf16 v[32:35], v[120:123], v[180:183], v[32:35]
	v_mfma_f32_16x16x32_bf16 v[24:27], v[172:175], v[180:183], v[24:27]
	v_mfma_f32_16x16x32_bf16 v[28:31], v[120:123], v[194:197], v[28:31]
	v_mfma_f32_16x16x32_bf16 v[20:23], v[172:175], v[194:197], v[20:23]
	v_mfma_f32_16x16x32_bf16 v[16:19], v[120:123], v[210:213], v[16:19]
	v_mfma_f32_16x16x32_bf16 v[12:15], v[172:175], v[210:213], v[12:15]
	v_mfma_f32_16x16x32_bf16 v[8:11], v[120:123], v[218:221], v[6:9]
	v_mfma_f32_16x16x32_bf16 v[4:7], v[172:175], v[218:221], v[2:5]
	s_setprio 0
	s_barrier
	s_add_i32 s4, s4, 2
	s_add_u32 s97, s97, 0x100
	s_addc_u32 s96, s96, 0
	s_cmp_gt_u32 s4, 29
	s_mov_b64 s[8:9], s[68:69]
	s_cbranch_scc0 .LBB0_327

; #define PG8_STAGE(bufoff, gbase, voff) do { _Pragma("unroll") for (int _i = 0; _i < 2; ++_i) \
;         __builtin_amdgcn_global_load_lds((const unsigned*)((const char*)(gbase) + (voff)[_i]), (PG8_LAS unsigned*)(lds + (bufoff) + ldsw + _i * 8192), 16, 0, 0); } while (0)
; #define PG8_LDA(dst, b, h) do { _Pragma("unroll") for (int m = 0; m < 4; ++m) _Pragma("unroll") for (int k = 0; k < 2; ++k) dst[m][k] = *(const PG8_LAS bf16x8*)(lds + PG8_SA(b, h) + aoff + m * 2048 + k * 1024); } while (0)
; #define PG8_LDB(dst, b, h) do { _Pragma("unroll") for (int n = 0; n < 2; ++n) _Pragma("unroll") for (int k = 0; k < 2; ++k) dst[n][k] = *(const PG8_LAS bf16x8*)(lds + PG8_SB(b, h) + boff + n * 2048 + k * 1024); } while (0)
; #define PG8_MMA(ai, bj, At, Bt) do { __builtin_amdgcn_s_setprio(1); _Pragma("unroll") for (int m = 0; m < 4; ++m) _Pragma("unroll") for (int n = 0; n < 2; ++n) _Pragma("unroll") for (int k = 0; k < 2; ++k) \
;         acc[ai][bj][m][n] = mma16<Epi::I8>(Bt[n][k], At[m][k], acc[ai][bj][m][n]); __builtin_amdgcn_s_setprio(0); } while (0)
; #define PG8_WAIT_V(n) asm volatile("s_waitcnt vmcnt(" #n ")" ::: "memory")
; #define PG8_WAIT_L(n) asm volatile("s_waitcnt lgkmcnt(" #n ")" ::: "memory")
; #define PG8_BAR __builtin_amdgcn_s_barrier()
; #define PG8_SCHED __builtin_amdgcn_sched_barrier(0)
; template <class Epi, class Sched, bool ALIGN_EPI = false, bool SP2 = false>
; __device__ __forceinline__ void gemm_phase(PG8_LAS unsigned char* lds, const Gemm g, const Sched& S, const Epi& E) {
;     ...
;             PG8_LDB(B0, 0, 0); PG8_LDB(B1, 0, 1); PG8_SCHED; PG8_LDA(At, 0, 0); PG8_STAGE(PG8_SA(1, 1), a1 + hstep, voffA);
;             PG8_WAIT_V(8); PG8_WAIT_L(0); PG8_BAR; PG8_MMA(0, 0, At, B0); PG8_MMA(0, 1, At, B1); PG8_BAR; PG8_SCHED;
;             PG8_LDA(At, 0, 1); PG8_STAGE(PG8_SB(0, 0), b2, voffB); PG8_STAGE(PG8_SB(0, 1), b2 + hstep, voffB); PG8_STAGE(PG8_SA(0, 0), a2, voffA);
;             PG8_WAIT_V(8); PG8_WAIT_L(0); PG8_BAR; PG8_MMA(1, 0, At, B0); PG8_MMA(1, 1, At, B1); PG8_BAR; PG8_SCHED;
.Lpeel385:
	s_add_u32 s70, s8, 0x100
	s_addc_u32 s71, s9, 0
	s_add_i32 s84, 0, 0x10000
	s_cmp_eq_u32 s5, 12
	s_cselect_b32 vcc_hi, s1, s71
	s_cselect_b32 vcc_lo, s7, s70
	v_add_u32_e32 v0, s84, v214
	s_cselect_b32 s83, s69, s68
	s_cselect_b32 s82, s81, s85
	s_add_i32 s10, 0, 0x14000
	ds_read_b128 v[44:47], v0
	ds_read_b128 v[52:55], v0 offset:1024
	ds_read_b128 v[60:63], v0 offset:2048
	ds_read_b128 v[64:67], v0 offset:3072
	v_add_u32_e32 v0, s10, v214
	ds_read_b128 v[84:87], v0
	ds_read_b128 v[88:91], v0 offset:1024
	ds_read_b128 v[92:95], v0 offset:2048
	ds_read_b128 v[100:103], v0 offset:3072
	v_lshl_add_u64 v[2:3], s[8:9], 0, v[184:185]
	s_add_i32 m0, s13, 0xc000
	ds_read_b128 v[124:127], v215
	ds_read_b128 v[128:131], v215 offset:1024
	ds_read_b128 v[140:143], v215 offset:2048
	ds_read_b128 v[188:191], v215 offset:3072
	ds_read_b128 v[192:195], v215 offset:4096
	ds_read_b128 v[196:199], v215 offset:5120
	ds_read_b128 v[216:219], v215 offset:6144
	ds_read_b128 v[220:223], v215 offset:7168
	global_load_lds_dwordx4 v[2:3], off
	v_lshl_add_u64 v[2:3], s[8:9], 0, v[186:187]
	s_add_i32 m0, s13, 0xe000
	s_nop 0
	global_load_lds_dwordx4 v[2:3], off
	s_waitcnt vmcnt(8)
	s_waitcnt lgkmcnt(0)
	s_barrier
	s_setprio 1
	s_waitcnt lgkmcnt(0)
	v_mfma_i32_16x16x64_i8 v[172:175], v[44:47], v[124:127], 0
	v_mfma_i32_16x16x64_i8 v[172:175], v[52:55], v[128:131], v[172:175]
	v_mfma_i32_16x16x64_i8 v[168:171], v[44:47], v[140:143], 0
	v_mfma_i32_16x16x64_i8 v[168:171], v[52:55], v[188:191], v[168:171]
	v_mfma_i32_16x16x64_i8 v[156:159], v[44:47], v[192:195], 0
	v_mfma_i32_16x16x64_i8 v[156:159], v[52:55], v[196:199], v[156:159]
	v_mfma_i32_16x16x64_i8 v[148:151], v[44:47], v[216:219], 0
	v_mfma_i32_16x16x64_i8 v[148:151], v[52:55], v[220:223], v[148:151]
	v_mfma_i32_16x16x64_i8 v[144:147], v[60:63], v[216:219], 0
	v_mfma_i32_16x16x64_i8 v[144:147], v[64:67], v[220:223], v[144:147]
	v_mfma_i32_16x16x64_i8 v[152:155], v[60:63], v[192:195], 0
	v_mfma_i32_16x16x64_i8 v[152:155], v[64:67], v[196:199], v[152:155]
	v_mfma_i32_16x16x64_i8 v[160:163], v[60:63], v[140:143], 0
	v_mfma_i32_16x16x64_i8 v[160:163], v[64:67], v[188:191], v[160:163]
	v_mfma_i32_16x16x64_i8 v[164:167], v[60:63], v[124:127], 0
	v_mfma_i32_16x16x64_i8 v[164:167], v[64:67], v[128:131], v[164:167]
	s_setprio 0
	s_setprio 1
	v_mfma_i32_16x16x64_i8 v[136:139], v[84:87], v[124:127], 0
	v_mfma_i32_16x16x64_i8 v[120:123], v[92:95], v[124:127], 0
	v_mfma_i32_16x16x64_i8 v[116:119], v[92:95], v[140:143], 0
	v_mfma_i32_16x16x64_i8 v[112:115], v[84:87], v[192:195], 0
	v_mfma_i32_16x16x64_i8 v[108:111], v[92:95], v[192:195], 0
	v_mfma_i32_16x16x64_i8 v[104:107], v[84:87], v[216:219], 0
	v_mfma_i32_16x16x64_i8 v[96:99], v[92:95], v[216:219], 0
	v_mfma_i32_16x16x64_i8 v[136:139], v[88:91], v[128:131], v[136:139]
	v_mfma_i32_16x16x64_i8 v[120:123], v[100:103], v[128:131], v[120:123]
	v_mfma_i32_16x16x64_i8 v[124:127], v[84:87], v[140:143], 0
	v_mfma_i32_16x16x64_i8 v[116:119], v[100:103], v[188:191], v[116:119]
	v_mfma_i32_16x16x64_i8 v[112:115], v[88:91], v[196:199], v[112:115]
	v_mfma_i32_16x16x64_i8 v[108:111], v[100:103], v[196:199], v[108:111]
	v_mfma_i32_16x16x64_i8 v[104:107], v[88:91], v[220:223], v[104:107]
	v_mfma_i32_16x16x64_i8 v[96:99], v[100:103], v[220:223], v[96:99]
	v_mfma_i32_16x16x64_i8 v[124:127], v[88:91], v[188:191], v[124:127]
	s_setprio 0
	s_barrier
	s_add_i32 s8, s84, s12
	v_lshl_add_u64 v[200:201], s[82:83], 0, v[178:179]
	s_mov_b32 m0, s8
	ds_read_b128 v[128:131], v215 offset:16384
	ds_read_b128 v[132:135], v215 offset:17408
	ds_read_b128 v[140:143], v215 offset:18432
	ds_read_b128 v[188:191], v215 offset:19456
	ds_read_b128 v[192:195], v215 offset:20480
	ds_read_b128 v[196:199], v215 offset:21504
	ds_read_b128 v[216:219], v215 offset:22528
	ds_read_b128 v[220:223], v215 offset:23552
	global_load_lds_dwordx4 v[200:201], off
	s_add_i32 m0, s8, 0x2000
	s_add_u32 s8, s82, 0x40000
	v_lshl_add_u64 v[206:207], s[82:83], 0, v[182:183]
	s_addc_u32 s9, s83, 0
	s_add_i32 s10, s10, s12
	global_load_lds_dwordx4 v[206:207], off
	v_lshl_add_u64 v[2:3], s[8:9], 0, v[178:179]
	s_mov_b32 m0, s10
	v_lshl_add_u64 v[210:211], vcc, 0, v[176:177]
	global_load_lds_dwordx4 v[2:3], off
	v_lshl_add_u64 v[2:3], s[8:9], 0, v[182:183]
	s_add_i32 m0, s10, 0x2000
	v_lshl_add_u64 v[224:225], vcc, 0, v[180:181]
	global_load_lds_dwordx4 v[2:3], off
	s_mov_b32 m0, s13
	s_nop 0
	global_load_lds_dwordx4 v[210:211], off
	s_mov_b32 m0, s66
	s_nop 0
	global_load_lds_dwordx4 v[224:225], off
	s_waitcnt vmcnt(8)
	s_waitcnt lgkmcnt(0)
	s_barrier
	s_setprio 1
	s_waitcnt lgkmcnt(0)
	v_mfma_i32_16x16x64_i8 v[80:83], v[44:47], v[128:131], 0
	v_mfma_i32_16x16x64_i8 v[80:83], v[52:55], v[132:135], v[80:83]
	v_mfma_i32_16x16x64_i8 v[76:79], v[44:47], v[140:143], 0
	v_mfma_i32_16x16x64_i8 v[76:79], v[52:55], v[188:191], v[76:79]
	v_mfma_i32_16x16x64_i8 v[56:59], v[44:47], v[192:195], 0
	v_mfma_i32_16x16x64_i8 v[56:59], v[52:55], v[196:199], v[56:59]
	v_mfma_i32_16x16x64_i8 v[40:43], v[44:47], v[216:219], 0
	v_mfma_i32_16x16x64_i8 v[40:43], v[52:55], v[220:223], v[40:43]
	v_mfma_i32_16x16x64_i8 v[36:39], v[60:63], v[216:219], 0
	v_mfma_i32_16x16x64_i8 v[36:39], v[64:67], v[220:223], v[36:39]
	v_mfma_i32_16x16x64_i8 v[48:51], v[60:63], v[192:195], 0
	v_mfma_i32_16x16x64_i8 v[48:51], v[64:67], v[196:199], v[48:51]
	v_mfma_i32_16x16x64_i8 v[68:71], v[60:63], v[140:143], 0
	v_mfma_i32_16x16x64_i8 v[68:71], v[64:67], v[188:191], v[68:71]
	v_mfma_i32_16x16x64_i8 v[72:75], v[60:63], v[128:131], 0
	v_mfma_i32_16x16x64_i8 v[72:75], v[64:67], v[132:135], v[72:75]
	s_setprio 0
	s_setprio 1
	v_mfma_i32_16x16x64_i8 v[32:35], v[84:87], v[128:131], 0
	v_mfma_i32_16x16x64_i8 v[32:35], v[88:91], v[132:135], v[32:35]
	v_mfma_i32_16x16x64_i8 v[28:31], v[84:87], v[140:143], 0
	v_mfma_i32_16x16x64_i8 v[28:31], v[88:91], v[188:191], v[28:31]
	v_mfma_i32_16x16x64_i8 v[16:19], v[84:87], v[192:195], 0
	v_mfma_i32_16x16x64_i8 v[16:19], v[88:91], v[196:199], v[16:19]
	v_mfma_i32_16x16x64_i8 v[8:11], v[84:87], v[216:219], 0
	v_mfma_i32_16x16x64_i8 v[8:11], v[88:91], v[220:223], v[8:11]
	v_mfma_i32_16x16x64_i8 v[2:5], v[92:95], v[216:219], 0
	v_mfma_i32_16x16x64_i8 v[2:5], v[100:103], v[220:223], v[2:5]
	v_mfma_i32_16x16x64_i8 v[12:15], v[92:95], v[192:195], 0
	v_mfma_i32_16x16x64_i8 v[12:15], v[100:103], v[196:199], v[12:15]
	v_mfma_i32_16x16x64_i8 v[20:23], v[92:95], v[140:143], 0
	v_mfma_i32_16x16x64_i8 v[20:23], v[100:103], v[188:191], v[20:23]
	v_mfma_i32_16x16x64_i8 v[24:27], v[92:95], v[128:131], 0
	v_mfma_i32_16x16x64_i8 v[24:27], v[100:103], v[132:135], v[24:27]
	s_setprio 0
	s_barrier
; #define PG8_STAGE(bufoff, gbase, voff) do { _Pragma("unroll") for (int _i = 0; _i < 2; ++_i) \
;         __builtin_amdgcn_global_load_lds((const unsigned*)((const char*)(gbase) + (voff)[_i]), (PG8_LAS unsigned*)(lds + (bufoff) + ldsw + _i * 8192), 16, 0, 0); } while (0)
; #define PG8_LDA(dst, b, h) do { _Pragma("unroll") for (int m = 0; m < 4; ++m) _Pragma("unroll") for (int k = 0; k < 2; ++k) dst[m][k] = *(const PG8_LAS bf16x8*)(lds + PG8_SA(b, h) + aoff + m * 2048 + k * 1024); } while (0)
; #define PG8_LDB(dst, b, h) do { _Pragma("unroll") for (int n = 0; n < 2; ++n) _Pragma("unroll") for (int k = 0; k < 2; ++k) dst[n][k] = *(const PG8_LAS bf16x8*)(lds + PG8_SB(b, h) + boff + n * 2048 + k * 1024); } while (0)
; #define PG8_MMA(ai, bj, At, Bt) do { __builtin_amdgcn_s_setprio(1); _Pragma("unroll") for (int m = 0; m < 4; ++m) _Pragma("unroll") for (int n = 0; n < 2; ++n) _Pragma("unroll") for (int k = 0; k < 2; ++k) \
;         acc[ai][bj][m][n] = mma16<Epi::I8>(Bt[n][k], At[m][k], acc[ai][bj][m][n]); __builtin_amdgcn_s_setprio(0); } while (0)
; #define PG8_WAIT_V(n) asm volatile("s_waitcnt vmcnt(" #n ")" ::: "memory")
; #define PG8_WAIT_L(n) asm volatile("s_waitcnt lgkmcnt(" #n ")" ::: "memory")
; #define PG8_BAR __builtin_amdgcn_s_barrier()
; #define PG8_SCHED __builtin_amdgcn_sched_barrier(0)
; template <class Epi, class Sched, bool ALIGN_EPI = false, bool SP2 = false>
; __device__ __forceinline__ void gemm_phase(PG8_LAS unsigned char* lds, const Gemm g, const Sched& S, const Epi& E) {
;     ...
;         for (int t = 0; t < nt; t += 2) {
;     ...
;             PG8_LDB(B0, 1, 0); PG8_LDB(B1, 1, 1); PG8_SCHED; PG8_LDA(At, 1, 0); PG8_STAGE(PG8_SA(0, 1), a2 + hstep, voffA);
;             PG8_WAIT_V(8); PG8_WAIT_L(0); PG8_BAR; PG8_MMA(0, 0, At, B0); PG8_MMA(0, 1, At, B1); PG8_BAR; PG8_SCHED;
;             PG8_LDA(At, 1, 1); PG8_STAGE(PG8_SB(1, 0), b3, voffB); PG8_STAGE(PG8_SB(1, 1), b3 + hstep, voffB); PG8_STAGE(PG8_SA(1, 0), a3, voffA);
;             PG8_WAIT_V(8); PG8_WAIT_L(0); PG8_BAR; PG8_MMA(1, 0, At, B0); PG8_MMA(1, 1, At, B1); PG8_BAR; PG8_SCHED;
	s_add_i32 s10, 0, 0x18000
	v_add_u32_e32 v0, s10, v214
	s_add_i32 s11, 0, 0x1c000
	ds_read_b128 v[44:47], v0
	ds_read_b128 v[52:55], v0 offset:1024
	ds_read_b128 v[60:63], v0 offset:2048
	ds_read_b128 v[64:67], v0 offset:3072
	v_add_u32_e32 v0, s11, v214
	ds_read_b128 v[84:87], v0
	ds_read_b128 v[88:91], v0 offset:1024
	ds_read_b128 v[92:95], v0 offset:2048
	ds_read_b128 v[100:103], v0 offset:3072
	s_add_u32 s8, vcc_lo, 0x40000
	s_addc_u32 s9, vcc_hi, 0
	s_mov_b32 m0, s67
	v_lshl_add_u64 v[6:7], s[8:9], 0, v[176:177]
	ds_read_b128 v[128:131], v215 offset:32768
	ds_read_b128 v[132:135], v215 offset:33792
	ds_read_b128 v[140:143], v215 offset:34816
	ds_read_b128 v[188:191], v215 offset:35840
	ds_read_b128 v[192:195], v215 offset:36864
	ds_read_b128 v[196:199], v215 offset:37888
	ds_read_b128 v[216:219], v215 offset:38912
	ds_read_b128 v[220:223], v215 offset:39936
	global_load_lds_dwordx4 v[6:7], off
	v_lshl_add_u64 v[6:7], s[8:9], 0, v[180:181]
	s_mov_b32 m0, s80
	s_nop 0
	global_load_lds_dwordx4 v[6:7], off
	s_waitcnt vmcnt(8)
	s_waitcnt lgkmcnt(0)
	s_barrier
	s_setprio 1
	s_waitcnt lgkmcnt(0)
	v_mfma_i32_16x16x64_i8 v[172:175], v[44:47], v[128:131], v[172:175]
	v_mfma_i32_16x16x64_i8 v[172:175], v[52:55], v[132:135], v[172:175]
	v_mfma_i32_16x16x64_i8 v[168:171], v[44:47], v[140:143], v[168:171]
	v_mfma_i32_16x16x64_i8 v[168:171], v[52:55], v[188:191], v[168:171]
	v_mfma_i32_16x16x64_i8 v[156:159], v[44:47], v[192:195], v[156:159]
	v_mfma_i32_16x16x64_i8 v[156:159], v[52:55], v[196:199], v[156:159]
	v_mfma_i32_16x16x64_i8 v[148:151], v[44:47], v[216:219], v[148:151]
	v_mfma_i32_16x16x64_i8 v[148:151], v[52:55], v[220:223], v[148:151]
	v_mfma_i32_16x16x64_i8 v[144:147], v[60:63], v[216:219], v[144:147]
	v_mfma_i32_16x16x64_i8 v[144:147], v[64:67], v[220:223], v[144:147]
	v_mfma_i32_16x16x64_i8 v[152:155], v[60:63], v[192:195], v[152:155]
	v_mfma_i32_16x16x64_i8 v[152:155], v[64:67], v[196:199], v[152:155]
	v_mfma_i32_16x16x64_i8 v[160:163], v[60:63], v[140:143], v[160:163]
	v_mfma_i32_16x16x64_i8 v[160:163], v[64:67], v[188:191], v[160:163]
	v_mfma_i32_16x16x64_i8 v[164:167], v[60:63], v[128:131], v[164:167]
	v_mfma_i32_16x16x64_i8 v[164:167], v[64:67], v[132:135], v[164:167]
	s_setprio 0
	s_setprio 1
	v_mfma_i32_16x16x64_i8 v[136:139], v[84:87], v[128:131], v[136:139]
	v_mfma_i32_16x16x64_i8 v[120:123], v[92:95], v[128:131], v[120:123]
	v_mfma_i32_16x16x64_i8 v[124:127], v[84:87], v[140:143], v[124:127]
	v_mfma_i32_16x16x64_i8 v[116:119], v[92:95], v[140:143], v[116:119]
	v_mfma_i32_16x16x64_i8 v[112:115], v[84:87], v[192:195], v[112:115]
	v_mfma_i32_16x16x64_i8 v[108:111], v[92:95], v[192:195], v[108:111]
	v_mfma_i32_16x16x64_i8 v[104:107], v[84:87], v[216:219], v[104:107]
	v_mfma_i32_16x16x64_i8 v[96:99], v[92:95], v[216:219], v[96:99]
	v_mfma_i32_16x16x64_i8 v[136:139], v[88:91], v[132:135], v[136:139]
	v_mfma_i32_16x16x64_i8 v[120:123], v[100:103], v[132:135], v[120:123]
	v_mfma_i32_16x16x64_i8 v[132:135], v[88:91], v[188:191], v[124:127]
	v_mfma_i32_16x16x64_i8 v[116:119], v[100:103], v[188:191], v[116:119]
	v_mfma_i32_16x16x64_i8 v[112:115], v[88:91], v[196:199], v[112:115]
	v_mfma_i32_16x16x64_i8 v[108:111], v[100:103], v[196:199], v[108:111]
	v_mfma_i32_16x16x64_i8 v[104:107], v[88:91], v[220:223], v[104:107]
	v_mfma_i32_16x16x64_i8 v[96:99], v[100:103], v[220:223], v[96:99]
	s_setprio 0
	s_barrier
	s_add_i32 s8, s10, s12
	v_lshl_add_u64 v[6:7], v[200:201], 0, s[92:93]
	s_mov_b32 m0, s8
	ds_read_b128 v[124:127], v215 offset:49152
	ds_read_b128 v[128:131], v215 offset:50176
	ds_read_b128 v[140:143], v215 offset:51200
	ds_read_b128 v[188:191], v215 offset:52224
	ds_read_b128 v[192:195], v215 offset:53248
	ds_read_b128 v[196:199], v215 offset:54272
	ds_read_b128 v[216:219], v215 offset:55296
	ds_read_b128 v[220:223], v215 offset:56320
	global_load_lds_dwordx4 v[6:7], off
	s_add_i32 m0, s8, 0x2000
	s_add_u32 s8, s82, 0x40080
	v_lshl_add_u64 v[6:7], v[206:207], 0, s[92:93]
	s_addc_u32 s9, s83, 0
	s_add_i32 s10, s11, s12
	global_load_lds_dwordx4 v[6:7], off
	v_lshl_add_u64 v[6:7], s[8:9], 0, v[178:179]
	s_mov_b32 m0, s10
	s_nop 0
	global_load_lds_dwordx4 v[6:7], off
	v_lshl_add_u64 v[6:7], s[8:9], 0, v[182:183]
	s_add_i32 m0, s10, 0x2000
	s_nop 0
	global_load_lds_dwordx4 v[6:7], off
	v_lshl_add_u64 v[6:7], v[210:211], 0, s[92:93]
	s_mov_b32 m0, s58
	s_nop 0
	global_load_lds_dwordx4 v[6:7], off
	v_lshl_add_u64 v[6:7], v[224:225], 0, s[92:93]
	s_mov_b32 m0, s4
	s_nop 0
	global_load_lds_dwordx4 v[6:7], off
	s_waitcnt vmcnt(8)
	s_waitcnt lgkmcnt(0)
	s_barrier
	s_setprio 1
	s_waitcnt lgkmcnt(0)
	v_mfma_i32_16x16x64_i8 v[80:83], v[44:47], v[124:127], v[80:83]
	v_mfma_i32_16x16x64_i8 v[80:83], v[52:55], v[128:131], v[80:83]
	v_mfma_i32_16x16x64_i8 v[76:79], v[44:47], v[140:143], v[76:79]
	v_mfma_i32_16x16x64_i8 v[76:79], v[52:55], v[188:191], v[76:79]
	v_mfma_i32_16x16x64_i8 v[56:59], v[44:47], v[192:195], v[56:59]
	v_mfma_i32_16x16x64_i8 v[56:59], v[52:55], v[196:199], v[56:59]
	v_mfma_i32_16x16x64_i8 v[40:43], v[44:47], v[216:219], v[40:43]
	v_mfma_i32_16x16x64_i8 v[40:43], v[52:55], v[220:223], v[40:43]
	v_mfma_i32_16x16x64_i8 v[36:39], v[60:63], v[216:219], v[36:39]
	v_mfma_i32_16x16x64_i8 v[36:39], v[64:67], v[220:223], v[36:39]
	v_mfma_i32_16x16x64_i8 v[48:51], v[60:63], v[192:195], v[48:51]
	v_mfma_i32_16x16x64_i8 v[48:51], v[64:67], v[196:199], v[48:51]
	v_mfma_i32_16x16x64_i8 v[68:71], v[60:63], v[140:143], v[68:71]
	v_mfma_i32_16x16x64_i8 v[68:71], v[64:67], v[188:191], v[68:71]
	v_mfma_i32_16x16x64_i8 v[72:75], v[60:63], v[124:127], v[72:75]
	v_mfma_i32_16x16x64_i8 v[72:75], v[64:67], v[128:131], v[72:75]
	s_setprio 0
	s_setprio 1
	v_mfma_i32_16x16x64_i8 v[32:35], v[84:87], v[124:127], v[32:35]
	v_mfma_i32_16x16x64_i8 v[24:27], v[92:95], v[124:127], v[24:27]
	v_mfma_i32_16x16x64_i8 v[28:31], v[84:87], v[140:143], v[28:31]
	v_mfma_i32_16x16x64_i8 v[20:23], v[92:95], v[140:143], v[20:23]
	v_mfma_i32_16x16x64_i8 v[16:19], v[84:87], v[192:195], v[16:19]
	v_mfma_i32_16x16x64_i8 v[12:15], v[92:95], v[192:195], v[12:15]
	v_mfma_i32_16x16x64_i8 v[6:9], v[84:87], v[216:219], v[8:11]
	v_mfma_i32_16x16x64_i8 v[2:5], v[92:95], v[216:219], v[2:5]
	v_mfma_i32_16x16x64_i8 v[32:35], v[88:91], v[128:131], v[32:35]
	v_mfma_i32_16x16x64_i8 v[24:27], v[100:103], v[128:131], v[24:27]
	v_mfma_i32_16x16x64_i8 v[28:31], v[88:91], v[188:191], v[28:31]
	v_mfma_i32_16x16x64_i8 v[20:23], v[100:103], v[188:191], v[20:23]
	v_mfma_i32_16x16x64_i8 v[16:19], v[88:91], v[196:199], v[16:19]
	v_mfma_i32_16x16x64_i8 v[12:15], v[100:103], v[196:199], v[12:15]
	v_mfma_i32_16x16x64_i8 v[8:11], v[88:91], v[220:223], v[6:9]
	v_mfma_i32_16x16x64_i8 v[4:7], v[100:103], v[220:223], v[2:5]
	s_setprio 0
	s_barrier
	s_add_i32 s5, s5, 2
	s_add_u32 s85, s85, 0x100
	s_addc_u32 s68, s68, 0
	s_cmp_gt_u32 s5, 13
	s_mov_b64 s[8:9], s[70:71]
	s_cbranch_scc0 .LBB0_385
	s_branch .Lpeelx385
; #define PG8_STAGE(bufoff, gbase, voff) do { _Pragma("unroll") for (int _i = 0; _i < 2; ++_i) \
;         __builtin_amdgcn_global_load_lds((const unsigned*)((const char*)(gbase) + (voff)[_i]), (PG8_LAS unsigned*)(lds + (bufoff) + ldsw + _i * 8192), 16, 0, 0); } while (0)
; #define PG8_LDA(dst, b, h) do { _Pragma("unroll") for (int m = 0; m < 4; ++m) _Pragma("unroll") for (int k = 0; k < 2; ++k) dst[m][k] = *(const PG8_LAS bf16x8*)(lds + PG8_SA(b, h) + aoff + m * 2048 + k * 1024); } while (0)
; #define PG8_LDB(dst, b, h) do { _Pragma("unroll") for (int n = 0; n < 2; ++n) _Pragma("unroll") for (int k = 0; k < 2; ++k) dst[n][k] = *(const PG8_LAS bf16x8*)(lds + PG8_SB(b, h) + boff + n * 2048 + k * 1024); } while (0)
; #define PG8_MMA(ai, bj, At, Bt) do { __builtin_amdgcn_s_setprio(1); _Pragma("unroll") for (int m = 0; m < 4; ++m) _Pragma("unroll") for (int n = 0; n < 2; ++n) _Pragma("unroll") for (int k = 0; k < 2; ++k) \
;         acc[ai][bj][m][n] = mma16<Epi::I8>(Bt[n][k], At[m][k], acc[ai][bj][m][n]); __builtin_amdgcn_s_setprio(0); } while (0)
; #define PG8_WAIT_V(n) asm volatile("s_waitcnt vmcnt(" #n ")" ::: "memory")
; #define PG8_WAIT_L(n) asm volatile("s_waitcnt lgkmcnt(" #n ")" ::: "memory")
; #define PG8_BAR __builtin_amdgcn_s_barrier()
; #define PG8_SCHED __builtin_amdgcn_sched_barrier(0)
; template <class Epi, class Sched, bool ALIGN_EPI = false, bool SP2 = false>
; __device__ __forceinline__ void gemm_phase(PG8_LAS unsigned char* lds, const Gemm g, const Sched& S, const Epi& E) {
;     ...
;             PG8_LDB(B0, 0, 0); PG8_LDB(B1, 0, 1); PG8_SCHED; PG8_LDA(At, 0, 0); PG8_STAGE(PG8_SA(1, 1), a1 + hstep, voffA);
;             PG8_WAIT_V(8); PG8_WAIT_L(0); PG8_BAR; PG8_MMA(0, 0, At, B0); PG8_MMA(0, 1, At, B1); PG8_BAR; PG8_SCHED;
;             PG8_LDA(At, 0, 1); PG8_STAGE(PG8_SB(0, 0), b2, voffB); PG8_STAGE(PG8_SB(0, 1), b2 + hstep, voffB); PG8_STAGE(PG8_SA(0, 0), a2, voffA);
.LBB0_385:
	s_add_u32 s70, s8, 0x100
	s_addc_u32 s71, s9, 0
	s_add_i32 s84, 0, 0x10000
	s_cmp_eq_u32 s5, 12
	s_cselect_b32 vcc_hi, s1, s71
	s_cselect_b32 vcc_lo, s7, s70
	v_add_u32_e32 v0, s84, v214
	s_cselect_b32 s83, s69, s68
	s_cselect_b32 s82, s81, s85
	s_add_i32 s10, 0, 0x14000
	ds_read_b128 v[44:47], v0
	ds_read_b128 v[52:55], v0 offset:1024
	ds_read_b128 v[60:63], v0 offset:2048
	ds_read_b128 v[64:67], v0 offset:3072
	v_add_u32_e32 v0, s10, v214
	ds_read_b128 v[84:87], v0
	ds_read_b128 v[88:91], v0 offset:1024
	ds_read_b128 v[92:95], v0 offset:2048
	ds_read_b128 v[100:103], v0 offset:3072
	v_lshl_add_u64 v[2:3], s[8:9], 0, v[184:185]
	s_add_i32 m0, s13, 0xc000
	ds_read_b128 v[124:127], v215
	ds_read_b128 v[128:131], v215 offset:1024
	ds_read_b128 v[140:143], v215 offset:2048
	ds_read_b128 v[188:191], v215 offset:3072
	ds_read_b128 v[192:195], v215 offset:4096
	ds_read_b128 v[196:199], v215 offset:5120
	ds_read_b128 v[216:219], v215 offset:6144
	ds_read_b128 v[220:223], v215 offset:7168
	global_load_lds_dwordx4 v[2:3], off
	v_lshl_add_u64 v[2:3], s[8:9], 0, v[186:187]
	s_add_i32 m0, s13, 0xe000
	s_nop 0
	global_load_lds_dwordx4 v[2:3], off
	s_waitcnt vmcnt(8)
	s_waitcnt lgkmcnt(0)
	s_barrier
	s_setprio 1
	s_waitcnt lgkmcnt(0)
	v_mfma_i32_16x16x64_i8 v[172:175], v[44:47], v[124:127], v[172:175]
	v_mfma_i32_16x16x64_i8 v[172:175], v[52:55], v[128:131], v[172:175]
	v_mfma_i32_16x16x64_i8 v[168:171], v[44:47], v[140:143], v[168:171]
	v_mfma_i32_16x16x64_i8 v[168:171], v[52:55], v[188:191], v[168:171]
	v_mfma_i32_16x16x64_i8 v[156:159], v[44:47], v[192:195], v[156:159]
	v_mfma_i32_16x16x64_i8 v[156:159], v[52:55], v[196:199], v[156:159]
	v_mfma_i32_16x16x64_i8 v[148:151], v[44:47], v[216:219], v[148:151]
	v_mfma_i32_16x16x64_i8 v[148:151], v[52:55], v[220:223], v[148:151]
	v_mfma_i32_16x16x64_i8 v[144:147], v[60:63], v[216:219], v[144:147]
	v_mfma_i32_16x16x64_i8 v[144:147], v[64:67], v[220:223], v[144:147]
	v_mfma_i32_16x16x64_i8 v[152:155], v[60:63], v[192:195], v[152:155]
	v_mfma_i32_16x16x64_i8 v[152:155], v[64:67], v[196:199], v[152:155]
	v_mfma_i32_16x16x64_i8 v[160:163], v[60:63], v[140:143], v[160:163]
	v_mfma_i32_16x16x64_i8 v[160:163], v[64:67], v[188:191], v[160:163]
	v_mfma_i32_16x16x64_i8 v[164:167], v[60:63], v[124:127], v[164:167]
	v_mfma_i32_16x16x64_i8 v[164:167], v[64:67], v[128:131], v[164:167]
	s_setprio 0
	s_setprio 1
	v_mfma_i32_16x16x64_i8 v[136:139], v[84:87], v[124:127], v[136:139]
	v_mfma_i32_16x16x64_i8 v[120:123], v[92:95], v[124:127], v[120:123]
	v_mfma_i32_16x16x64_i8 v[116:119], v[92:95], v[140:143], v[116:119]
	v_mfma_i32_16x16x64_i8 v[112:115], v[84:87], v[192:195], v[112:115]
	v_mfma_i32_16x16x64_i8 v[108:111], v[92:95], v[192:195], v[108:111]
	v_mfma_i32_16x16x64_i8 v[104:107], v[84:87], v[216:219], v[104:107]
	v_mfma_i32_16x16x64_i8 v[96:99], v[92:95], v[216:219], v[96:99]
	v_mfma_i32_16x16x64_i8 v[136:139], v[88:91], v[128:131], v[136:139]
	v_mfma_i32_16x16x64_i8 v[120:123], v[100:103], v[128:131], v[120:123]
	v_mfma_i32_16x16x64_i8 v[124:127], v[84:87], v[140:143], v[132:135]
	v_mfma_i32_16x16x64_i8 v[116:119], v[100:103], v[188:191], v[116:119]
	v_mfma_i32_16x16x64_i8 v[112:115], v[88:91], v[196:199], v[112:115]
	v_mfma_i32_16x16x64_i8 v[108:111], v[100:103], v[196:199], v[108:111]
	v_mfma_i32_16x16x64_i8 v[104:107], v[88:91], v[220:223], v[104:107]
	v_mfma_i32_16x16x64_i8 v[96:99], v[100:103], v[220:223], v[96:99]
	v_mfma_i32_16x16x64_i8 v[124:127], v[88:91], v[188:191], v[124:127]
	s_setprio 0
	s_barrier
	s_add_i32 s8, s84, s12
	v_lshl_add_u64 v[200:201], s[82:83], 0, v[178:179]
	s_mov_b32 m0, s8
	ds_read_b128 v[128:131], v215 offset:16384
	ds_read_b128 v[132:135], v215 offset:17408
	ds_read_b128 v[140:143], v215 offset:18432
	ds_read_b128 v[188:191], v215 offset:19456
	ds_read_b128 v[192:195], v215 offset:20480
	ds_read_b128 v[196:199], v215 offset:21504
	ds_read_b128 v[216:219], v215 offset:22528
	ds_read_b128 v[220:223], v215 offset:23552
	global_load_lds_dwordx4 v[200:201], off
	s_add_i32 m0, s8, 0x2000
	s_add_u32 s8, s82, 0x40000
	v_lshl_add_u64 v[206:207], s[82:83], 0, v[182:183]
	s_addc_u32 s9, s83, 0
	s_add_i32 s10, s10, s12
	global_load_lds_dwordx4 v[206:207], off
	v_lshl_add_u64 v[2:3], s[8:9], 0, v[178:179]
	s_mov_b32 m0, s10
	v_lshl_add_u64 v[210:211], vcc, 0, v[176:177]
	global_load_lds_dwordx4 v[2:3], off
	v_lshl_add_u64 v[2:3], s[8:9], 0, v[182:183]
	s_add_i32 m0, s10, 0x2000
	v_lshl_add_u64 v[224:225], vcc, 0, v[180:181]
	global_load_lds_dwordx4 v[2:3], off
	s_mov_b32 m0, s13
	s_nop 0
	global_load_lds_dwordx4 v[210:211], off
	s_mov_b32 m0, s66
	s_nop 0
	global_load_lds_dwordx4 v[224:225], off
	s_waitcnt vmcnt(8)
	s_waitcnt lgkmcnt(0)
	s_barrier
; #define PG8_STAGE(bufoff, gbase, voff) do { _Pragma("unroll") for (int _i = 0; _i < 2; ++_i) \
;         __builtin_amdgcn_global_load_lds((const unsigned*)((const char*)(gbase) + (voff)[_i]), (PG8_LAS unsigned*)(lds + (bufoff) + ldsw + _i * 8192), 16, 0, 0); } while (0)
; #define PG8_LDA(dst, b, h) do { _Pragma("unroll") for (int m = 0; m < 4; ++m) _Pragma("unroll") for (int k = 0; k < 2; ++k) dst[m][k] = *(const PG8_LAS bf16x8*)(lds + PG8_SA(b, h) + aoff + m * 2048 + k * 1024); } while (0)
; #define PG8_LDB(dst, b, h) do { _Pragma("unroll") for (int n = 0; n < 2; ++n) _Pragma("unroll") for (int k = 0; k < 2; ++k) dst[n][k] = *(const PG8_LAS bf16x8*)(lds + PG8_SB(b, h) + boff + n * 2048 + k * 1024); } while (0)
; #define PG8_MMA(ai, bj, At, Bt) do { __builtin_amdgcn_s_setprio(1); _Pragma("unroll") for (int m = 0; m < 4; ++m) _Pragma("unroll") for (int n = 0; n < 2; ++n) _Pragma("unroll") for (int k = 0; k < 2; ++k) \
;         acc[ai][bj][m][n] = mma16<Epi::I8>(Bt[n][k], At[m][k], acc[ai][bj][m][n]); __builtin_amdgcn_s_setprio(0); } while (0)
; #define PG8_WAIT_V(n) asm volatile("s_waitcnt vmcnt(" #n ")" ::: "memory")
; #define PG8_WAIT_L(n) asm volatile("s_waitcnt lgkmcnt(" #n ")" ::: "memory")
; #define PG8_BAR __builtin_amdgcn_s_barrier()
; #define PG8_SCHED __builtin_amdgcn_sched_barrier(0)
; template <class Epi, class Sched, bool ALIGN_EPI = false, bool SP2 = false>
; __device__ __forceinline__ void gemm_phase(PG8_LAS unsigned char* lds, const Gemm g, const Sched& S, const Epi& E) {
;     ...
;             PG8_WAIT_V(8); PG8_WAIT_L(0); PG8_BAR; PG8_MMA(1, 0, At, B0); PG8_MMA(1, 1, At, B1); PG8_BAR; PG8_SCHED;
;             PG8_LDB(B0, 1, 0); PG8_LDB(B1, 1, 1); PG8_SCHED; PG8_LDA(At, 1, 0); PG8_STAGE(PG8_SA(0, 1), a2 + hstep, voffA);
;             PG8_WAIT_V(8); PG8_WAIT_L(0); PG8_BAR; PG8_MMA(0, 0, At, B0); PG8_MMA(0, 1, At, B1); PG8_BAR; PG8_SCHED;
	s_setprio 1
	s_waitcnt lgkmcnt(0)
	v_mfma_i32_16x16x64_i8 v[80:83], v[44:47], v[128:131], v[80:83]
	v_mfma_i32_16x16x64_i8 v[80:83], v[52:55], v[132:135], v[80:83]
	v_mfma_i32_16x16x64_i8 v[76:79], v[44:47], v[140:143], v[76:79]
	v_mfma_i32_16x16x64_i8 v[76:79], v[52:55], v[188:191], v[76:79]
	v_mfma_i32_16x16x64_i8 v[56:59], v[44:47], v[192:195], v[56:59]
	v_mfma_i32_16x16x64_i8 v[56:59], v[52:55], v[196:199], v[56:59]
	v_mfma_i32_16x16x64_i8 v[40:43], v[44:47], v[216:219], v[40:43]
	v_mfma_i32_16x16x64_i8 v[40:43], v[52:55], v[220:223], v[40:43]
	v_mfma_i32_16x16x64_i8 v[36:39], v[60:63], v[216:219], v[36:39]
	v_mfma_i32_16x16x64_i8 v[36:39], v[64:67], v[220:223], v[36:39]
	v_mfma_i32_16x16x64_i8 v[48:51], v[60:63], v[192:195], v[48:51]
	v_mfma_i32_16x16x64_i8 v[48:51], v[64:67], v[196:199], v[48:51]
	v_mfma_i32_16x16x64_i8 v[68:71], v[60:63], v[140:143], v[68:71]
	v_mfma_i32_16x16x64_i8 v[68:71], v[64:67], v[188:191], v[68:71]
	v_mfma_i32_16x16x64_i8 v[72:75], v[60:63], v[128:131], v[72:75]
	v_mfma_i32_16x16x64_i8 v[72:75], v[64:67], v[132:135], v[72:75]
	s_setprio 0
	s_setprio 1
	v_mfma_i32_16x16x64_i8 v[32:35], v[84:87], v[128:131], v[32:35]
	v_mfma_i32_16x16x64_i8 v[24:27], v[92:95], v[128:131], v[24:27]
	v_mfma_i32_16x16x64_i8 v[28:31], v[84:87], v[140:143], v[28:31]
	v_mfma_i32_16x16x64_i8 v[20:23], v[92:95], v[140:143], v[20:23]
	v_mfma_i32_16x16x64_i8 v[16:19], v[84:87], v[192:195], v[16:19]
	v_mfma_i32_16x16x64_i8 v[12:15], v[92:95], v[192:195], v[12:15]
	v_mfma_i32_16x16x64_i8 v[8:11], v[84:87], v[216:219], v[8:11]
	v_mfma_i32_16x16x64_i8 v[2:5], v[92:95], v[216:219], v[4:7]
	v_mfma_i32_16x16x64_i8 v[32:35], v[88:91], v[132:135], v[32:35]
	v_mfma_i32_16x16x64_i8 v[24:27], v[100:103], v[132:135], v[24:27]
	v_mfma_i32_16x16x64_i8 v[28:31], v[88:91], v[188:191], v[28:31]
	v_mfma_i32_16x16x64_i8 v[20:23], v[100:103], v[188:191], v[20:23]
	v_mfma_i32_16x16x64_i8 v[16:19], v[88:91], v[196:199], v[16:19]
	v_mfma_i32_16x16x64_i8 v[12:15], v[100:103], v[196:199], v[12:15]
	v_mfma_i32_16x16x64_i8 v[8:11], v[88:91], v[220:223], v[8:11]
	v_mfma_i32_16x16x64_i8 v[2:5], v[100:103], v[220:223], v[2:5]
	s_setprio 0
	s_barrier
	s_add_i32 s10, 0, 0x18000
	v_add_u32_e32 v0, s10, v214
	s_add_i32 s11, 0, 0x1c000
	ds_read_b128 v[44:47], v0
	ds_read_b128 v[52:55], v0 offset:1024
	ds_read_b128 v[60:63], v0 offset:2048
	ds_read_b128 v[64:67], v0 offset:3072
	v_add_u32_e32 v0, s11, v214
	ds_read_b128 v[84:87], v0
	ds_read_b128 v[88:91], v0 offset:1024
	ds_read_b128 v[92:95], v0 offset:2048
	ds_read_b128 v[100:103], v0 offset:3072
	s_add_u32 s8, vcc_lo, 0x40000
	s_addc_u32 s9, vcc_hi, 0
	s_mov_b32 m0, s67
	v_lshl_add_u64 v[6:7], s[8:9], 0, v[176:177]
	ds_read_b128 v[128:131], v215 offset:32768
	ds_read_b128 v[132:135], v215 offset:33792
	ds_read_b128 v[140:143], v215 offset:34816
	ds_read_b128 v[188:191], v215 offset:35840
	ds_read_b128 v[192:195], v215 offset:36864
	ds_read_b128 v[196:199], v215 offset:37888
	ds_read_b128 v[216:219], v215 offset:38912
	ds_read_b128 v[220:223], v215 offset:39936
	global_load_lds_dwordx4 v[6:7], off
	v_lshl_add_u64 v[6:7], s[8:9], 0, v[180:181]
	s_mov_b32 m0, s80
	s_nop 0
	global_load_lds_dwordx4 v[6:7], off
	s_waitcnt vmcnt(8)
	s_waitcnt lgkmcnt(0)
	s_barrier
	s_setprio 1
	s_waitcnt lgkmcnt(0)
	v_mfma_i32_16x16x64_i8 v[172:175], v[44:47], v[128:131], v[172:175]
	v_mfma_i32_16x16x64_i8 v[172:175], v[52:55], v[132:135], v[172:175]
	v_mfma_i32_16x16x64_i8 v[168:171], v[44:47], v[140:143], v[168:171]
	v_mfma_i32_16x16x64_i8 v[168:171], v[52:55], v[188:191], v[168:171]
	v_mfma_i32_16x16x64_i8 v[156:159], v[44:47], v[192:195], v[156:159]
	v_mfma_i32_16x16x64_i8 v[156:159], v[52:55], v[196:199], v[156:159]
	v_mfma_i32_16x16x64_i8 v[148:151], v[44:47], v[216:219], v[148:151]
	v_mfma_i32_16x16x64_i8 v[148:151], v[52:55], v[220:223], v[148:151]
	v_mfma_i32_16x16x64_i8 v[144:147], v[60:63], v[216:219], v[144:147]
	v_mfma_i32_16x16x64_i8 v[144:147], v[64:67], v[220:223], v[144:147]
	v_mfma_i32_16x16x64_i8 v[152:155], v[60:63], v[192:195], v[152:155]
	v_mfma_i32_16x16x64_i8 v[152:155], v[64:67], v[196:199], v[152:155]
	v_mfma_i32_16x16x64_i8 v[160:163], v[60:63], v[140:143], v[160:163]
	v_mfma_i32_16x16x64_i8 v[160:163], v[64:67], v[188:191], v[160:163]
	v_mfma_i32_16x16x64_i8 v[164:167], v[60:63], v[128:131], v[164:167]
	v_mfma_i32_16x16x64_i8 v[164:167], v[64:67], v[132:135], v[164:167]
	s_setprio 0
	s_setprio 1
	v_mfma_i32_16x16x64_i8 v[136:139], v[84:87], v[128:131], v[136:139]
	v_mfma_i32_16x16x64_i8 v[120:123], v[92:95], v[128:131], v[120:123]
	v_mfma_i32_16x16x64_i8 v[124:127], v[84:87], v[140:143], v[124:127]
	v_mfma_i32_16x16x64_i8 v[116:119], v[92:95], v[140:143], v[116:119]
	v_mfma_i32_16x16x64_i8 v[112:115], v[84:87], v[192:195], v[112:115]
	v_mfma_i32_16x16x64_i8 v[108:111], v[92:95], v[192:195], v[108:111]
	v_mfma_i32_16x16x64_i8 v[104:107], v[84:87], v[216:219], v[104:107]
	v_mfma_i32_16x16x64_i8 v[96:99], v[92:95], v[216:219], v[96:99]
	v_mfma_i32_16x16x64_i8 v[136:139], v[88:91], v[132:135], v[136:139]
	v_mfma_i32_16x16x64_i8 v[120:123], v[100:103], v[132:135], v[120:123]
	v_mfma_i32_16x16x64_i8 v[132:135], v[88:91], v[188:191], v[124:127]
	v_mfma_i32_16x16x64_i8 v[116:119], v[100:103], v[188:191], v[116:119]
	v_mfma_i32_16x16x64_i8 v[112:115], v[88:91], v[196:199], v[112:115]
	v_mfma_i32_16x16x64_i8 v[108:111], v[100:103], v[196:199], v[108:111]
	v_mfma_i32_16x16x64_i8 v[104:107], v[88:91], v[220:223], v[104:107]
	v_mfma_i32_16x16x64_i8 v[96:99], v[100:103], v[220:223], v[96:99]
	s_setprio 0
	s_barrier
; #define PG8_STAGE(bufoff, gbase, voff) do { _Pragma("unroll") for (int _i = 0; _i < 2; ++_i) \
;         __builtin_amdgcn_global_load_lds((const unsigned*)((const char*)(gbase) + (voff)[_i]), (PG8_LAS unsigned*)(lds + (bufoff) + ldsw + _i * 8192), 16, 0, 0); } while (0)
; #define PG8_LDA(dst, b, h) do { _Pragma("unroll") for (int m = 0; m < 4; ++m) _Pragma("unroll") for (int k = 0; k < 2; ++k) dst[m][k] = *(const PG8_LAS bf16x8*)(lds + PG8_SA(b, h) + aoff + m * 2048 + k * 1024); } while (0)
; #define PG8_MMA(ai, bj, At, Bt) do { __builtin_amdgcn_s_setprio(1); _Pragma("unroll") for (int m = 0; m < 4; ++m) _Pragma("unroll") for (int n = 0; n < 2; ++n) _Pragma("unroll") for (int k = 0; k < 2; ++k) \
;         acc[ai][bj][m][n] = mma16<Epi::I8>(Bt[n][k], At[m][k], acc[ai][bj][m][n]); __builtin_amdgcn_s_setprio(0); } while (0)
; #define PG8_WAIT_V(n) asm volatile("s_waitcnt vmcnt(" #n ")" ::: "memory")
; #define PG8_WAIT_L(n) asm volatile("s_waitcnt lgkmcnt(" #n ")" ::: "memory")
; #define PG8_BAR __builtin_amdgcn_s_barrier()
; #define PG8_SCHED __builtin_amdgcn_sched_barrier(0)
; template <class Epi, class Sched, bool ALIGN_EPI = false, bool SP2 = false>
; __device__ __forceinline__ void gemm_phase(PG8_LAS unsigned char* lds, const Gemm g, const Sched& S, const Epi& E) {
;     ...
;             PG8_LDA(At, 1, 1); PG8_STAGE(PG8_SB(1, 0), b3, voffB); PG8_STAGE(PG8_SB(1, 1), b3 + hstep, voffB); PG8_STAGE(PG8_SA(1, 0), a3, voffA);
;             PG8_WAIT_V(8); PG8_WAIT_L(0); PG8_BAR; PG8_MMA(1, 0, At, B0); PG8_MMA(1, 1, At, B1); PG8_BAR; PG8_SCHED;
	s_add_i32 s8, s10, s12
	v_lshl_add_u64 v[6:7], v[200:201], 0, s[92:93]
	s_mov_b32 m0, s8
	ds_read_b128 v[124:127], v215 offset:49152
	ds_read_b128 v[128:131], v215 offset:50176
	ds_read_b128 v[140:143], v215 offset:51200
	ds_read_b128 v[188:191], v215 offset:52224
	ds_read_b128 v[192:195], v215 offset:53248
	ds_read_b128 v[196:199], v215 offset:54272
	ds_read_b128 v[216:219], v215 offset:55296
	ds_read_b128 v[220:223], v215 offset:56320
	global_load_lds_dwordx4 v[6:7], off
	s_add_i32 m0, s8, 0x2000
	s_add_u32 s8, s82, 0x40080
	v_lshl_add_u64 v[6:7], v[206:207], 0, s[92:93]
	s_addc_u32 s9, s83, 0
	s_add_i32 s10, s11, s12
	global_load_lds_dwordx4 v[6:7], off
	v_lshl_add_u64 v[6:7], s[8:9], 0, v[178:179]
	s_mov_b32 m0, s10
	s_nop 0
	global_load_lds_dwordx4 v[6:7], off
	v_lshl_add_u64 v[6:7], s[8:9], 0, v[182:183]
	s_add_i32 m0, s10, 0x2000
	s_nop 0
	global_load_lds_dwordx4 v[6:7], off
	v_lshl_add_u64 v[6:7], v[210:211], 0, s[92:93]
	s_mov_b32 m0, s58
	s_nop 0
	global_load_lds_dwordx4 v[6:7], off
	v_lshl_add_u64 v[6:7], v[224:225], 0, s[92:93]
	s_mov_b32 m0, s4
	s_nop 0
	global_load_lds_dwordx4 v[6:7], off
	s_waitcnt vmcnt(8)
	s_waitcnt lgkmcnt(0)
	s_barrier
	s_setprio 1
	s_waitcnt lgkmcnt(0)
	v_mfma_i32_16x16x64_i8 v[80:83], v[44:47], v[124:127], v[80:83]
	v_mfma_i32_16x16x64_i8 v[80:83], v[52:55], v[128:131], v[80:83]
	v_mfma_i32_16x16x64_i8 v[76:79], v[44:47], v[140:143], v[76:79]
	v_mfma_i32_16x16x64_i8 v[76:79], v[52:55], v[188:191], v[76:79]
	v_mfma_i32_16x16x64_i8 v[56:59], v[44:47], v[192:195], v[56:59]
	v_mfma_i32_16x16x64_i8 v[56:59], v[52:55], v[196:199], v[56:59]
	v_mfma_i32_16x16x64_i8 v[40:43], v[44:47], v[216:219], v[40:43]
	v_mfma_i32_16x16x64_i8 v[40:43], v[52:55], v[220:223], v[40:43]
	v_mfma_i32_16x16x64_i8 v[36:39], v[60:63], v[216:219], v[36:39]
	v_mfma_i32_16x16x64_i8 v[36:39], v[64:67], v[220:223], v[36:39]
	v_mfma_i32_16x16x64_i8 v[48:51], v[60:63], v[192:195], v[48:51]
	v_mfma_i32_16x16x64_i8 v[48:51], v[64:67], v[196:199], v[48:51]
	v_mfma_i32_16x16x64_i8 v[68:71], v[60:63], v[140:143], v[68:71]
	v_mfma_i32_16x16x64_i8 v[68:71], v[64:67], v[188:191], v[68:71]
	v_mfma_i32_16x16x64_i8 v[72:75], v[60:63], v[124:127], v[72:75]
	v_mfma_i32_16x16x64_i8 v[72:75], v[64:67], v[128:131], v[72:75]
	s_setprio 0
	s_setprio 1
	v_mfma_i32_16x16x64_i8 v[32:35], v[84:87], v[124:127], v[32:35]
	v_mfma_i32_16x16x64_i8 v[24:27], v[92:95], v[124:127], v[24:27]
	v_mfma_i32_16x16x64_i8 v[28:31], v[84:87], v[140:143], v[28:31]
	v_mfma_i32_16x16x64_i8 v[20:23], v[92:95], v[140:143], v[20:23]
	v_mfma_i32_16x16x64_i8 v[16:19], v[84:87], v[192:195], v[16:19]
	v_mfma_i32_16x16x64_i8 v[12:15], v[92:95], v[192:195], v[12:15]
	v_mfma_i32_16x16x64_i8 v[6:9], v[84:87], v[216:219], v[8:11]
	v_mfma_i32_16x16x64_i8 v[2:5], v[92:95], v[216:219], v[2:5]
	v_mfma_i32_16x16x64_i8 v[32:35], v[88:91], v[128:131], v[32:35]
	v_mfma_i32_16x16x64_i8 v[24:27], v[100:103], v[128:131], v[24:27]
	v_mfma_i32_16x16x64_i8 v[28:31], v[88:91], v[188:191], v[28:31]
	v_mfma_i32_16x16x64_i8 v[20:23], v[100:103], v[188:191], v[20:23]
	v_mfma_i32_16x16x64_i8 v[16:19], v[88:91], v[196:199], v[16:19]
	v_mfma_i32_16x16x64_i8 v[12:15], v[100:103], v[196:199], v[12:15]
	v_mfma_i32_16x16x64_i8 v[8:11], v[88:91], v[220:223], v[6:9]
	v_mfma_i32_16x16x64_i8 v[4:7], v[100:103], v[220:223], v[2:5]
	s_setprio 0
	s_barrier
	s_add_i32 s5, s5, 2
	s_add_u32 s85, s85, 0x100
	s_addc_u32 s68, s68, 0
	s_cmp_gt_u32 s5, 13
	s_mov_b64 s[8:9], s[70:71]
	s_cbranch_scc0 .LBB0_385
